# removed the mid-burst s_setprio 0/1 flip inside each 32-MFMA compute segment of the 12 GEMM K-loops and skipped the final grid barrier on the fused-norm path
# speedup vs baseline: 1.0096x; 1.0058x over previous
; #define PG8_STAGE(bufoff, gbase, voff) do { _Pragma("unroll") for (int _i = 0; _i < 2; ++_i) \
;         __builtin_amdgcn_global_load_lds((const unsigned*)((const char*)(gbase) + (voff)[_i]), (PG8_LAS unsigned*)(lds + (bufoff) + ldsw + _i * 8192), 16, 0, 0); } while (0)
; #define PG8_LDA(dst, b, h) do { _Pragma("unroll") for (int m = 0; m < 4; ++m) _Pragma("unroll") for (int k = 0; k < 2; ++k) dst[m][k] = *(const PG8_LAS bf16x8*)(lds + PG8_SA(b, h) + aoff + m * 2048 + k * 1024); } while (0)
; #define PG8_LDB(dst, b, h) do { _Pragma("unroll") for (int n = 0; n < 2; ++n) _Pragma("unroll") for (int k = 0; k < 2; ++k) dst[n][k] = *(const PG8_LAS bf16x8*)(lds + PG8_SB(b, h) + boff + n * 2048 + k * 1024); } while (0)
; #define PG8_MMA(ai, bj, At, Bt) do { __builtin_amdgcn_s_setprio(1); _Pragma("unroll") for (int m = 0; m < 4; ++m) _Pragma("unroll") for (int n = 0; n < 2; ++n) _Pragma("unroll") for (int k = 0; k < 2; ++k) \
;         acc[ai][bj][m][n] = __builtin_amdgcn_mfma_f32_16x16x32_bf16(Bt[n][k], At[m][k], acc[ai][bj][m][n], 0, 0, 0); __builtin_amdgcn_s_setprio(0); } while (0)
; #define PG8_WAIT_V(n) asm volatile("s_waitcnt vmcnt(" #n ")" ::: "memory")
; #define PG8_WAIT_L(n) asm volatile("s_waitcnt lgkmcnt(" #n ")" ::: "memory")
; template <class Epi, class Sched, bool ALIGN_EPI = false, bool SP2 = false>
; __device__ __forceinline__ void gemm_phase(PG8_LAS unsigned char* lds, const Gemm g, const Sched& S, const Epi& E) {
;     ...
;             const bool last = (t == nt - 2);
;             const char* a1 = cA + (size_t)(t + 1) * kstep;
;             const char* a2 = last ? nA : cA + (size_t)(t + 2) * kstep; const char* b2 = last ? nB : cB + (size_t)(t + 2) * kstep;
;             const char* a3 = a2 + kstep; const char* b3 = b2 + kstep;
;             if (last && has_next) S.a_ready(nxt);
;             if constexpr (SP2) {
;             PG8_LDB(B0, 0, 0); PG8_LDB(B1, 0, 1); PG8_SCHED; PG8_LDA(At, 0, 0); PG8_STAGE(PG8_SA(1, 1), a1 + hstep, voffA);
;             PG8_WAIT_V(8); PG8_WAIT_L(0); PG8_BAR; PG8_MMA(0, 0, At, B0); PG8_MMA(0, 1, At, B1); PG8_BAR; PG8_SCHED;
;             PG8_LDA(At, 0, 1); PG8_STAGE(PG8_SB(0, 0), b2, voffB); PG8_STAGE(PG8_SB(0, 1), b2 + hstep, voffB); PG8_STAGE(PG8_SA(0, 0), a2, voffA);
;             PG8_WAIT_V(8); PG8_WAIT_L(0); PG8_BAR; PG8_MMA(1, 0, At, B0); PG8_MMA(1, 1, At, B1); PG8_BAR; PG8_SCHED;
.LBB0_220:
	ds_read_b128 v[152:155], v148
	ds_read_b128 v[156:159], v148 offset:1024
	ds_read_b128 v[160:163], v148 offset:2048
	ds_read_b128 v[164:167], v148 offset:3072
	ds_read_b128 v[168:171], v149
	ds_read_b128 v[172:175], v149 offset:1024
	ds_read_b128 v[176:179], v149 offset:2048
	ds_read_b128 v[180:183], v149 offset:3072
	s_add_u32 s26, s24, 0xfff80080
	s_addc_u32 s27, s25, -1
	s_cmp_eq_u32 s51, 28
	s_cselect_b32 s29, s19, s27
	s_cselect_b32 s28, s47, s26
	s_cselect_b32 s27, s17, s50
	s_cselect_b32 s26, s48, s49
	v_lshl_add_u64 v[216:217], s[24:25], 0, v[136:137]
	s_add_i32 m0, s15, 0xc000
	ds_read_b128 v[184:187], v150
	ds_read_b128 v[188:191], v150 offset:1024
	ds_read_b128 v[192:195], v150 offset:2048
	ds_read_b128 v[196:199], v150 offset:3072
	ds_read_b128 v[200:203], v150 offset:4096
	ds_read_b128 v[204:207], v150 offset:5120
	ds_read_b128 v[208:211], v150 offset:6144
	ds_read_b128 v[212:215], v150 offset:7168
	global_load_lds_dwordx4 v[216:217], off
	v_lshl_add_u64 v[216:217], s[24:25], 0, v[138:139]
	s_add_i32 m0, s15, 0xe000
	s_nop 0
	global_load_lds_dwordx4 v[216:217], off
	s_waitcnt vmcnt(8)
	s_waitcnt lgkmcnt(0)
	s_barrier
	s_setprio 1
	s_waitcnt lgkmcnt(0)
	v_mfma_f32_16x16x32_bf16 v[124:127], v[152:155], v[184:187], v[124:127]
	v_mfma_f32_16x16x32_bf16 v[120:123], v[160:163], v[184:187], v[120:123]
	v_mfma_f32_16x16x32_bf16 v[116:119], v[152:155], v[192:195], v[116:119]
	v_mfma_f32_16x16x32_bf16 v[112:115], v[160:163], v[192:195], v[112:115]
	v_mfma_f32_16x16x32_bf16 v[100:103], v[152:155], v[200:203], v[100:103]
	v_mfma_f32_16x16x32_bf16 v[96:99], v[160:163], v[200:203], v[96:99]
	v_mfma_f32_16x16x32_bf16 v[84:87], v[152:155], v[208:211], v[84:87]
	v_mfma_f32_16x16x32_bf16 v[80:83], v[160:163], v[208:211], v[80:83]
	v_mfma_f32_16x16x32_bf16 v[124:127], v[156:159], v[188:191], v[124:127]
	v_mfma_f32_16x16x32_bf16 v[120:123], v[164:167], v[188:191], v[120:123]
	v_mfma_f32_16x16x32_bf16 v[116:119], v[156:159], v[196:199], v[116:119]
	v_mfma_f32_16x16x32_bf16 v[112:115], v[164:167], v[196:199], v[112:115]
	v_mfma_f32_16x16x32_bf16 v[100:103], v[156:159], v[204:207], v[100:103]
	v_mfma_f32_16x16x32_bf16 v[96:99], v[164:167], v[204:207], v[96:99]
	v_mfma_f32_16x16x32_bf16 v[84:87], v[156:159], v[212:215], v[84:87]
	v_mfma_f32_16x16x32_bf16 v[80:83], v[164:167], v[212:215], v[80:83]
	v_mfma_f32_16x16x32_bf16 v[108:111], v[168:171], v[184:187], v[108:111]
	v_mfma_f32_16x16x32_bf16 v[104:107], v[176:179], v[184:187], v[104:107]
	v_mfma_f32_16x16x32_bf16 v[92:95], v[168:171], v[192:195], v[92:95]
	v_mfma_f32_16x16x32_bf16 v[88:91], v[176:179], v[192:195], v[88:91]
	v_mfma_f32_16x16x32_bf16 v[76:79], v[168:171], v[200:203], v[76:79]
	v_mfma_f32_16x16x32_bf16 v[72:75], v[176:179], v[200:203], v[72:75]
	v_mfma_f32_16x16x32_bf16 v[68:71], v[168:171], v[208:211], v[68:71]
	v_mfma_f32_16x16x32_bf16 v[64:67], v[176:179], v[208:211], v[64:67]
	v_mfma_f32_16x16x32_bf16 v[108:111], v[172:175], v[188:191], v[108:111]
	v_mfma_f32_16x16x32_bf16 v[104:107], v[180:183], v[188:191], v[104:107]
	v_mfma_f32_16x16x32_bf16 v[92:95], v[172:175], v[196:199], v[92:95]
	v_mfma_f32_16x16x32_bf16 v[88:91], v[180:183], v[196:199], v[88:91]
	v_mfma_f32_16x16x32_bf16 v[76:79], v[172:175], v[204:207], v[76:79]
	v_mfma_f32_16x16x32_bf16 v[72:75], v[180:183], v[204:207], v[72:75]
	v_mfma_f32_16x16x32_bf16 v[68:71], v[172:175], v[212:215], v[68:71]
	v_mfma_f32_16x16x32_bf16 v[64:67], v[180:183], v[212:215], v[64:67]
	s_setprio 0
	s_barrier
	s_add_i32 s52, s43, s36
	v_lshl_add_u64 v[216:217], s[26:27], 0, v[132:133]
	s_mov_b32 m0, s52
	ds_read_b128 v[184:187], v150 offset:16384
	ds_read_b128 v[188:191], v150 offset:17408
	ds_read_b128 v[192:195], v150 offset:18432
	ds_read_b128 v[196:199], v150 offset:19456
	ds_read_b128 v[200:203], v150 offset:20480
	ds_read_b128 v[204:207], v150 offset:21504
	ds_read_b128 v[208:211], v150 offset:22528
	ds_read_b128 v[212:215], v150 offset:23552
	global_load_lds_dwordx4 v[216:217], off
	s_add_i32 m0, s52, 0x2000
	s_add_u32 s52, s26, 0x80000
	v_lshl_add_u64 v[218:219], s[26:27], 0, v[128:129]
	s_addc_u32 s53, s27, 0
	s_add_i32 s54, s44, s36
	global_load_lds_dwordx4 v[218:219], off
	v_lshl_add_u64 v[222:223], s[52:53], 0, v[132:133]
	s_mov_b32 m0, s54
	v_lshl_add_u64 v[224:225], s[28:29], 0, v[130:131]
	global_load_lds_dwordx4 v[222:223], off
	v_lshl_add_u64 v[222:223], s[52:53], 0, v[128:129]
	s_add_i32 m0, s54, 0x2000
	s_nop 0
	global_load_lds_dwordx4 v[222:223], off
	v_lshl_add_u64 v[222:223], s[28:29], 0, v[134:135]
	s_mov_b32 m0, s15
	s_nop 0
	global_load_lds_dwordx4 v[222:223], off
	s_mov_b32 m0, s37
	s_nop 0
	global_load_lds_dwordx4 v[224:225], off
	s_waitcnt vmcnt(8)
	s_waitcnt lgkmcnt(0)
	s_barrier
; #define PG8_STAGE(bufoff, gbase, voff) do { _Pragma("unroll") for (int _i = 0; _i < 2; ++_i) \
;         __builtin_amdgcn_global_load_lds((const unsigned*)((const char*)(gbase) + (voff)[_i]), (PG8_LAS unsigned*)(lds + (bufoff) + ldsw + _i * 8192), 16, 0, 0); } while (0)
; #define PG8_LDA(dst, b, h) do { _Pragma("unroll") for (int m = 0; m < 4; ++m) _Pragma("unroll") for (int k = 0; k < 2; ++k) dst[m][k] = *(const PG8_LAS bf16x8*)(lds + PG8_SA(b, h) + aoff + m * 2048 + k * 1024); } while (0)
; #define PG8_LDB(dst, b, h) do { _Pragma("unroll") for (int n = 0; n < 2; ++n) _Pragma("unroll") for (int k = 0; k < 2; ++k) dst[n][k] = *(const PG8_LAS bf16x8*)(lds + PG8_SB(b, h) + boff + n * 2048 + k * 1024); } while (0)
; #define PG8_MMA(ai, bj, At, Bt) do { __builtin_amdgcn_s_setprio(1); _Pragma("unroll") for (int m = 0; m < 4; ++m) _Pragma("unroll") for (int n = 0; n < 2; ++n) _Pragma("unroll") for (int k = 0; k < 2; ++k) \
;         acc[ai][bj][m][n] = __builtin_amdgcn_mfma_f32_16x16x32_bf16(Bt[n][k], At[m][k], acc[ai][bj][m][n], 0, 0, 0); __builtin_amdgcn_s_setprio(0); } while (0)
; #define PG8_WAIT_V(n) asm volatile("s_waitcnt vmcnt(" #n ")" ::: "memory")
; #define PG8_WAIT_L(n) asm volatile("s_waitcnt lgkmcnt(" #n ")" ::: "memory")
; #define PG8_BAR __builtin_amdgcn_s_barrier()
; #define PG8_SCHED __builtin_amdgcn_sched_barrier(0)
; template <class Epi, class Sched, bool ALIGN_EPI = false, bool SP2 = false>
; __device__ __forceinline__ void gemm_phase(PG8_LAS unsigned char* lds, const Gemm g, const Sched& S, const Epi& E) {
;     ...
;             PG8_WAIT_V(8); PG8_WAIT_L(0); PG8_BAR; PG8_MMA(1, 0, At, B0); PG8_MMA(1, 1, At, B1); PG8_BAR; PG8_SCHED;
;             PG8_LDB(B0, 1, 0); PG8_LDB(B1, 1, 1); PG8_SCHED; PG8_LDA(At, 1, 0); PG8_STAGE(PG8_SA(0, 1), a2 + hstep, voffA);
;             PG8_WAIT_V(8); PG8_WAIT_L(0); PG8_BAR; PG8_MMA(0, 0, At, B0); PG8_MMA(0, 1, At, B1); PG8_BAR; PG8_SCHED;
	s_setprio 1
	s_waitcnt lgkmcnt(0)
	v_mfma_f32_16x16x32_bf16 v[60:63], v[152:155], v[184:187], v[60:63]
	v_mfma_f32_16x16x32_bf16 v[56:59], v[160:163], v[184:187], v[56:59]
	v_mfma_f32_16x16x32_bf16 v[52:55], v[152:155], v[192:195], v[52:55]
	v_mfma_f32_16x16x32_bf16 v[48:51], v[160:163], v[192:195], v[48:51]
	v_mfma_f32_16x16x32_bf16 v[36:39], v[152:155], v[200:203], v[36:39]
	v_mfma_f32_16x16x32_bf16 v[32:35], v[160:163], v[200:203], v[32:35]
	v_mfma_f32_16x16x32_bf16 v[20:23], v[152:155], v[208:211], v[20:23]
	v_mfma_f32_16x16x32_bf16 v[16:19], v[160:163], v[208:211], v[16:19]
	v_mfma_f32_16x16x32_bf16 v[60:63], v[156:159], v[188:191], v[60:63]
	v_mfma_f32_16x16x32_bf16 v[56:59], v[164:167], v[188:191], v[56:59]
	v_mfma_f32_16x16x32_bf16 v[52:55], v[156:159], v[196:199], v[52:55]
	v_mfma_f32_16x16x32_bf16 v[48:51], v[164:167], v[196:199], v[48:51]
	v_mfma_f32_16x16x32_bf16 v[36:39], v[156:159], v[204:207], v[36:39]
	v_mfma_f32_16x16x32_bf16 v[32:35], v[164:167], v[204:207], v[32:35]
	v_mfma_f32_16x16x32_bf16 v[20:23], v[156:159], v[212:215], v[20:23]
	v_mfma_f32_16x16x32_bf16 v[16:19], v[164:167], v[212:215], v[16:19]
	v_mfma_f32_16x16x32_bf16 v[44:47], v[168:171], v[184:187], v[44:47]
	v_mfma_f32_16x16x32_bf16 v[40:43], v[176:179], v[184:187], v[40:43]
	v_mfma_f32_16x16x32_bf16 v[28:31], v[168:171], v[192:195], v[28:31]
	v_mfma_f32_16x16x32_bf16 v[24:27], v[176:179], v[192:195], v[24:27]
	v_mfma_f32_16x16x32_bf16 v[12:15], v[168:171], v[200:203], v[12:15]
	v_mfma_f32_16x16x32_bf16 v[8:11], v[176:179], v[200:203], v[8:11]
	v_mfma_f32_16x16x32_bf16 v[4:7], v[168:171], v[208:211], v[4:7]
	v_mfma_f32_16x16x32_bf16 v[0:3], v[176:179], v[208:211], v[0:3]
	v_mfma_f32_16x16x32_bf16 v[44:47], v[172:175], v[188:191], v[44:47]
	v_mfma_f32_16x16x32_bf16 v[40:43], v[180:183], v[188:191], v[40:43]
	v_mfma_f32_16x16x32_bf16 v[28:31], v[172:175], v[196:199], v[28:31]
	v_mfma_f32_16x16x32_bf16 v[24:27], v[180:183], v[196:199], v[24:27]
	v_mfma_f32_16x16x32_bf16 v[12:15], v[172:175], v[204:207], v[12:15]
	v_mfma_f32_16x16x32_bf16 v[8:11], v[180:183], v[204:207], v[8:11]
	v_mfma_f32_16x16x32_bf16 v[4:7], v[172:175], v[212:215], v[4:7]
	v_mfma_f32_16x16x32_bf16 v[0:3], v[180:183], v[212:215], v[0:3]
	s_setprio 0
	s_barrier
	s_add_i32 s52, 0, 0x18000
	v_add_u32_e32 v151, s52, v146
	s_add_i32 s53, 0, 0x1c000
	ds_read_b128 v[152:155], v151
	ds_read_b128 v[156:159], v151 offset:1024
	ds_read_b128 v[160:163], v151 offset:2048
	ds_read_b128 v[164:167], v151 offset:3072
	v_add_u32_e32 v151, s53, v146
	ds_read_b128 v[168:171], v151
	ds_read_b128 v[172:175], v151 offset:1024
	ds_read_b128 v[176:179], v151 offset:2048
	ds_read_b128 v[180:183], v151 offset:3072
	s_add_u32 s28, s28, 0x80000
	s_addc_u32 s29, s29, 0
	s_mov_b32 m0, s38
	v_lshl_add_u64 v[226:227], s[28:29], 0, v[134:135]
	ds_read_b128 v[184:187], v150 offset:32768
	ds_read_b128 v[188:191], v150 offset:33792
	ds_read_b128 v[192:195], v150 offset:34816
	ds_read_b128 v[196:199], v150 offset:35840
	ds_read_b128 v[200:203], v150 offset:36864
	ds_read_b128 v[204:207], v150 offset:37888
	ds_read_b128 v[208:211], v150 offset:38912
	ds_read_b128 v[212:215], v150 offset:39936
	global_load_lds_dwordx4 v[226:227], off
	v_lshl_add_u64 v[226:227], s[28:29], 0, v[130:131]
	s_mov_b32 m0, s39
	s_nop 0
	global_load_lds_dwordx4 v[226:227], off
	s_waitcnt vmcnt(8)
	s_waitcnt lgkmcnt(0)
	s_barrier
	s_setprio 1
	s_waitcnt lgkmcnt(0)
	v_mfma_f32_16x16x32_bf16 v[124:127], v[152:155], v[184:187], v[124:127]
	v_mfma_f32_16x16x32_bf16 v[120:123], v[160:163], v[184:187], v[120:123]
	v_mfma_f32_16x16x32_bf16 v[116:119], v[152:155], v[192:195], v[116:119]
	v_mfma_f32_16x16x32_bf16 v[112:115], v[160:163], v[192:195], v[112:115]
	v_mfma_f32_16x16x32_bf16 v[100:103], v[152:155], v[200:203], v[100:103]
	v_mfma_f32_16x16x32_bf16 v[96:99], v[160:163], v[200:203], v[96:99]
	v_mfma_f32_16x16x32_bf16 v[84:87], v[152:155], v[208:211], v[84:87]
	v_mfma_f32_16x16x32_bf16 v[80:83], v[160:163], v[208:211], v[80:83]
	v_mfma_f32_16x16x32_bf16 v[124:127], v[156:159], v[188:191], v[124:127]
	v_mfma_f32_16x16x32_bf16 v[120:123], v[164:167], v[188:191], v[120:123]
	v_mfma_f32_16x16x32_bf16 v[116:119], v[156:159], v[196:199], v[116:119]
	v_mfma_f32_16x16x32_bf16 v[112:115], v[164:167], v[196:199], v[112:115]
	v_mfma_f32_16x16x32_bf16 v[100:103], v[156:159], v[204:207], v[100:103]
	v_mfma_f32_16x16x32_bf16 v[96:99], v[164:167], v[204:207], v[96:99]
	v_mfma_f32_16x16x32_bf16 v[84:87], v[156:159], v[212:215], v[84:87]
	v_mfma_f32_16x16x32_bf16 v[80:83], v[164:167], v[212:215], v[80:83]
	v_mfma_f32_16x16x32_bf16 v[108:111], v[168:171], v[184:187], v[108:111]
	v_mfma_f32_16x16x32_bf16 v[104:107], v[176:179], v[184:187], v[104:107]
	v_mfma_f32_16x16x32_bf16 v[92:95], v[168:171], v[192:195], v[92:95]
	v_mfma_f32_16x16x32_bf16 v[88:91], v[176:179], v[192:195], v[88:91]
	v_mfma_f32_16x16x32_bf16 v[76:79], v[168:171], v[200:203], v[76:79]
	v_mfma_f32_16x16x32_bf16 v[72:75], v[176:179], v[200:203], v[72:75]
	v_mfma_f32_16x16x32_bf16 v[68:71], v[168:171], v[208:211], v[68:71]
	v_mfma_f32_16x16x32_bf16 v[64:67], v[176:179], v[208:211], v[64:67]
	v_mfma_f32_16x16x32_bf16 v[108:111], v[172:175], v[188:191], v[108:111]
	v_mfma_f32_16x16x32_bf16 v[104:107], v[180:183], v[188:191], v[104:107]
	v_mfma_f32_16x16x32_bf16 v[92:95], v[172:175], v[196:199], v[92:95]
	v_mfma_f32_16x16x32_bf16 v[88:91], v[180:183], v[196:199], v[88:91]
	v_mfma_f32_16x16x32_bf16 v[76:79], v[172:175], v[204:207], v[76:79]
	v_mfma_f32_16x16x32_bf16 v[72:75], v[180:183], v[204:207], v[72:75]
	v_mfma_f32_16x16x32_bf16 v[68:71], v[172:175], v[212:215], v[68:71]
	v_mfma_f32_16x16x32_bf16 v[64:67], v[180:183], v[212:215], v[64:67]
	s_setprio 0
	s_barrier
; #define PG8_STAGE(bufoff, gbase, voff) do { _Pragma("unroll") for (int _i = 0; _i < 2; ++_i) \
;         __builtin_amdgcn_global_load_lds((const unsigned*)((const char*)(gbase) + (voff)[_i]), (PG8_LAS unsigned*)(lds + (bufoff) + ldsw + _i * 8192), 16, 0, 0); } while (0)
; #define PG8_LDA(dst, b, h) do { _Pragma("unroll") for (int m = 0; m < 4; ++m) _Pragma("unroll") for (int k = 0; k < 2; ++k) dst[m][k] = *(const PG8_LAS bf16x8*)(lds + PG8_SA(b, h) + aoff + m * 2048 + k * 1024); } while (0)
; #define PG8_MMA(ai, bj, At, Bt) do { __builtin_amdgcn_s_setprio(1); _Pragma("unroll") for (int m = 0; m < 4; ++m) _Pragma("unroll") for (int n = 0; n < 2; ++n) _Pragma("unroll") for (int k = 0; k < 2; ++k) \
;         acc[ai][bj][m][n] = __builtin_amdgcn_mfma_f32_16x16x32_bf16(Bt[n][k], At[m][k], acc[ai][bj][m][n], 0, 0, 0); __builtin_amdgcn_s_setprio(0); } while (0)
; #define PG8_WAIT_V(n) asm volatile("s_waitcnt vmcnt(" #n ")" ::: "memory")
; #define PG8_WAIT_L(n) asm volatile("s_waitcnt lgkmcnt(" #n ")" ::: "memory")
; #define PG8_BAR __builtin_amdgcn_s_barrier()
; #define PG8_SCHED __builtin_amdgcn_sched_barrier(0)
; template <class Epi, class Sched, bool ALIGN_EPI = false, bool SP2 = false>
; __device__ __forceinline__ void gemm_phase(PG8_LAS unsigned char* lds, const Gemm g, const Sched& S, const Epi& E) {
;     ...
;             PG8_LDA(At, 1, 1); PG8_STAGE(PG8_SB(1, 0), b3, voffB); PG8_STAGE(PG8_SB(1, 1), b3 + hstep, voffB); PG8_STAGE(PG8_SA(1, 0), a3, voffA);
;             PG8_WAIT_V(8); PG8_WAIT_L(0); PG8_BAR; PG8_MMA(1, 0, At, B0); PG8_MMA(1, 1, At, B1); PG8_BAR; PG8_SCHED;
;     ...
;         if constexpr (ALIGN_EPI) { if (wr == 0) PG8_BAR; }
	s_add_i32 s28, s52, s36
	v_lshl_add_u64 v[216:217], v[216:217], 0, s[10:11]
	s_mov_b32 m0, s28
	ds_read_b128 v[184:187], v150 offset:49152
	ds_read_b128 v[188:191], v150 offset:50176
	ds_read_b128 v[192:195], v150 offset:51200
	ds_read_b128 v[196:199], v150 offset:52224
	ds_read_b128 v[200:203], v150 offset:53248
	ds_read_b128 v[204:207], v150 offset:54272
	ds_read_b128 v[208:211], v150 offset:55296
	ds_read_b128 v[212:215], v150 offset:56320
	global_load_lds_dwordx4 v[216:217], off
	s_add_i32 m0, s28, 0x2000
	s_add_u32 s26, s26, 0x80080
	v_lshl_add_u64 v[216:217], v[218:219], 0, s[10:11]
	s_addc_u32 s27, s27, 0
	s_add_i32 s28, s53, s36
	global_load_lds_dwordx4 v[216:217], off
	v_lshl_add_u64 v[216:217], s[26:27], 0, v[132:133]
	s_mov_b32 m0, s28
	s_nop 0
	global_load_lds_dwordx4 v[216:217], off
	v_lshl_add_u64 v[216:217], s[26:27], 0, v[128:129]
	s_add_i32 m0, s28, 0x2000
	s_nop 0
	global_load_lds_dwordx4 v[216:217], off
	v_lshl_add_u64 v[216:217], v[222:223], 0, s[10:11]
	s_mov_b32 m0, s41
	s_nop 0
	global_load_lds_dwordx4 v[216:217], off
	v_lshl_add_u64 v[216:217], v[224:225], 0, s[10:11]
	s_mov_b32 m0, s42
	s_nop 0
	global_load_lds_dwordx4 v[216:217], off
	s_waitcnt vmcnt(8)
	s_waitcnt lgkmcnt(0)
	s_barrier
	s_setprio 1
	s_waitcnt lgkmcnt(0)
	v_mfma_f32_16x16x32_bf16 v[60:63], v[152:155], v[184:187], v[60:63]
	v_mfma_f32_16x16x32_bf16 v[56:59], v[160:163], v[184:187], v[56:59]
	v_mfma_f32_16x16x32_bf16 v[52:55], v[152:155], v[192:195], v[52:55]
	v_mfma_f32_16x16x32_bf16 v[48:51], v[160:163], v[192:195], v[48:51]
	v_mfma_f32_16x16x32_bf16 v[36:39], v[152:155], v[200:203], v[36:39]
	v_mfma_f32_16x16x32_bf16 v[32:35], v[160:163], v[200:203], v[32:35]
	v_mfma_f32_16x16x32_bf16 v[20:23], v[152:155], v[208:211], v[20:23]
	v_mfma_f32_16x16x32_bf16 v[16:19], v[160:163], v[208:211], v[16:19]
	v_mfma_f32_16x16x32_bf16 v[60:63], v[156:159], v[188:191], v[60:63]
	v_mfma_f32_16x16x32_bf16 v[56:59], v[164:167], v[188:191], v[56:59]
	v_mfma_f32_16x16x32_bf16 v[52:55], v[156:159], v[196:199], v[52:55]
	v_mfma_f32_16x16x32_bf16 v[48:51], v[164:167], v[196:199], v[48:51]
	v_mfma_f32_16x16x32_bf16 v[36:39], v[156:159], v[204:207], v[36:39]
	v_mfma_f32_16x16x32_bf16 v[32:35], v[164:167], v[204:207], v[32:35]
	v_mfma_f32_16x16x32_bf16 v[20:23], v[156:159], v[212:215], v[20:23]
	v_mfma_f32_16x16x32_bf16 v[16:19], v[164:167], v[212:215], v[16:19]
	v_mfma_f32_16x16x32_bf16 v[44:47], v[168:171], v[184:187], v[44:47]
	v_mfma_f32_16x16x32_bf16 v[40:43], v[176:179], v[184:187], v[40:43]
	v_mfma_f32_16x16x32_bf16 v[28:31], v[168:171], v[192:195], v[28:31]
	v_mfma_f32_16x16x32_bf16 v[24:27], v[176:179], v[192:195], v[24:27]
	v_mfma_f32_16x16x32_bf16 v[12:15], v[168:171], v[200:203], v[12:15]
	v_mfma_f32_16x16x32_bf16 v[8:11], v[176:179], v[200:203], v[8:11]
	v_mfma_f32_16x16x32_bf16 v[4:7], v[168:171], v[208:211], v[4:7]
	v_mfma_f32_16x16x32_bf16 v[0:3], v[176:179], v[208:211], v[0:3]
	v_mfma_f32_16x16x32_bf16 v[44:47], v[172:175], v[188:191], v[44:47]
	v_mfma_f32_16x16x32_bf16 v[40:43], v[180:183], v[188:191], v[40:43]
	v_mfma_f32_16x16x32_bf16 v[28:31], v[172:175], v[196:199], v[28:31]
	v_mfma_f32_16x16x32_bf16 v[24:27], v[180:183], v[196:199], v[24:27]
	v_mfma_f32_16x16x32_bf16 v[12:15], v[172:175], v[204:207], v[12:15]
	v_mfma_f32_16x16x32_bf16 v[8:11], v[180:183], v[204:207], v[8:11]
	v_mfma_f32_16x16x32_bf16 v[4:7], v[172:175], v[212:215], v[4:7]
	v_mfma_f32_16x16x32_bf16 v[0:3], v[180:183], v[212:215], v[0:3]
	s_setprio 0
	s_barrier
	s_add_i32 s51, s51, 2
	s_add_u32 s24, s24, 0x100
	s_addc_u32 s25, s25, 0
	s_add_u32 s49, s49, 0x100
	s_addc_u32 s50, s50, 0
	s_cmp_gt_u32 s51, 29
	s_cbranch_scc0 .LBB0_220
	s_and_b64 vcc, exec, s[12:13]
	s_cbranch_vccz .LBB0_223
	s_barrier

; #define PG8_STAGE(bufoff, gbase, voff) do { _Pragma("unroll") for (int _i = 0; _i < 2; ++_i) \
;         __builtin_amdgcn_global_load_lds((const unsigned*)((const char*)(gbase) + (voff)[_i]), (PG8_LAS unsigned*)(lds + (bufoff) + ldsw + _i * 8192), 16, 0, 0); } while (0)
; #define PG8_LDA(dst, b, h) do { _Pragma("unroll") for (int m = 0; m < 4; ++m) _Pragma("unroll") for (int k = 0; k < 2; ++k) dst[m][k] = *(const PG8_LAS bf16x8*)(lds + PG8_SA(b, h) + aoff + m * 2048 + k * 1024); } while (0)
; #define PG8_LDB(dst, b, h) do { _Pragma("unroll") for (int n = 0; n < 2; ++n) _Pragma("unroll") for (int k = 0; k < 2; ++k) dst[n][k] = *(const PG8_LAS bf16x8*)(lds + PG8_SB(b, h) + boff + n * 2048 + k * 1024); } while (0)
; #define PG8_MMA(ai, bj, At, Bt) do { __builtin_amdgcn_s_setprio(1); _Pragma("unroll") for (int m = 0; m < 4; ++m) _Pragma("unroll") for (int n = 0; n < 2; ++n) _Pragma("unroll") for (int k = 0; k < 2; ++k) \
;         acc[ai][bj][m][n] = __builtin_amdgcn_mfma_f32_16x16x32_bf16(Bt[n][k], At[m][k], acc[ai][bj][m][n], 0, 0, 0); __builtin_amdgcn_s_setprio(0); } while (0)
; #define PG8_WAIT_V(n) asm volatile("s_waitcnt vmcnt(" #n ")" ::: "memory")
; #define PG8_WAIT_L(n) asm volatile("s_waitcnt lgkmcnt(" #n ")" ::: "memory")
; template <class Epi, class Sched, bool ALIGN_EPI = false, bool SP2 = false>
; __device__ __forceinline__ void gemm_phase(PG8_LAS unsigned char* lds, const Gemm g, const Sched& S, const Epi& E) {
;     ...
;             const bool last = (t == nt - 2);
;             const char* a1 = cA + (size_t)(t + 1) * kstep;
;             const char* a2 = last ? nA : cA + (size_t)(t + 2) * kstep; const char* b2 = last ? nB : cB + (size_t)(t + 2) * kstep;
;             const char* a3 = a2 + kstep; const char* b3 = b2 + kstep;
;             if (last && has_next) S.a_ready(nxt);
;             if constexpr (SP2) {
;             PG8_LDB(B0, 0, 0); PG8_LDB(B1, 0, 1); PG8_SCHED; PG8_LDA(At, 0, 0); PG8_STAGE(PG8_SA(1, 1), a1 + hstep, voffA);
;             PG8_WAIT_V(8); PG8_WAIT_L(0); PG8_BAR; PG8_MMA(0, 0, At, B0); PG8_MMA(0, 1, At, B1); PG8_BAR; PG8_SCHED;
;             PG8_LDA(At, 0, 1); PG8_STAGE(PG8_SB(0, 0), b2, voffB); PG8_STAGE(PG8_SB(0, 1), b2 + hstep, voffB); PG8_STAGE(PG8_SA(0, 0), a2, voffA);
;             PG8_WAIT_V(8); PG8_WAIT_L(0); PG8_BAR; PG8_MMA(1, 0, At, B0); PG8_MMA(1, 1, At, B1); PG8_BAR; PG8_SCHED;
.LBB0_502:
	ds_read_b128 v[108:111], v223
	ds_read_b128 v[116:119], v223 offset:1024
	ds_read_b128 v[120:123], v223 offset:2048
	ds_read_b128 v[124:127], v223 offset:3072
	ds_read_b128 v[144:147], v224
	ds_read_b128 v[148:151], v224 offset:1024
	ds_read_b128 v[152:155], v224 offset:2048
	ds_read_b128 v[156:159], v224 offset:3072
	s_add_u32 s44, s40, 0xfff80080
	s_addc_u32 s45, s41, -1
	s_cmp_eq_u32 s67, 28
	s_cselect_b32 s47, s65, s45
	s_cselect_b32 s46, s66, s44
	s_cselect_b32 s45, s21, s43
	s_cselect_b32 s44, s20, s42
	s_mov_b32 m0, s58
	v_lshl_add_u64 v[216:217], s[40:41], 0, v[180:181]
	ds_read_b128 v[184:187], v225
	ds_read_b128 v[188:191], v225 offset:1024
	ds_read_b128 v[192:195], v225 offset:2048
	ds_read_b128 v[196:199], v225 offset:3072
	ds_read_b128 v[200:203], v225 offset:4096
	ds_read_b128 v[204:207], v225 offset:5120
	ds_read_b128 v[208:211], v225 offset:6144
	ds_read_b128 v[212:215], v225 offset:7168
	global_load_lds_dwordx4 v[216:217], off
	v_lshl_add_u64 v[216:217], s[40:41], 0, v[182:183]
	s_mov_b32 m0, s59
	s_nop 0
	global_load_lds_dwordx4 v[216:217], off
	s_waitcnt vmcnt(8)
	s_waitcnt lgkmcnt(0)
	s_barrier
	s_setprio 1
	s_waitcnt lgkmcnt(0)
	v_mfma_f32_16x16x32_bf16 v[140:143], v[108:111], v[184:187], v[140:143]
	v_mfma_f32_16x16x32_bf16 v[136:139], v[120:123], v[184:187], v[136:139]
	v_mfma_f32_16x16x32_bf16 v[112:115], v[108:111], v[192:195], v[112:115]
	v_mfma_f32_16x16x32_bf16 v[104:107], v[120:123], v[192:195], v[104:107]
	v_mfma_f32_16x16x32_bf16 v[92:95], v[108:111], v[200:203], v[92:95]
	v_mfma_f32_16x16x32_bf16 v[88:91], v[120:123], v[200:203], v[88:91]
	v_mfma_f32_16x16x32_bf16 v[76:79], v[108:111], v[208:211], v[76:79]
	v_mfma_f32_16x16x32_bf16 v[72:75], v[120:123], v[208:211], v[72:75]
	v_mfma_f32_16x16x32_bf16 v[140:143], v[116:119], v[188:191], v[140:143]
	v_mfma_f32_16x16x32_bf16 v[136:139], v[124:127], v[188:191], v[136:139]
	v_mfma_f32_16x16x32_bf16 v[112:115], v[116:119], v[196:199], v[112:115]
	v_mfma_f32_16x16x32_bf16 v[104:107], v[124:127], v[196:199], v[104:107]
	v_mfma_f32_16x16x32_bf16 v[92:95], v[116:119], v[204:207], v[92:95]
	v_mfma_f32_16x16x32_bf16 v[88:91], v[124:127], v[204:207], v[88:91]
	v_mfma_f32_16x16x32_bf16 v[76:79], v[116:119], v[212:215], v[76:79]
	v_mfma_f32_16x16x32_bf16 v[72:75], v[124:127], v[212:215], v[72:75]
	v_mfma_f32_16x16x32_bf16 v[132:135], v[144:147], v[184:187], v[132:135]
	v_mfma_f32_16x16x32_bf16 v[128:131], v[152:155], v[184:187], v[128:131]
	v_mfma_f32_16x16x32_bf16 v[100:103], v[144:147], v[192:195], v[100:103]
	v_mfma_f32_16x16x32_bf16 v[96:99], v[152:155], v[192:195], v[96:99]
	v_mfma_f32_16x16x32_bf16 v[84:87], v[144:147], v[200:203], v[84:87]
	v_mfma_f32_16x16x32_bf16 v[80:83], v[152:155], v[200:203], v[80:83]
	v_mfma_f32_16x16x32_bf16 v[68:71], v[144:147], v[208:211], v[68:71]
	v_mfma_f32_16x16x32_bf16 v[64:67], v[152:155], v[208:211], v[64:67]
	v_mfma_f32_16x16x32_bf16 v[132:135], v[148:151], v[188:191], v[132:135]
	v_mfma_f32_16x16x32_bf16 v[128:131], v[156:159], v[188:191], v[128:131]
	v_mfma_f32_16x16x32_bf16 v[100:103], v[148:151], v[196:199], v[100:103]
	v_mfma_f32_16x16x32_bf16 v[96:99], v[156:159], v[196:199], v[96:99]
	v_mfma_f32_16x16x32_bf16 v[84:87], v[148:151], v[204:207], v[84:87]
	v_mfma_f32_16x16x32_bf16 v[80:83], v[156:159], v[204:207], v[80:83]
	v_mfma_f32_16x16x32_bf16 v[68:71], v[148:151], v[212:215], v[68:71]
	v_mfma_f32_16x16x32_bf16 v[64:67], v[156:159], v[212:215], v[64:67]
	s_setprio 0
	s_barrier
	s_mov_b32 m0, s60
	v_lshl_add_u64 v[216:217], s[44:45], 0, v[162:163]
	s_add_u32 s68, s44, 0x80000
	ds_read_b128 v[184:187], v225 offset:16384
	ds_read_b128 v[188:191], v225 offset:17408
	ds_read_b128 v[192:195], v225 offset:18432
	ds_read_b128 v[196:199], v225 offset:19456
	ds_read_b128 v[200:203], v225 offset:20480
	ds_read_b128 v[204:207], v225 offset:21504
	ds_read_b128 v[208:211], v225 offset:22528
	ds_read_b128 v[212:215], v225 offset:23552
	global_load_lds_dwordx4 v[216:217], off
	v_lshl_add_u64 v[218:219], s[44:45], 0, v[160:161]
	s_mov_b32 m0, s61
	s_addc_u32 s69, s45, 0
	global_load_lds_dwordx4 v[218:219], off
	v_lshl_add_u64 v[228:229], s[68:69], 0, v[162:163]
	s_mov_b32 m0, s62
	v_lshl_add_u64 v[230:231], s[46:47], 0, v[160:161]
	global_load_lds_dwordx4 v[228:229], off
	v_lshl_add_u64 v[228:229], s[68:69], 0, v[160:161]
	s_add_i32 m0, s62, 0x2000
	s_nop 0
	global_load_lds_dwordx4 v[228:229], off
	v_lshl_add_u64 v[228:229], s[46:47], 0, v[162:163]
	s_mov_b32 m0, s19
	s_nop 0
	global_load_lds_dwordx4 v[228:229], off
	s_mov_b32 m0, s49
	s_nop 0
	global_load_lds_dwordx4 v[230:231], off
	s_waitcnt vmcnt(8)
	s_waitcnt lgkmcnt(0)
	s_barrier
; #define PG8_STAGE(bufoff, gbase, voff) do { _Pragma("unroll") for (int _i = 0; _i < 2; ++_i) \
;         __builtin_amdgcn_global_load_lds((const unsigned*)((const char*)(gbase) + (voff)[_i]), (PG8_LAS unsigned*)(lds + (bufoff) + ldsw + _i * 8192), 16, 0, 0); } while (0)
; #define PG8_LDA(dst, b, h) do { _Pragma("unroll") for (int m = 0; m < 4; ++m) _Pragma("unroll") for (int k = 0; k < 2; ++k) dst[m][k] = *(const PG8_LAS bf16x8*)(lds + PG8_SA(b, h) + aoff + m * 2048 + k * 1024); } while (0)
; #define PG8_LDB(dst, b, h) do { _Pragma("unroll") for (int n = 0; n < 2; ++n) _Pragma("unroll") for (int k = 0; k < 2; ++k) dst[n][k] = *(const PG8_LAS bf16x8*)(lds + PG8_SB(b, h) + boff + n * 2048 + k * 1024); } while (0)
; #define PG8_MMA(ai, bj, At, Bt) do { __builtin_amdgcn_s_setprio(1); _Pragma("unroll") for (int m = 0; m < 4; ++m) _Pragma("unroll") for (int n = 0; n < 2; ++n) _Pragma("unroll") for (int k = 0; k < 2; ++k) \
;         acc[ai][bj][m][n] = __builtin_amdgcn_mfma_f32_16x16x32_bf16(Bt[n][k], At[m][k], acc[ai][bj][m][n], 0, 0, 0); __builtin_amdgcn_s_setprio(0); } while (0)
; #define PG8_WAIT_V(n) asm volatile("s_waitcnt vmcnt(" #n ")" ::: "memory")
; #define PG8_WAIT_L(n) asm volatile("s_waitcnt lgkmcnt(" #n ")" ::: "memory")
; #define PG8_BAR __builtin_amdgcn_s_barrier()
; #define PG8_SCHED __builtin_amdgcn_sched_barrier(0)
; template <class Epi, class Sched, bool ALIGN_EPI = false, bool SP2 = false>
; __device__ __forceinline__ void gemm_phase(PG8_LAS unsigned char* lds, const Gemm g, const Sched& S, const Epi& E) {
;     ...
;             PG8_WAIT_V(8); PG8_WAIT_L(0); PG8_BAR; PG8_MMA(1, 0, At, B0); PG8_MMA(1, 1, At, B1); PG8_BAR; PG8_SCHED;
;             PG8_LDB(B0, 1, 0); PG8_LDB(B1, 1, 1); PG8_SCHED; PG8_LDA(At, 1, 0); PG8_STAGE(PG8_SA(0, 1), a2 + hstep, voffA);
;             PG8_WAIT_V(8); PG8_WAIT_L(0); PG8_BAR; PG8_MMA(0, 0, At, B0); PG8_MMA(0, 1, At, B1); PG8_BAR; PG8_SCHED;
	s_setprio 1
	s_waitcnt lgkmcnt(0)
	v_mfma_f32_16x16x32_bf16 v[60:63], v[108:111], v[184:187], v[60:63]
	v_mfma_f32_16x16x32_bf16 v[56:59], v[120:123], v[184:187], v[56:59]
	v_mfma_f32_16x16x32_bf16 v[44:47], v[108:111], v[192:195], v[44:47]
	v_mfma_f32_16x16x32_bf16 v[40:43], v[120:123], v[192:195], v[40:43]
	v_mfma_f32_16x16x32_bf16 v[28:31], v[108:111], v[200:203], v[28:31]
	v_mfma_f32_16x16x32_bf16 v[24:27], v[120:123], v[200:203], v[24:27]
	v_mfma_f32_16x16x32_bf16 v[12:15], v[108:111], v[208:211], v[12:15]
	v_mfma_f32_16x16x32_bf16 v[8:11], v[120:123], v[208:211], v[8:11]
	v_mfma_f32_16x16x32_bf16 v[60:63], v[116:119], v[188:191], v[60:63]
	v_mfma_f32_16x16x32_bf16 v[56:59], v[124:127], v[188:191], v[56:59]
	v_mfma_f32_16x16x32_bf16 v[44:47], v[116:119], v[196:199], v[44:47]
	v_mfma_f32_16x16x32_bf16 v[40:43], v[124:127], v[196:199], v[40:43]
	v_mfma_f32_16x16x32_bf16 v[28:31], v[116:119], v[204:207], v[28:31]
	v_mfma_f32_16x16x32_bf16 v[24:27], v[124:127], v[204:207], v[24:27]
	v_mfma_f32_16x16x32_bf16 v[12:15], v[116:119], v[212:215], v[12:15]
	v_mfma_f32_16x16x32_bf16 v[8:11], v[124:127], v[212:215], v[8:11]
	v_mfma_f32_16x16x32_bf16 v[52:55], v[144:147], v[184:187], v[52:55]
	v_mfma_f32_16x16x32_bf16 v[48:51], v[152:155], v[184:187], v[48:51]
	v_mfma_f32_16x16x32_bf16 v[36:39], v[144:147], v[192:195], v[36:39]
	v_mfma_f32_16x16x32_bf16 v[32:35], v[152:155], v[192:195], v[32:35]
	v_mfma_f32_16x16x32_bf16 v[20:23], v[144:147], v[200:203], v[20:23]
	v_mfma_f32_16x16x32_bf16 v[16:19], v[152:155], v[200:203], v[16:19]
	v_mfma_f32_16x16x32_bf16 v[4:7], v[144:147], v[208:211], v[4:7]
	v_mfma_f32_16x16x32_bf16 v[0:3], v[152:155], v[208:211], v[0:3]
	v_mfma_f32_16x16x32_bf16 v[52:55], v[148:151], v[188:191], v[52:55]
	v_mfma_f32_16x16x32_bf16 v[48:51], v[156:159], v[188:191], v[48:51]
	v_mfma_f32_16x16x32_bf16 v[36:39], v[148:151], v[196:199], v[36:39]
	v_mfma_f32_16x16x32_bf16 v[32:35], v[156:159], v[196:199], v[32:35]
	v_mfma_f32_16x16x32_bf16 v[20:23], v[148:151], v[204:207], v[20:23]
	v_mfma_f32_16x16x32_bf16 v[16:19], v[156:159], v[204:207], v[16:19]
	v_mfma_f32_16x16x32_bf16 v[4:7], v[148:151], v[212:215], v[4:7]
	v_mfma_f32_16x16x32_bf16 v[0:3], v[156:159], v[212:215], v[0:3]
	s_setprio 0
	s_barrier
	s_add_i32 s68, 0, 0x18000
	s_add_i32 s69, 0, 0x1c000
	v_add_u32_e32 v124, s68, v222
	v_add_u32_e32 v156, s69, v222
	ds_read_b128 v[108:111], v124
	ds_read_b128 v[116:119], v124 offset:1024
	ds_read_b128 v[120:123], v124 offset:2048
	ds_read_b128 v[124:127], v124 offset:3072
	ds_read_b128 v[144:147], v156
	ds_read_b128 v[148:151], v156 offset:1024
	ds_read_b128 v[152:155], v156 offset:2048
	ds_read_b128 v[156:159], v156 offset:3072
	s_add_u32 s46, s46, 0x80000
	s_addc_u32 s47, s47, 0
	s_mov_b32 m0, s50
	v_lshl_add_u64 v[232:233], s[46:47], 0, v[162:163]
	ds_read_b128 v[184:187], v225 offset:32768
	ds_read_b128 v[188:191], v225 offset:33792
	ds_read_b128 v[192:195], v225 offset:34816
	ds_read_b128 v[196:199], v225 offset:35840
	ds_read_b128 v[200:203], v225 offset:36864
	ds_read_b128 v[204:207], v225 offset:37888
	ds_read_b128 v[208:211], v225 offset:38912
	ds_read_b128 v[212:215], v225 offset:39936
	global_load_lds_dwordx4 v[232:233], off
	v_lshl_add_u64 v[232:233], s[46:47], 0, v[160:161]
	s_mov_b32 m0, s51
	s_nop 0
	global_load_lds_dwordx4 v[232:233], off
	s_waitcnt vmcnt(8)
	s_waitcnt lgkmcnt(0)
	s_barrier
	s_setprio 1
	s_waitcnt lgkmcnt(0)
	v_mfma_f32_16x16x32_bf16 v[140:143], v[108:111], v[184:187], v[140:143]
	v_mfma_f32_16x16x32_bf16 v[136:139], v[120:123], v[184:187], v[136:139]
	v_mfma_f32_16x16x32_bf16 v[112:115], v[108:111], v[192:195], v[112:115]
	v_mfma_f32_16x16x32_bf16 v[104:107], v[120:123], v[192:195], v[104:107]
	v_mfma_f32_16x16x32_bf16 v[92:95], v[108:111], v[200:203], v[92:95]
	v_mfma_f32_16x16x32_bf16 v[88:91], v[120:123], v[200:203], v[88:91]
	v_mfma_f32_16x16x32_bf16 v[76:79], v[108:111], v[208:211], v[76:79]
	v_mfma_f32_16x16x32_bf16 v[72:75], v[120:123], v[208:211], v[72:75]
	v_mfma_f32_16x16x32_bf16 v[140:143], v[116:119], v[188:191], v[140:143]
	v_mfma_f32_16x16x32_bf16 v[136:139], v[124:127], v[188:191], v[136:139]
	v_mfma_f32_16x16x32_bf16 v[112:115], v[116:119], v[196:199], v[112:115]
	v_mfma_f32_16x16x32_bf16 v[104:107], v[124:127], v[196:199], v[104:107]
	v_mfma_f32_16x16x32_bf16 v[92:95], v[116:119], v[204:207], v[92:95]
	v_mfma_f32_16x16x32_bf16 v[88:91], v[124:127], v[204:207], v[88:91]
	v_mfma_f32_16x16x32_bf16 v[76:79], v[116:119], v[212:215], v[76:79]
	v_mfma_f32_16x16x32_bf16 v[72:75], v[124:127], v[212:215], v[72:75]
	v_mfma_f32_16x16x32_bf16 v[132:135], v[144:147], v[184:187], v[132:135]
	v_mfma_f32_16x16x32_bf16 v[128:131], v[152:155], v[184:187], v[128:131]
	v_mfma_f32_16x16x32_bf16 v[100:103], v[144:147], v[192:195], v[100:103]
	v_mfma_f32_16x16x32_bf16 v[96:99], v[152:155], v[192:195], v[96:99]
	v_mfma_f32_16x16x32_bf16 v[84:87], v[144:147], v[200:203], v[84:87]
	v_mfma_f32_16x16x32_bf16 v[80:83], v[152:155], v[200:203], v[80:83]
	v_mfma_f32_16x16x32_bf16 v[68:71], v[144:147], v[208:211], v[68:71]
	v_mfma_f32_16x16x32_bf16 v[64:67], v[152:155], v[208:211], v[64:67]
	v_mfma_f32_16x16x32_bf16 v[132:135], v[148:151], v[188:191], v[132:135]
	v_mfma_f32_16x16x32_bf16 v[128:131], v[156:159], v[188:191], v[128:131]
	v_mfma_f32_16x16x32_bf16 v[100:103], v[148:151], v[196:199], v[100:103]
	v_mfma_f32_16x16x32_bf16 v[96:99], v[156:159], v[196:199], v[96:99]
	v_mfma_f32_16x16x32_bf16 v[84:87], v[148:151], v[204:207], v[84:87]
	v_mfma_f32_16x16x32_bf16 v[80:83], v[156:159], v[204:207], v[80:83]
	v_mfma_f32_16x16x32_bf16 v[68:71], v[148:151], v[212:215], v[68:71]
	v_mfma_f32_16x16x32_bf16 v[64:67], v[156:159], v[212:215], v[64:67]
	s_setprio 0
	s_barrier
; #define PG8_STAGE(bufoff, gbase, voff) do { _Pragma("unroll") for (int _i = 0; _i < 2; ++_i) \
;         __builtin_amdgcn_global_load_lds((const unsigned*)((const char*)(gbase) + (voff)[_i]), (PG8_LAS unsigned*)(lds + (bufoff) + ldsw + _i * 8192), 16, 0, 0); } while (0)
; #define PG8_LDA(dst, b, h) do { _Pragma("unroll") for (int m = 0; m < 4; ++m) _Pragma("unroll") for (int k = 0; k < 2; ++k) dst[m][k] = *(const PG8_LAS bf16x8*)(lds + PG8_SA(b, h) + aoff + m * 2048 + k * 1024); } while (0)
; #define PG8_MMA(ai, bj, At, Bt) do { __builtin_amdgcn_s_setprio(1); _Pragma("unroll") for (int m = 0; m < 4; ++m) _Pragma("unroll") for (int n = 0; n < 2; ++n) _Pragma("unroll") for (int k = 0; k < 2; ++k) \
;         acc[ai][bj][m][n] = __builtin_amdgcn_mfma_f32_16x16x32_bf16(Bt[n][k], At[m][k], acc[ai][bj][m][n], 0, 0, 0); __builtin_amdgcn_s_setprio(0); } while (0)
; #define PG8_WAIT_V(n) asm volatile("s_waitcnt vmcnt(" #n ")" ::: "memory")
; #define PG8_WAIT_L(n) asm volatile("s_waitcnt lgkmcnt(" #n ")" ::: "memory")
; #define PG8_BAR __builtin_amdgcn_s_barrier()
; #define PG8_SCHED __builtin_amdgcn_sched_barrier(0)
; template <class Epi, class Sched, bool ALIGN_EPI = false, bool SP2 = false>
; __device__ __forceinline__ void gemm_phase(PG8_LAS unsigned char* lds, const Gemm g, const Sched& S, const Epi& E) {
;     ...
;             PG8_LDA(At, 1, 1); PG8_STAGE(PG8_SB(1, 0), b3, voffB); PG8_STAGE(PG8_SB(1, 1), b3 + hstep, voffB); PG8_STAGE(PG8_SA(1, 0), a3, voffA);
;             PG8_WAIT_V(8); PG8_WAIT_L(0); PG8_BAR; PG8_MMA(1, 0, At, B0); PG8_MMA(1, 1, At, B1); PG8_BAR; PG8_SCHED;
;     ...
;         if constexpr (ALIGN_EPI) { if (wr == 0) PG8_BAR; }
	s_add_i32 s46, s68, s48
	v_lshl_add_u64 v[216:217], v[216:217], 0, s[30:31]
	s_mov_b32 m0, s46
	ds_read_b128 v[184:187], v225 offset:49152
	ds_read_b128 v[188:191], v225 offset:50176
	ds_read_b128 v[192:195], v225 offset:51200
	ds_read_b128 v[196:199], v225 offset:52224
	ds_read_b128 v[200:203], v225 offset:53248
	ds_read_b128 v[204:207], v225 offset:54272
	ds_read_b128 v[208:211], v225 offset:55296
	ds_read_b128 v[212:215], v225 offset:56320
	global_load_lds_dwordx4 v[216:217], off
	s_add_i32 m0, s46, 0x2000
	s_add_u32 s44, s44, 0x80080
	v_lshl_add_u64 v[216:217], v[218:219], 0, s[30:31]
	s_addc_u32 s45, s45, 0
	s_add_i32 s46, s69, s48
	global_load_lds_dwordx4 v[216:217], off
	v_lshl_add_u64 v[216:217], s[44:45], 0, v[162:163]
	s_mov_b32 m0, s46
	s_nop 0
	global_load_lds_dwordx4 v[216:217], off
	v_lshl_add_u64 v[216:217], s[44:45], 0, v[160:161]
	s_add_i32 m0, s46, 0x2000
	s_nop 0
	global_load_lds_dwordx4 v[216:217], off
	v_lshl_add_u64 v[216:217], v[228:229], 0, s[30:31]
	s_mov_b32 m0, s54
	s_nop 0
	global_load_lds_dwordx4 v[216:217], off
	v_lshl_add_u64 v[216:217], v[230:231], 0, s[30:31]
	s_mov_b32 m0, s55
	s_nop 0
	global_load_lds_dwordx4 v[216:217], off
	s_waitcnt vmcnt(8)
	s_waitcnt lgkmcnt(0)
	s_barrier
	s_setprio 1
	s_waitcnt lgkmcnt(0)
	v_mfma_f32_16x16x32_bf16 v[60:63], v[108:111], v[184:187], v[60:63]
	v_mfma_f32_16x16x32_bf16 v[56:59], v[120:123], v[184:187], v[56:59]
	v_mfma_f32_16x16x32_bf16 v[44:47], v[108:111], v[192:195], v[44:47]
	v_mfma_f32_16x16x32_bf16 v[40:43], v[120:123], v[192:195], v[40:43]
	v_mfma_f32_16x16x32_bf16 v[28:31], v[108:111], v[200:203], v[28:31]
	v_mfma_f32_16x16x32_bf16 v[24:27], v[120:123], v[200:203], v[24:27]
	v_mfma_f32_16x16x32_bf16 v[12:15], v[108:111], v[208:211], v[12:15]
	v_mfma_f32_16x16x32_bf16 v[8:11], v[120:123], v[208:211], v[8:11]
	v_mfma_f32_16x16x32_bf16 v[60:63], v[116:119], v[188:191], v[60:63]
	v_mfma_f32_16x16x32_bf16 v[56:59], v[124:127], v[188:191], v[56:59]
	v_mfma_f32_16x16x32_bf16 v[44:47], v[116:119], v[196:199], v[44:47]
	v_mfma_f32_16x16x32_bf16 v[40:43], v[124:127], v[196:199], v[40:43]
	v_mfma_f32_16x16x32_bf16 v[28:31], v[116:119], v[204:207], v[28:31]
	v_mfma_f32_16x16x32_bf16 v[24:27], v[124:127], v[204:207], v[24:27]
	v_mfma_f32_16x16x32_bf16 v[12:15], v[116:119], v[212:215], v[12:15]
	v_mfma_f32_16x16x32_bf16 v[8:11], v[124:127], v[212:215], v[8:11]
	v_mfma_f32_16x16x32_bf16 v[52:55], v[144:147], v[184:187], v[52:55]
	v_mfma_f32_16x16x32_bf16 v[48:51], v[152:155], v[184:187], v[48:51]
	v_mfma_f32_16x16x32_bf16 v[36:39], v[144:147], v[192:195], v[36:39]
	v_mfma_f32_16x16x32_bf16 v[32:35], v[152:155], v[192:195], v[32:35]
	v_mfma_f32_16x16x32_bf16 v[20:23], v[144:147], v[200:203], v[20:23]
	v_mfma_f32_16x16x32_bf16 v[16:19], v[152:155], v[200:203], v[16:19]
	v_mfma_f32_16x16x32_bf16 v[4:7], v[144:147], v[208:211], v[4:7]
	v_mfma_f32_16x16x32_bf16 v[0:3], v[152:155], v[208:211], v[0:3]
	v_mfma_f32_16x16x32_bf16 v[52:55], v[148:151], v[188:191], v[52:55]
	v_mfma_f32_16x16x32_bf16 v[48:51], v[156:159], v[188:191], v[48:51]
	v_mfma_f32_16x16x32_bf16 v[36:39], v[148:151], v[196:199], v[36:39]
	v_mfma_f32_16x16x32_bf16 v[32:35], v[156:159], v[196:199], v[32:35]
	v_mfma_f32_16x16x32_bf16 v[20:23], v[148:151], v[204:207], v[20:23]
	v_mfma_f32_16x16x32_bf16 v[16:19], v[156:159], v[204:207], v[16:19]
	v_mfma_f32_16x16x32_bf16 v[4:7], v[148:151], v[212:215], v[4:7]
	v_mfma_f32_16x16x32_bf16 v[0:3], v[156:159], v[212:215], v[0:3]
	s_setprio 0
	s_barrier
	s_add_i32 s67, s67, 2
	s_add_u32 s40, s40, 0x100
	s_addc_u32 s41, s41, 0
	s_add_u32 s42, s42, 0x100
	s_addc_u32 s43, s43, 0
	s_cmp_gt_u32 s67, 29
	s_cbranch_scc0 .LBB0_502
	s_and_b64 vcc, exec, s[34:35]
	s_cbranch_vccz .LBB0_505
	s_barrier

; #define PG8_STAGE(bufoff, gbase, voff) do { _Pragma("unroll") for (int _i = 0; _i < 2; ++_i) \
;         __builtin_amdgcn_global_load_lds((const unsigned*)((const char*)(gbase) + (voff)[_i]), (PG8_LAS unsigned*)(lds + (bufoff) + ldsw + _i * 8192), 16, 0, 0); } while (0)
; #define PG8_LDA(dst, b, h) do { _Pragma("unroll") for (int m = 0; m < 4; ++m) _Pragma("unroll") for (int k = 0; k < 2; ++k) dst[m][k] = *(const PG8_LAS bf16x8*)(lds + PG8_SA(b, h) + aoff + m * 2048 + k * 1024); } while (0)
; #define PG8_LDB(dst, b, h) do { _Pragma("unroll") for (int n = 0; n < 2; ++n) _Pragma("unroll") for (int k = 0; k < 2; ++k) dst[n][k] = *(const PG8_LAS bf16x8*)(lds + PG8_SB(b, h) + boff + n * 2048 + k * 1024); } while (0)
; #define PG8_MMA(ai, bj, At, Bt) do { __builtin_amdgcn_s_setprio(1); _Pragma("unroll") for (int m = 0; m < 4; ++m) _Pragma("unroll") for (int n = 0; n < 2; ++n) _Pragma("unroll") for (int k = 0; k < 2; ++k) \
;         acc[ai][bj][m][n] = __builtin_amdgcn_mfma_f32_16x16x32_bf16(Bt[n][k], At[m][k], acc[ai][bj][m][n], 0, 0, 0); __builtin_amdgcn_s_setprio(0); } while (0)
; #define PG8_WAIT_V(n) asm volatile("s_waitcnt vmcnt(" #n ")" ::: "memory")
; #define PG8_WAIT_L(n) asm volatile("s_waitcnt lgkmcnt(" #n ")" ::: "memory")
; template <class Epi, class Sched, bool ALIGN_EPI = false, bool SP2 = false>
; __device__ __forceinline__ void gemm_phase(PG8_LAS unsigned char* lds, const Gemm g, const Sched& S, const Epi& E) {
;     ...
;             const bool last = (t == nt - 2);
;             const char* a1 = cA + (size_t)(t + 1) * kstep;
;             const char* a2 = last ? nA : cA + (size_t)(t + 2) * kstep; const char* b2 = last ? nB : cB + (size_t)(t + 2) * kstep;
;             const char* a3 = a2 + kstep; const char* b3 = b2 + kstep;
;             if (last && has_next) S.a_ready(nxt);
;             if constexpr (SP2) {
;             PG8_LDB(B0, 0, 0); PG8_LDB(B1, 0, 1); PG8_SCHED; PG8_LDA(At, 0, 0); PG8_STAGE(PG8_SA(1, 1), a1 + hstep, voffA);
;             PG8_WAIT_V(8); PG8_WAIT_L(0); PG8_BAR; PG8_MMA(0, 0, At, B0); PG8_MMA(0, 1, At, B1); PG8_BAR; PG8_SCHED;
;             PG8_LDA(At, 0, 1); PG8_STAGE(PG8_SB(0, 0), b2, voffB); PG8_STAGE(PG8_SB(0, 1), b2 + hstep, voffB); PG8_STAGE(PG8_SA(0, 0), a2, voffA);
;             PG8_WAIT_V(8); PG8_WAIT_L(0); PG8_BAR; PG8_MMA(1, 0, At, B0); PG8_MMA(1, 1, At, B1); PG8_BAR; PG8_SCHED;
.LBB0_554:
	ds_read_b128 v[128:131], v167
	ds_read_b128 v[132:135], v167 offset:1024
	ds_read_b128 v[136:139], v167 offset:2048
	ds_read_b128 v[140:143], v167 offset:3072
	ds_read_b128 v[156:159], v168
	ds_read_b128 v[160:163], v168 offset:1024
	ds_read_b128 v[170:173], v168 offset:2048
	ds_read_b128 v[174:177], v168 offset:3072
	s_add_u32 s34, s30, 0x100
	s_addc_u32 s35, s31, 0
	s_cmp_eq_u32 s62, 28
	s_cselect_b32 s39, s23, s35
	s_cselect_b32 s38, s58, s34
	s_cselect_b32 s37, s21, s61
	s_cselect_b32 s36, s59, s60
	v_lshl_add_u64 v[210:211], s[30:31], 0, v[148:149]
	s_add_i32 m0, s29, 0xc000
	ds_read_b128 v[178:181], v169
	ds_read_b128 v[182:185], v169 offset:1024
	ds_read_b128 v[186:189], v169 offset:2048
	ds_read_b128 v[190:193], v169 offset:3072
	ds_read_b128 v[194:197], v169 offset:4096
	ds_read_b128 v[198:201], v169 offset:5120
	ds_read_b128 v[202:205], v169 offset:6144
	ds_read_b128 v[206:209], v169 offset:7168
	global_load_lds_dwordx4 v[210:211], off
	v_lshl_add_u64 v[210:211], s[30:31], 0, v[150:151]
	s_add_i32 m0, s29, 0xe000
	s_nop 0
	global_load_lds_dwordx4 v[210:211], off
	s_waitcnt vmcnt(8)
	s_waitcnt lgkmcnt(0)
	s_barrier
	s_setprio 1
	s_waitcnt lgkmcnt(0)
	v_mfma_f32_16x16x32_bf16 v[124:127], v[128:131], v[178:181], v[124:127]
	v_mfma_f32_16x16x32_bf16 v[120:123], v[136:139], v[178:181], v[120:123]
	v_mfma_f32_16x16x32_bf16 v[116:119], v[128:131], v[186:189], v[116:119]
	v_mfma_f32_16x16x32_bf16 v[112:115], v[136:139], v[186:189], v[112:115]
	v_mfma_f32_16x16x32_bf16 v[92:95], v[128:131], v[194:197], v[92:95]
	v_mfma_f32_16x16x32_bf16 v[88:91], v[136:139], v[194:197], v[88:91]
	v_mfma_f32_16x16x32_bf16 v[84:87], v[128:131], v[202:205], v[84:87]
	v_mfma_f32_16x16x32_bf16 v[80:83], v[136:139], v[202:205], v[80:83]
	v_mfma_f32_16x16x32_bf16 v[124:127], v[132:135], v[182:185], v[124:127]
	v_mfma_f32_16x16x32_bf16 v[120:123], v[140:143], v[182:185], v[120:123]
	v_mfma_f32_16x16x32_bf16 v[116:119], v[132:135], v[190:193], v[116:119]
	v_mfma_f32_16x16x32_bf16 v[112:115], v[140:143], v[190:193], v[112:115]
	v_mfma_f32_16x16x32_bf16 v[92:95], v[132:135], v[198:201], v[92:95]
	v_mfma_f32_16x16x32_bf16 v[88:91], v[140:143], v[198:201], v[88:91]
	v_mfma_f32_16x16x32_bf16 v[84:87], v[132:135], v[206:209], v[84:87]
	v_mfma_f32_16x16x32_bf16 v[80:83], v[140:143], v[206:209], v[80:83]
	v_mfma_f32_16x16x32_bf16 v[108:111], v[156:159], v[178:181], v[108:111]
	v_mfma_f32_16x16x32_bf16 v[104:107], v[170:173], v[178:181], v[104:107]
	v_mfma_f32_16x16x32_bf16 v[100:103], v[156:159], v[186:189], v[100:103]
	v_mfma_f32_16x16x32_bf16 v[96:99], v[170:173], v[186:189], v[96:99]
	v_mfma_f32_16x16x32_bf16 v[76:79], v[156:159], v[194:197], v[76:79]
	v_mfma_f32_16x16x32_bf16 v[72:75], v[170:173], v[194:197], v[72:75]
	v_mfma_f32_16x16x32_bf16 v[68:71], v[156:159], v[202:205], v[68:71]
	v_mfma_f32_16x16x32_bf16 v[64:67], v[170:173], v[202:205], v[64:67]
	v_mfma_f32_16x16x32_bf16 v[108:111], v[160:163], v[182:185], v[108:111]
	v_mfma_f32_16x16x32_bf16 v[104:107], v[174:177], v[182:185], v[104:107]
	v_mfma_f32_16x16x32_bf16 v[100:103], v[160:163], v[190:193], v[100:103]
	v_mfma_f32_16x16x32_bf16 v[96:99], v[174:177], v[190:193], v[96:99]
	v_mfma_f32_16x16x32_bf16 v[76:79], v[160:163], v[198:201], v[76:79]
	v_mfma_f32_16x16x32_bf16 v[72:75], v[174:177], v[198:201], v[72:75]
	v_mfma_f32_16x16x32_bf16 v[68:71], v[160:163], v[206:209], v[68:71]
	v_mfma_f32_16x16x32_bf16 v[64:67], v[174:177], v[206:209], v[64:67]
	s_setprio 0
	s_barrier
	s_add_i32 s30, s53, s44
	v_lshl_add_u64 v[210:211], s[36:37], 0, v[144:145]
	s_mov_b32 m0, s30
	ds_read_b128 v[178:181], v169 offset:16384
	ds_read_b128 v[182:185], v169 offset:17408
	ds_read_b128 v[186:189], v169 offset:18432
	ds_read_b128 v[190:193], v169 offset:19456
	ds_read_b128 v[194:197], v169 offset:20480
	ds_read_b128 v[198:201], v169 offset:21504
	ds_read_b128 v[202:205], v169 offset:22528
	ds_read_b128 v[206:209], v169 offset:23552
	global_load_lds_dwordx4 v[210:211], off
	s_add_i32 m0, s30, 0x2000
	s_add_u32 s30, s36, 0x80000
	v_lshl_add_u64 v[212:213], s[36:37], 0, v[146:147]
	s_addc_u32 s31, s37, 0
	s_add_i32 s63, s54, s44
	global_load_lds_dwordx4 v[212:213], off
	v_lshl_add_u64 v[214:215], s[30:31], 0, v[144:145]
	s_mov_b32 m0, s63
	v_lshl_add_u64 v[216:217], s[38:39], 0, v[146:147]
	global_load_lds_dwordx4 v[214:215], off
	v_lshl_add_u64 v[214:215], s[30:31], 0, v[146:147]
	s_add_i32 m0, s63, 0x2000
	s_nop 0
	global_load_lds_dwordx4 v[214:215], off
	v_lshl_add_u64 v[214:215], s[38:39], 0, v[144:145]
	s_mov_b32 m0, s29
	s_nop 0
	global_load_lds_dwordx4 v[214:215], off
	s_mov_b32 m0, s45
	s_nop 0
	global_load_lds_dwordx4 v[216:217], off
	s_waitcnt vmcnt(8)
	s_waitcnt lgkmcnt(0)
	s_barrier
; #define PG8_STAGE(bufoff, gbase, voff) do { _Pragma("unroll") for (int _i = 0; _i < 2; ++_i) \
;         __builtin_amdgcn_global_load_lds((const unsigned*)((const char*)(gbase) + (voff)[_i]), (PG8_LAS unsigned*)(lds + (bufoff) + ldsw + _i * 8192), 16, 0, 0); } while (0)
; #define PG8_LDA(dst, b, h) do { _Pragma("unroll") for (int m = 0; m < 4; ++m) _Pragma("unroll") for (int k = 0; k < 2; ++k) dst[m][k] = *(const PG8_LAS bf16x8*)(lds + PG8_SA(b, h) + aoff + m * 2048 + k * 1024); } while (0)
; #define PG8_LDB(dst, b, h) do { _Pragma("unroll") for (int n = 0; n < 2; ++n) _Pragma("unroll") for (int k = 0; k < 2; ++k) dst[n][k] = *(const PG8_LAS bf16x8*)(lds + PG8_SB(b, h) + boff + n * 2048 + k * 1024); } while (0)
; #define PG8_MMA(ai, bj, At, Bt) do { __builtin_amdgcn_s_setprio(1); _Pragma("unroll") for (int m = 0; m < 4; ++m) _Pragma("unroll") for (int n = 0; n < 2; ++n) _Pragma("unroll") for (int k = 0; k < 2; ++k) \
;         acc[ai][bj][m][n] = __builtin_amdgcn_mfma_f32_16x16x32_bf16(Bt[n][k], At[m][k], acc[ai][bj][m][n], 0, 0, 0); __builtin_amdgcn_s_setprio(0); } while (0)
; #define PG8_WAIT_V(n) asm volatile("s_waitcnt vmcnt(" #n ")" ::: "memory")
; #define PG8_WAIT_L(n) asm volatile("s_waitcnt lgkmcnt(" #n ")" ::: "memory")
; #define PG8_BAR __builtin_amdgcn_s_barrier()
; #define PG8_SCHED __builtin_amdgcn_sched_barrier(0)
; template <class Epi, class Sched, bool ALIGN_EPI = false, bool SP2 = false>
; __device__ __forceinline__ void gemm_phase(PG8_LAS unsigned char* lds, const Gemm g, const Sched& S, const Epi& E) {
;     ...
;             PG8_WAIT_V(8); PG8_WAIT_L(0); PG8_BAR; PG8_MMA(1, 0, At, B0); PG8_MMA(1, 1, At, B1); PG8_BAR; PG8_SCHED;
;             PG8_LDB(B0, 1, 0); PG8_LDB(B1, 1, 1); PG8_SCHED; PG8_LDA(At, 1, 0); PG8_STAGE(PG8_SA(0, 1), a2 + hstep, voffA);
;             PG8_WAIT_V(8); PG8_WAIT_L(0); PG8_BAR; PG8_MMA(0, 0, At, B0); PG8_MMA(0, 1, At, B1); PG8_BAR; PG8_SCHED;
	s_setprio 1
	s_waitcnt lgkmcnt(0)
	v_mfma_f32_16x16x32_bf16 v[60:63], v[128:131], v[178:181], v[60:63]
	v_mfma_f32_16x16x32_bf16 v[56:59], v[136:139], v[178:181], v[56:59]
	v_mfma_f32_16x16x32_bf16 v[52:55], v[128:131], v[186:189], v[52:55]
	v_mfma_f32_16x16x32_bf16 v[48:51], v[136:139], v[186:189], v[48:51]
	v_mfma_f32_16x16x32_bf16 v[28:31], v[128:131], v[194:197], v[28:31]
	v_mfma_f32_16x16x32_bf16 v[24:27], v[136:139], v[194:197], v[24:27]
	v_mfma_f32_16x16x32_bf16 v[20:23], v[128:131], v[202:205], v[20:23]
	v_mfma_f32_16x16x32_bf16 v[16:19], v[136:139], v[202:205], v[16:19]
	v_mfma_f32_16x16x32_bf16 v[60:63], v[132:135], v[182:185], v[60:63]
	v_mfma_f32_16x16x32_bf16 v[56:59], v[140:143], v[182:185], v[56:59]
	v_mfma_f32_16x16x32_bf16 v[52:55], v[132:135], v[190:193], v[52:55]
	v_mfma_f32_16x16x32_bf16 v[48:51], v[140:143], v[190:193], v[48:51]
	v_mfma_f32_16x16x32_bf16 v[28:31], v[132:135], v[198:201], v[28:31]
	v_mfma_f32_16x16x32_bf16 v[24:27], v[140:143], v[198:201], v[24:27]
	v_mfma_f32_16x16x32_bf16 v[20:23], v[132:135], v[206:209], v[20:23]
	v_mfma_f32_16x16x32_bf16 v[16:19], v[140:143], v[206:209], v[16:19]
	v_mfma_f32_16x16x32_bf16 v[44:47], v[156:159], v[178:181], v[44:47]
	v_mfma_f32_16x16x32_bf16 v[40:43], v[170:173], v[178:181], v[40:43]
	v_mfma_f32_16x16x32_bf16 v[36:39], v[156:159], v[186:189], v[36:39]
	v_mfma_f32_16x16x32_bf16 v[32:35], v[170:173], v[186:189], v[32:35]
	v_mfma_f32_16x16x32_bf16 v[12:15], v[156:159], v[194:197], v[12:15]
	v_mfma_f32_16x16x32_bf16 v[8:11], v[170:173], v[194:197], v[8:11]
	v_mfma_f32_16x16x32_bf16 v[4:7], v[156:159], v[202:205], v[4:7]
	v_mfma_f32_16x16x32_bf16 v[0:3], v[170:173], v[202:205], v[0:3]
	v_mfma_f32_16x16x32_bf16 v[44:47], v[160:163], v[182:185], v[44:47]
	v_mfma_f32_16x16x32_bf16 v[40:43], v[174:177], v[182:185], v[40:43]
	v_mfma_f32_16x16x32_bf16 v[36:39], v[160:163], v[190:193], v[36:39]
	v_mfma_f32_16x16x32_bf16 v[32:35], v[174:177], v[190:193], v[32:35]
	v_mfma_f32_16x16x32_bf16 v[12:15], v[160:163], v[198:201], v[12:15]
	v_mfma_f32_16x16x32_bf16 v[8:11], v[174:177], v[198:201], v[8:11]
	v_mfma_f32_16x16x32_bf16 v[4:7], v[160:163], v[206:209], v[4:7]
	v_mfma_f32_16x16x32_bf16 v[0:3], v[174:177], v[206:209], v[0:3]
	s_setprio 0
	s_barrier
	s_add_i32 s63, 0, 0x18000
	s_add_i32 s64, 0, 0x1c000
	v_add_u32_e32 v140, s63, v165
	v_add_u32_e32 v174, s64, v165
	ds_read_b128 v[128:131], v140
	ds_read_b128 v[132:135], v140 offset:1024
	ds_read_b128 v[136:139], v140 offset:2048
	ds_read_b128 v[140:143], v140 offset:3072
	ds_read_b128 v[156:159], v174
	ds_read_b128 v[160:163], v174 offset:1024
	ds_read_b128 v[170:173], v174 offset:2048
	ds_read_b128 v[174:177], v174 offset:3072
	s_add_u32 s30, s38, 0x80000
	s_addc_u32 s31, s39, 0
	s_mov_b32 m0, s46
	v_lshl_add_u64 v[218:219], s[30:31], 0, v[144:145]
	ds_read_b128 v[178:181], v169 offset:32768
	ds_read_b128 v[182:185], v169 offset:33792
	ds_read_b128 v[186:189], v169 offset:34816
	ds_read_b128 v[190:193], v169 offset:35840
	ds_read_b128 v[194:197], v169 offset:36864
	ds_read_b128 v[198:201], v169 offset:37888
	ds_read_b128 v[202:205], v169 offset:38912
	ds_read_b128 v[206:209], v169 offset:39936
	global_load_lds_dwordx4 v[218:219], off
	v_lshl_add_u64 v[218:219], s[30:31], 0, v[146:147]
	s_mov_b32 m0, s47
	s_nop 0
	global_load_lds_dwordx4 v[218:219], off
	s_waitcnt vmcnt(8)
	s_waitcnt lgkmcnt(0)
	s_barrier
	s_setprio 1
	s_waitcnt lgkmcnt(0)
	v_mfma_f32_16x16x32_bf16 v[124:127], v[128:131], v[178:181], v[124:127]
	v_mfma_f32_16x16x32_bf16 v[120:123], v[136:139], v[178:181], v[120:123]
	v_mfma_f32_16x16x32_bf16 v[116:119], v[128:131], v[186:189], v[116:119]
	v_mfma_f32_16x16x32_bf16 v[112:115], v[136:139], v[186:189], v[112:115]
	v_mfma_f32_16x16x32_bf16 v[92:95], v[128:131], v[194:197], v[92:95]
	v_mfma_f32_16x16x32_bf16 v[88:91], v[136:139], v[194:197], v[88:91]
	v_mfma_f32_16x16x32_bf16 v[84:87], v[128:131], v[202:205], v[84:87]
	v_mfma_f32_16x16x32_bf16 v[80:83], v[136:139], v[202:205], v[80:83]
	v_mfma_f32_16x16x32_bf16 v[124:127], v[132:135], v[182:185], v[124:127]
	v_mfma_f32_16x16x32_bf16 v[120:123], v[140:143], v[182:185], v[120:123]
	v_mfma_f32_16x16x32_bf16 v[116:119], v[132:135], v[190:193], v[116:119]
	v_mfma_f32_16x16x32_bf16 v[112:115], v[140:143], v[190:193], v[112:115]
	v_mfma_f32_16x16x32_bf16 v[92:95], v[132:135], v[198:201], v[92:95]
	v_mfma_f32_16x16x32_bf16 v[88:91], v[140:143], v[198:201], v[88:91]
	v_mfma_f32_16x16x32_bf16 v[84:87], v[132:135], v[206:209], v[84:87]
	v_mfma_f32_16x16x32_bf16 v[80:83], v[140:143], v[206:209], v[80:83]
	v_mfma_f32_16x16x32_bf16 v[108:111], v[156:159], v[178:181], v[108:111]
	v_mfma_f32_16x16x32_bf16 v[104:107], v[170:173], v[178:181], v[104:107]
	v_mfma_f32_16x16x32_bf16 v[100:103], v[156:159], v[186:189], v[100:103]
	v_mfma_f32_16x16x32_bf16 v[96:99], v[170:173], v[186:189], v[96:99]
	v_mfma_f32_16x16x32_bf16 v[76:79], v[156:159], v[194:197], v[76:79]
	v_mfma_f32_16x16x32_bf16 v[72:75], v[170:173], v[194:197], v[72:75]
	v_mfma_f32_16x16x32_bf16 v[68:71], v[156:159], v[202:205], v[68:71]
	v_mfma_f32_16x16x32_bf16 v[64:67], v[170:173], v[202:205], v[64:67]
	v_mfma_f32_16x16x32_bf16 v[108:111], v[160:163], v[182:185], v[108:111]
	v_mfma_f32_16x16x32_bf16 v[104:107], v[174:177], v[182:185], v[104:107]
	v_mfma_f32_16x16x32_bf16 v[100:103], v[160:163], v[190:193], v[100:103]
	v_mfma_f32_16x16x32_bf16 v[96:99], v[174:177], v[190:193], v[96:99]
	v_mfma_f32_16x16x32_bf16 v[76:79], v[160:163], v[198:201], v[76:79]
	v_mfma_f32_16x16x32_bf16 v[72:75], v[174:177], v[198:201], v[72:75]
	v_mfma_f32_16x16x32_bf16 v[68:71], v[160:163], v[206:209], v[68:71]
	v_mfma_f32_16x16x32_bf16 v[64:67], v[174:177], v[206:209], v[64:67]
	s_setprio 0
	s_barrier
; #define PG8_STAGE(bufoff, gbase, voff) do { _Pragma("unroll") for (int _i = 0; _i < 2; ++_i) \
;         __builtin_amdgcn_global_load_lds((const unsigned*)((const char*)(gbase) + (voff)[_i]), (PG8_LAS unsigned*)(lds + (bufoff) + ldsw + _i * 8192), 16, 0, 0); } while (0)
; #define PG8_LDA(dst, b, h) do { _Pragma("unroll") for (int m = 0; m < 4; ++m) _Pragma("unroll") for (int k = 0; k < 2; ++k) dst[m][k] = *(const PG8_LAS bf16x8*)(lds + PG8_SA(b, h) + aoff + m * 2048 + k * 1024); } while (0)
; #define PG8_MMA(ai, bj, At, Bt) do { __builtin_amdgcn_s_setprio(1); _Pragma("unroll") for (int m = 0; m < 4; ++m) _Pragma("unroll") for (int n = 0; n < 2; ++n) _Pragma("unroll") for (int k = 0; k < 2; ++k) \
;         acc[ai][bj][m][n] = __builtin_amdgcn_mfma_f32_16x16x32_bf16(Bt[n][k], At[m][k], acc[ai][bj][m][n], 0, 0, 0); __builtin_amdgcn_s_setprio(0); } while (0)
; #define PG8_WAIT_V(n) asm volatile("s_waitcnt vmcnt(" #n ")" ::: "memory")
; #define PG8_WAIT_L(n) asm volatile("s_waitcnt lgkmcnt(" #n ")" ::: "memory")
; #define PG8_BAR __builtin_amdgcn_s_barrier()
; #define PG8_SCHED __builtin_amdgcn_sched_barrier(0)
; template <class Epi, class Sched, bool ALIGN_EPI = false, bool SP2 = false>
; __device__ __forceinline__ void gemm_phase(PG8_LAS unsigned char* lds, const Gemm g, const Sched& S, const Epi& E) {
;     ...
;             PG8_LDA(At, 1, 1); PG8_STAGE(PG8_SB(1, 0), b3, voffB); PG8_STAGE(PG8_SB(1, 1), b3 + hstep, voffB); PG8_STAGE(PG8_SA(1, 0), a3, voffA);
;             PG8_WAIT_V(8); PG8_WAIT_L(0); PG8_BAR; PG8_MMA(1, 0, At, B0); PG8_MMA(1, 1, At, B1); PG8_BAR; PG8_SCHED;
;     ...
;         if constexpr (ALIGN_EPI) { if (wr == 0) PG8_BAR; }
	s_add_i32 s30, s63, s44
	v_lshl_add_u64 v[210:211], v[210:211], 0, s[10:11]
	s_mov_b32 m0, s30
	ds_read_b128 v[178:181], v169 offset:49152
	ds_read_b128 v[182:185], v169 offset:50176
	ds_read_b128 v[186:189], v169 offset:51200
	ds_read_b128 v[190:193], v169 offset:52224
	ds_read_b128 v[194:197], v169 offset:53248
	ds_read_b128 v[198:201], v169 offset:54272
	ds_read_b128 v[202:205], v169 offset:55296
	ds_read_b128 v[206:209], v169 offset:56320
	global_load_lds_dwordx4 v[210:211], off
	s_add_i32 m0, s30, 0x2000
	s_add_u32 s30, s36, 0x80080
	v_lshl_add_u64 v[210:211], v[212:213], 0, s[10:11]
	s_addc_u32 s31, s37, 0
	s_add_i32 s36, s64, s44
	global_load_lds_dwordx4 v[210:211], off
	v_lshl_add_u64 v[210:211], s[30:31], 0, v[144:145]
	s_mov_b32 m0, s36
	s_nop 0
	global_load_lds_dwordx4 v[210:211], off
	v_lshl_add_u64 v[210:211], s[30:31], 0, v[146:147]
	s_add_i32 m0, s36, 0x2000
	s_nop 0
	global_load_lds_dwordx4 v[210:211], off
	v_lshl_add_u64 v[210:211], v[214:215], 0, s[10:11]
	s_mov_b32 m0, s51
	s_nop 0
	global_load_lds_dwordx4 v[210:211], off
	v_lshl_add_u64 v[210:211], v[216:217], 0, s[10:11]
	s_mov_b32 m0, s52
	s_nop 0
	global_load_lds_dwordx4 v[210:211], off
	s_waitcnt vmcnt(8)
	s_waitcnt lgkmcnt(0)
	s_barrier
	s_setprio 1
	s_waitcnt lgkmcnt(0)
	v_mfma_f32_16x16x32_bf16 v[60:63], v[128:131], v[178:181], v[60:63]
	v_mfma_f32_16x16x32_bf16 v[56:59], v[136:139], v[178:181], v[56:59]
	v_mfma_f32_16x16x32_bf16 v[52:55], v[128:131], v[186:189], v[52:55]
	v_mfma_f32_16x16x32_bf16 v[48:51], v[136:139], v[186:189], v[48:51]
	v_mfma_f32_16x16x32_bf16 v[28:31], v[128:131], v[194:197], v[28:31]
	v_mfma_f32_16x16x32_bf16 v[24:27], v[136:139], v[194:197], v[24:27]
	v_mfma_f32_16x16x32_bf16 v[20:23], v[128:131], v[202:205], v[20:23]
	v_mfma_f32_16x16x32_bf16 v[16:19], v[136:139], v[202:205], v[16:19]
	v_mfma_f32_16x16x32_bf16 v[60:63], v[132:135], v[182:185], v[60:63]
	v_mfma_f32_16x16x32_bf16 v[56:59], v[140:143], v[182:185], v[56:59]
	v_mfma_f32_16x16x32_bf16 v[52:55], v[132:135], v[190:193], v[52:55]
	v_mfma_f32_16x16x32_bf16 v[48:51], v[140:143], v[190:193], v[48:51]
	v_mfma_f32_16x16x32_bf16 v[28:31], v[132:135], v[198:201], v[28:31]
	v_mfma_f32_16x16x32_bf16 v[24:27], v[140:143], v[198:201], v[24:27]
	v_mfma_f32_16x16x32_bf16 v[20:23], v[132:135], v[206:209], v[20:23]
	v_mfma_f32_16x16x32_bf16 v[16:19], v[140:143], v[206:209], v[16:19]
	v_mfma_f32_16x16x32_bf16 v[44:47], v[156:159], v[178:181], v[44:47]
	v_mfma_f32_16x16x32_bf16 v[40:43], v[170:173], v[178:181], v[40:43]
	v_mfma_f32_16x16x32_bf16 v[36:39], v[156:159], v[186:189], v[36:39]
	v_mfma_f32_16x16x32_bf16 v[32:35], v[170:173], v[186:189], v[32:35]
	v_mfma_f32_16x16x32_bf16 v[12:15], v[156:159], v[194:197], v[12:15]
	v_mfma_f32_16x16x32_bf16 v[8:11], v[170:173], v[194:197], v[8:11]
	v_mfma_f32_16x16x32_bf16 v[4:7], v[156:159], v[202:205], v[4:7]
	v_mfma_f32_16x16x32_bf16 v[0:3], v[170:173], v[202:205], v[0:3]
	v_mfma_f32_16x16x32_bf16 v[44:47], v[160:163], v[182:185], v[44:47]
	v_mfma_f32_16x16x32_bf16 v[40:43], v[174:177], v[182:185], v[40:43]
	v_mfma_f32_16x16x32_bf16 v[36:39], v[160:163], v[190:193], v[36:39]
	v_mfma_f32_16x16x32_bf16 v[32:35], v[174:177], v[190:193], v[32:35]
	v_mfma_f32_16x16x32_bf16 v[12:15], v[160:163], v[198:201], v[12:15]
	v_mfma_f32_16x16x32_bf16 v[8:11], v[174:177], v[198:201], v[8:11]
	v_mfma_f32_16x16x32_bf16 v[4:7], v[160:163], v[206:209], v[4:7]
	v_mfma_f32_16x16x32_bf16 v[0:3], v[174:177], v[206:209], v[0:3]
	s_setprio 0
	s_barrier
	s_add_i32 s62, s62, 2
	s_add_u32 s60, s60, 0x100
	s_addc_u32 s61, s61, 0
	s_cmp_gt_u32 s62, 29
	s_mov_b64 s[30:31], s[34:35]
	s_cbranch_scc0 .LBB0_554
	s_and_b64 vcc, exec, s[14:15]
	s_cbranch_vccz .LBB0_557
	s_barrier

; #define PG8_STAGE(bufoff, gbase, voff) do { _Pragma("unroll") for (int _i = 0; _i < 2; ++_i) \
;         __builtin_amdgcn_global_load_lds((const unsigned*)((const char*)(gbase) + (voff)[_i]), (PG8_LAS unsigned*)(lds + (bufoff) + ldsw + _i * 8192), 16, 0, 0); } while (0)
; #define PG8_LDA(dst, b, h) do { _Pragma("unroll") for (int m = 0; m < 4; ++m) _Pragma("unroll") for (int k = 0; k < 2; ++k) dst[m][k] = *(const PG8_LAS bf16x8*)(lds + PG8_SA(b, h) + aoff + m * 2048 + k * 1024); } while (0)
; #define PG8_LDB(dst, b, h) do { _Pragma("unroll") for (int n = 0; n < 2; ++n) _Pragma("unroll") for (int k = 0; k < 2; ++k) dst[n][k] = *(const PG8_LAS bf16x8*)(lds + PG8_SB(b, h) + boff + n * 2048 + k * 1024); } while (0)
; #define PG8_MMA(ai, bj, At, Bt) do { __builtin_amdgcn_s_setprio(1); _Pragma("unroll") for (int m = 0; m < 4; ++m) _Pragma("unroll") for (int n = 0; n < 2; ++n) _Pragma("unroll") for (int k = 0; k < 2; ++k) \
;         acc[ai][bj][m][n] = __builtin_amdgcn_mfma_f32_16x16x32_bf16(Bt[n][k], At[m][k], acc[ai][bj][m][n], 0, 0, 0); __builtin_amdgcn_s_setprio(0); } while (0)
; #define PG8_WAIT_V(n) asm volatile("s_waitcnt vmcnt(" #n ")" ::: "memory")
; #define PG8_WAIT_L(n) asm volatile("s_waitcnt lgkmcnt(" #n ")" ::: "memory")
; template <class Epi, class Sched, bool ALIGN_EPI = false, bool SP2 = false>
; __device__ __forceinline__ void gemm_phase(PG8_LAS unsigned char* lds, const Gemm g, const Sched& S, const Epi& E) {
;     ...
;             const bool last = (t == nt - 2);
;             const char* a1 = cA + (size_t)(t + 1) * kstep;
;             const char* a2 = last ? nA : cA + (size_t)(t + 2) * kstep; const char* b2 = last ? nB : cB + (size_t)(t + 2) * kstep;
;             const char* a3 = a2 + kstep; const char* b3 = b2 + kstep;
;             if (last && has_next) S.a_ready(nxt);
;             if constexpr (SP2) {
;             PG8_LDB(B0, 0, 0); PG8_LDB(B1, 0, 1); PG8_SCHED; PG8_LDA(At, 0, 0); PG8_STAGE(PG8_SA(1, 1), a1 + hstep, voffA);
;             PG8_WAIT_V(8); PG8_WAIT_L(0); PG8_BAR; PG8_MMA(0, 0, At, B0); PG8_MMA(0, 1, At, B1); PG8_BAR; PG8_SCHED;
;             PG8_LDA(At, 0, 1); PG8_STAGE(PG8_SB(0, 0), b2, voffB); PG8_STAGE(PG8_SB(0, 1), b2 + hstep, voffB); PG8_STAGE(PG8_SA(0, 0), a2, voffA);
;             PG8_WAIT_V(8); PG8_WAIT_L(0); PG8_BAR; PG8_MMA(1, 0, At, B0); PG8_MMA(1, 1, At, B1); PG8_BAR; PG8_SCHED;
.LBB0_679:
	ds_read_b128 v[120:123], v200
	ds_read_b128 v[124:127], v200 offset:1024
	ds_read_b128 v[128:131], v200 offset:2048
	ds_read_b128 v[132:135], v200 offset:3072
	ds_read_b128 v[136:139], v201
	ds_read_b128 v[140:143], v201 offset:1024
	ds_read_b128 v[144:147], v201 offset:2048
	ds_read_b128 v[148:151], v201 offset:3072
	s_add_u32 s58, s54, 0xfff80080
	s_addc_u32 s59, s55, -1
	s_cmp_eq_u32 s91, 28
	s_cselect_b32 s61, s49, s59
	s_cselect_b32 s60, s85, s58
	s_cselect_b32 s59, s47, s90
	s_cselect_b32 s58, s88, s89
	v_lshl_add_u64 v[192:193], s[54:55], 0, v[174:175]
	s_add_i32 m0, s67, 0xc000
	ds_read_b128 v[160:163], v202
	ds_read_b128 v[164:167], v202 offset:1024
	ds_read_b128 v[180:183], v202 offset:2048
	ds_read_b128 v[184:187], v202 offset:3072
	ds_read_b128 v[188:191], v202 offset:4096
	ds_read_b128 v[206:209], v202 offset:5120
	ds_read_b128 v[210:213], v202 offset:6144
	ds_read_b128 v[214:217], v202 offset:7168
	global_load_lds_dwordx4 v[192:193], off
	v_lshl_add_u64 v[192:193], s[54:55], 0, v[172:173]
	s_add_i32 m0, s67, 0xe000
	s_nop 0
	global_load_lds_dwordx4 v[192:193], off
	s_waitcnt vmcnt(8)
	s_waitcnt lgkmcnt(0)
	s_barrier
	s_setprio 1
	s_waitcnt lgkmcnt(0)
	v_mfma_f32_16x16x32_bf16 v[156:159], v[120:123], v[160:163], v[156:159]
	v_mfma_f32_16x16x32_bf16 v[60:63], v[128:131], v[160:163], v[60:63]
	v_mfma_f32_16x16x32_bf16 v[116:119], v[120:123], v[180:183], v[116:119]
	v_mfma_f32_16x16x32_bf16 v[52:55], v[128:131], v[180:183], v[52:55]
	v_mfma_f32_16x16x32_bf16 v[108:111], v[120:123], v[188:191], v[108:111]
	v_mfma_f32_16x16x32_bf16 v[44:47], v[128:131], v[188:191], v[44:47]
	v_mfma_f32_16x16x32_bf16 v[104:107], v[120:123], v[210:213], v[104:107]
	v_mfma_f32_16x16x32_bf16 v[40:43], v[128:131], v[210:213], v[40:43]
	v_mfma_f32_16x16x32_bf16 v[156:159], v[124:127], v[164:167], v[156:159]
	v_mfma_f32_16x16x32_bf16 v[60:63], v[132:135], v[164:167], v[60:63]
	v_mfma_f32_16x16x32_bf16 v[116:119], v[124:127], v[184:187], v[116:119]
	v_mfma_f32_16x16x32_bf16 v[52:55], v[132:135], v[184:187], v[52:55]
	v_mfma_f32_16x16x32_bf16 v[108:111], v[124:127], v[206:209], v[108:111]
	v_mfma_f32_16x16x32_bf16 v[44:47], v[132:135], v[206:209], v[44:47]
	v_mfma_f32_16x16x32_bf16 v[104:107], v[124:127], v[214:217], v[104:107]
	v_mfma_f32_16x16x32_bf16 v[40:43], v[132:135], v[214:217], v[40:43]
	v_mfma_f32_16x16x32_bf16 v[152:155], v[136:139], v[160:163], v[152:155]
	v_mfma_f32_16x16x32_bf16 v[56:59], v[144:147], v[160:163], v[56:59]
	v_mfma_f32_16x16x32_bf16 v[112:115], v[136:139], v[180:183], v[112:115]
	v_mfma_f32_16x16x32_bf16 v[48:51], v[144:147], v[180:183], v[48:51]
	v_mfma_f32_16x16x32_bf16 v[100:103], v[136:139], v[188:191], v[100:103]
	v_mfma_f32_16x16x32_bf16 v[36:39], v[144:147], v[188:191], v[36:39]
	v_mfma_f32_16x16x32_bf16 v[96:99], v[136:139], v[210:213], v[96:99]
	v_mfma_f32_16x16x32_bf16 v[32:35], v[144:147], v[210:213], v[32:35]
	v_mfma_f32_16x16x32_bf16 v[152:155], v[140:143], v[164:167], v[152:155]
	v_mfma_f32_16x16x32_bf16 v[56:59], v[148:151], v[164:167], v[56:59]
	v_mfma_f32_16x16x32_bf16 v[112:115], v[140:143], v[184:187], v[112:115]
	v_mfma_f32_16x16x32_bf16 v[48:51], v[148:151], v[184:187], v[48:51]
	v_mfma_f32_16x16x32_bf16 v[100:103], v[140:143], v[206:209], v[100:103]
	v_mfma_f32_16x16x32_bf16 v[36:39], v[148:151], v[206:209], v[36:39]
	v_mfma_f32_16x16x32_bf16 v[96:99], v[140:143], v[214:217], v[96:99]
	v_mfma_f32_16x16x32_bf16 v[32:35], v[148:151], v[214:217], v[32:35]
	s_setprio 0
	s_barrier
	s_add_i32 s92, s78, s66
	v_lshl_add_u64 v[192:193], s[58:59], 0, v[170:171]
	s_mov_b32 m0, s92
	ds_read_b128 v[160:163], v202 offset:16384
	ds_read_b128 v[164:167], v202 offset:17408
	ds_read_b128 v[180:183], v202 offset:18432
	ds_read_b128 v[184:187], v202 offset:19456
	ds_read_b128 v[188:191], v202 offset:20480
	ds_read_b128 v[206:209], v202 offset:21504
	ds_read_b128 v[210:213], v202 offset:22528
	ds_read_b128 v[214:217], v202 offset:23552
	global_load_lds_dwordx4 v[192:193], off
	s_add_i32 m0, s92, 0x2000
	s_add_u32 s92, s58, 0x80000
	v_lshl_add_u64 v[218:219], s[58:59], 0, v[168:169]
	s_addc_u32 s93, s59, 0
	s_add_i32 s95, s79, s66
	global_load_lds_dwordx4 v[218:219], off
	v_lshl_add_u64 v[222:223], s[92:93], 0, v[170:171]
	s_mov_b32 m0, s95
	v_lshl_add_u64 v[224:225], s[60:61], 0, v[168:169]
	global_load_lds_dwordx4 v[222:223], off
	v_lshl_add_u64 v[222:223], s[92:93], 0, v[168:169]
	s_add_i32 m0, s95, 0x2000
	s_nop 0
	global_load_lds_dwordx4 v[222:223], off
	v_lshl_add_u64 v[222:223], s[60:61], 0, v[170:171]
	s_mov_b32 m0, s67
	s_nop 0
	global_load_lds_dwordx4 v[222:223], off
	s_mov_b32 m0, s68
	s_nop 0
	global_load_lds_dwordx4 v[224:225], off
	s_waitcnt vmcnt(8)
	s_waitcnt lgkmcnt(0)
	s_barrier
; #define PG8_STAGE(bufoff, gbase, voff) do { _Pragma("unroll") for (int _i = 0; _i < 2; ++_i) \
;         __builtin_amdgcn_global_load_lds((const unsigned*)((const char*)(gbase) + (voff)[_i]), (PG8_LAS unsigned*)(lds + (bufoff) + ldsw + _i * 8192), 16, 0, 0); } while (0)
; #define PG8_LDA(dst, b, h) do { _Pragma("unroll") for (int m = 0; m < 4; ++m) _Pragma("unroll") for (int k = 0; k < 2; ++k) dst[m][k] = *(const PG8_LAS bf16x8*)(lds + PG8_SA(b, h) + aoff + m * 2048 + k * 1024); } while (0)
; #define PG8_LDB(dst, b, h) do { _Pragma("unroll") for (int n = 0; n < 2; ++n) _Pragma("unroll") for (int k = 0; k < 2; ++k) dst[n][k] = *(const PG8_LAS bf16x8*)(lds + PG8_SB(b, h) + boff + n * 2048 + k * 1024); } while (0)
; #define PG8_MMA(ai, bj, At, Bt) do { __builtin_amdgcn_s_setprio(1); _Pragma("unroll") for (int m = 0; m < 4; ++m) _Pragma("unroll") for (int n = 0; n < 2; ++n) _Pragma("unroll") for (int k = 0; k < 2; ++k) \
;         acc[ai][bj][m][n] = __builtin_amdgcn_mfma_f32_16x16x32_bf16(Bt[n][k], At[m][k], acc[ai][bj][m][n], 0, 0, 0); __builtin_amdgcn_s_setprio(0); } while (0)
; #define PG8_WAIT_V(n) asm volatile("s_waitcnt vmcnt(" #n ")" ::: "memory")
; #define PG8_WAIT_L(n) asm volatile("s_waitcnt lgkmcnt(" #n ")" ::: "memory")
; #define PG8_BAR __builtin_amdgcn_s_barrier()
; #define PG8_SCHED __builtin_amdgcn_sched_barrier(0)
; template <class Epi, class Sched, bool ALIGN_EPI = false, bool SP2 = false>
; __device__ __forceinline__ void gemm_phase(PG8_LAS unsigned char* lds, const Gemm g, const Sched& S, const Epi& E) {
;     ...
;             PG8_WAIT_V(8); PG8_WAIT_L(0); PG8_BAR; PG8_MMA(1, 0, At, B0); PG8_MMA(1, 1, At, B1); PG8_BAR; PG8_SCHED;
;             PG8_LDB(B0, 1, 0); PG8_LDB(B1, 1, 1); PG8_SCHED; PG8_LDA(At, 1, 0); PG8_STAGE(PG8_SA(0, 1), a2 + hstep, voffA);
;             PG8_WAIT_V(8); PG8_WAIT_L(0); PG8_BAR; PG8_MMA(0, 0, At, B0); PG8_MMA(0, 1, At, B1); PG8_BAR; PG8_SCHED;
	s_setprio 1
	s_waitcnt lgkmcnt(0)
	v_mfma_f32_16x16x32_bf16 v[92:95], v[120:123], v[160:163], v[92:95]
	v_mfma_f32_16x16x32_bf16 v[28:31], v[128:131], v[160:163], v[28:31]
	v_mfma_f32_16x16x32_bf16 v[84:87], v[120:123], v[180:183], v[84:87]
	v_mfma_f32_16x16x32_bf16 v[20:23], v[128:131], v[180:183], v[20:23]
	v_mfma_f32_16x16x32_bf16 v[76:79], v[120:123], v[188:191], v[76:79]
	v_mfma_f32_16x16x32_bf16 v[12:15], v[128:131], v[188:191], v[12:15]
	v_mfma_f32_16x16x32_bf16 v[72:75], v[120:123], v[210:213], v[72:75]
	v_mfma_f32_16x16x32_bf16 v[8:11], v[128:131], v[210:213], v[8:11]
	v_mfma_f32_16x16x32_bf16 v[92:95], v[124:127], v[164:167], v[92:95]
	v_mfma_f32_16x16x32_bf16 v[28:31], v[132:135], v[164:167], v[28:31]
	v_mfma_f32_16x16x32_bf16 v[84:87], v[124:127], v[184:187], v[84:87]
	v_mfma_f32_16x16x32_bf16 v[20:23], v[132:135], v[184:187], v[20:23]
	v_mfma_f32_16x16x32_bf16 v[76:79], v[124:127], v[206:209], v[76:79]
	v_mfma_f32_16x16x32_bf16 v[12:15], v[132:135], v[206:209], v[12:15]
	v_mfma_f32_16x16x32_bf16 v[72:75], v[124:127], v[214:217], v[72:75]
	v_mfma_f32_16x16x32_bf16 v[8:11], v[132:135], v[214:217], v[8:11]
	v_mfma_f32_16x16x32_bf16 v[88:91], v[136:139], v[160:163], v[88:91]
	v_mfma_f32_16x16x32_bf16 v[24:27], v[144:147], v[160:163], v[24:27]
	v_mfma_f32_16x16x32_bf16 v[80:83], v[136:139], v[180:183], v[80:83]
	v_mfma_f32_16x16x32_bf16 v[16:19], v[144:147], v[180:183], v[16:19]
	v_mfma_f32_16x16x32_bf16 v[68:71], v[136:139], v[188:191], v[68:71]
	v_mfma_f32_16x16x32_bf16 v[4:7], v[144:147], v[188:191], v[4:7]
	v_mfma_f32_16x16x32_bf16 v[64:67], v[136:139], v[210:213], v[64:67]
	v_mfma_f32_16x16x32_bf16 v[0:3], v[144:147], v[210:213], v[0:3]
	v_mfma_f32_16x16x32_bf16 v[88:91], v[140:143], v[164:167], v[88:91]
	v_mfma_f32_16x16x32_bf16 v[24:27], v[148:151], v[164:167], v[24:27]
	v_mfma_f32_16x16x32_bf16 v[80:83], v[140:143], v[184:187], v[80:83]
	v_mfma_f32_16x16x32_bf16 v[16:19], v[148:151], v[184:187], v[16:19]
	v_mfma_f32_16x16x32_bf16 v[68:71], v[140:143], v[206:209], v[68:71]
	v_mfma_f32_16x16x32_bf16 v[4:7], v[148:151], v[206:209], v[4:7]
	v_mfma_f32_16x16x32_bf16 v[64:67], v[140:143], v[214:217], v[64:67]
	v_mfma_f32_16x16x32_bf16 v[0:3], v[148:151], v[214:217], v[0:3]
	s_setprio 0
	s_barrier
	s_add_i32 s92, 0, 0x18000
	s_add_i32 s93, 0, 0x1c000
	v_add_u32_e32 v132, s92, v196
	v_add_u32_e32 v148, s93, v196
	ds_read_b128 v[120:123], v132
	ds_read_b128 v[124:127], v132 offset:1024
	ds_read_b128 v[128:131], v132 offset:2048
	ds_read_b128 v[132:135], v132 offset:3072
	ds_read_b128 v[136:139], v148
	ds_read_b128 v[140:143], v148 offset:1024
	ds_read_b128 v[144:147], v148 offset:2048
	ds_read_b128 v[148:151], v148 offset:3072
	s_add_u32 s60, s60, 0x80000
	s_addc_u32 s61, s61, 0
	s_mov_b32 m0, s69
	v_lshl_add_u64 v[226:227], s[60:61], 0, v[170:171]
	ds_read_b128 v[160:163], v202 offset:32768
	ds_read_b128 v[164:167], v202 offset:33792
	ds_read_b128 v[180:183], v202 offset:34816
	ds_read_b128 v[184:187], v202 offset:35840
	ds_read_b128 v[188:191], v202 offset:36864
	ds_read_b128 v[206:209], v202 offset:37888
	ds_read_b128 v[210:213], v202 offset:38912
	ds_read_b128 v[214:217], v202 offset:39936
	global_load_lds_dwordx4 v[226:227], off
	v_lshl_add_u64 v[226:227], s[60:61], 0, v[168:169]
	s_mov_b32 m0, s70
	s_nop 0
	global_load_lds_dwordx4 v[226:227], off
	s_waitcnt vmcnt(8)
	s_waitcnt lgkmcnt(0)
	s_barrier
	s_setprio 1
	s_waitcnt lgkmcnt(0)
	v_mfma_f32_16x16x32_bf16 v[156:159], v[120:123], v[160:163], v[156:159]
	v_mfma_f32_16x16x32_bf16 v[60:63], v[128:131], v[160:163], v[60:63]
	v_mfma_f32_16x16x32_bf16 v[116:119], v[120:123], v[180:183], v[116:119]
	v_mfma_f32_16x16x32_bf16 v[52:55], v[128:131], v[180:183], v[52:55]
	v_mfma_f32_16x16x32_bf16 v[108:111], v[120:123], v[188:191], v[108:111]
	v_mfma_f32_16x16x32_bf16 v[44:47], v[128:131], v[188:191], v[44:47]
	v_mfma_f32_16x16x32_bf16 v[104:107], v[120:123], v[210:213], v[104:107]
	v_mfma_f32_16x16x32_bf16 v[40:43], v[128:131], v[210:213], v[40:43]
	v_mfma_f32_16x16x32_bf16 v[156:159], v[124:127], v[164:167], v[156:159]
	v_mfma_f32_16x16x32_bf16 v[60:63], v[132:135], v[164:167], v[60:63]
	v_mfma_f32_16x16x32_bf16 v[116:119], v[124:127], v[184:187], v[116:119]
	v_mfma_f32_16x16x32_bf16 v[52:55], v[132:135], v[184:187], v[52:55]
	v_mfma_f32_16x16x32_bf16 v[108:111], v[124:127], v[206:209], v[108:111]
	v_mfma_f32_16x16x32_bf16 v[44:47], v[132:135], v[206:209], v[44:47]
	v_mfma_f32_16x16x32_bf16 v[104:107], v[124:127], v[214:217], v[104:107]
	v_mfma_f32_16x16x32_bf16 v[40:43], v[132:135], v[214:217], v[40:43]
	v_mfma_f32_16x16x32_bf16 v[152:155], v[136:139], v[160:163], v[152:155]
	v_mfma_f32_16x16x32_bf16 v[56:59], v[144:147], v[160:163], v[56:59]
	v_mfma_f32_16x16x32_bf16 v[112:115], v[136:139], v[180:183], v[112:115]
	v_mfma_f32_16x16x32_bf16 v[48:51], v[144:147], v[180:183], v[48:51]
	v_mfma_f32_16x16x32_bf16 v[100:103], v[136:139], v[188:191], v[100:103]
	v_mfma_f32_16x16x32_bf16 v[36:39], v[144:147], v[188:191], v[36:39]
	v_mfma_f32_16x16x32_bf16 v[96:99], v[136:139], v[210:213], v[96:99]
	v_mfma_f32_16x16x32_bf16 v[32:35], v[144:147], v[210:213], v[32:35]
	v_mfma_f32_16x16x32_bf16 v[152:155], v[140:143], v[164:167], v[152:155]
	v_mfma_f32_16x16x32_bf16 v[56:59], v[148:151], v[164:167], v[56:59]
	v_mfma_f32_16x16x32_bf16 v[112:115], v[140:143], v[184:187], v[112:115]
	v_mfma_f32_16x16x32_bf16 v[48:51], v[148:151], v[184:187], v[48:51]
	v_mfma_f32_16x16x32_bf16 v[100:103], v[140:143], v[206:209], v[100:103]
	v_mfma_f32_16x16x32_bf16 v[36:39], v[148:151], v[206:209], v[36:39]
	v_mfma_f32_16x16x32_bf16 v[96:99], v[140:143], v[214:217], v[96:99]
	v_mfma_f32_16x16x32_bf16 v[32:35], v[148:151], v[214:217], v[32:35]
	s_setprio 0
	s_barrier
; #define PG8_STAGE(bufoff, gbase, voff) do { _Pragma("unroll") for (int _i = 0; _i < 2; ++_i) \
;         __builtin_amdgcn_global_load_lds((const unsigned*)((const char*)(gbase) + (voff)[_i]), (PG8_LAS unsigned*)(lds + (bufoff) + ldsw + _i * 8192), 16, 0, 0); } while (0)
; #define PG8_LDA(dst, b, h) do { _Pragma("unroll") for (int m = 0; m < 4; ++m) _Pragma("unroll") for (int k = 0; k < 2; ++k) dst[m][k] = *(const PG8_LAS bf16x8*)(lds + PG8_SA(b, h) + aoff + m * 2048 + k * 1024); } while (0)
; #define PG8_MMA(ai, bj, At, Bt) do { __builtin_amdgcn_s_setprio(1); _Pragma("unroll") for (int m = 0; m < 4; ++m) _Pragma("unroll") for (int n = 0; n < 2; ++n) _Pragma("unroll") for (int k = 0; k < 2; ++k) \
;         acc[ai][bj][m][n] = __builtin_amdgcn_mfma_f32_16x16x32_bf16(Bt[n][k], At[m][k], acc[ai][bj][m][n], 0, 0, 0); __builtin_amdgcn_s_setprio(0); } while (0)
; #define PG8_WAIT_V(n) asm volatile("s_waitcnt vmcnt(" #n ")" ::: "memory")
; #define PG8_WAIT_L(n) asm volatile("s_waitcnt lgkmcnt(" #n ")" ::: "memory")
; #define PG8_BAR __builtin_amdgcn_s_barrier()
; #define PG8_SCHED __builtin_amdgcn_sched_barrier(0)
; template <class Epi, class Sched, bool ALIGN_EPI = false, bool SP2 = false>
; __device__ __forceinline__ void gemm_phase(PG8_LAS unsigned char* lds, const Gemm g, const Sched& S, const Epi& E) {
;     ...
;             PG8_LDA(At, 1, 1); PG8_STAGE(PG8_SB(1, 0), b3, voffB); PG8_STAGE(PG8_SB(1, 1), b3 + hstep, voffB); PG8_STAGE(PG8_SA(1, 0), a3, voffA);
;             PG8_WAIT_V(8); PG8_WAIT_L(0); PG8_BAR; PG8_MMA(1, 0, At, B0); PG8_MMA(1, 1, At, B1); PG8_BAR; PG8_SCHED;
;     ...
;         if constexpr (ALIGN_EPI) { if (wr == 0) PG8_BAR; }
	s_add_i32 s60, s92, s66
	v_lshl_add_u64 v[192:193], v[192:193], 0, s[22:23]
	s_mov_b32 m0, s60
	ds_read_b128 v[160:163], v202 offset:49152
	ds_read_b128 v[164:167], v202 offset:50176
	ds_read_b128 v[180:183], v202 offset:51200
	ds_read_b128 v[184:187], v202 offset:52224
	ds_read_b128 v[188:191], v202 offset:53248
	ds_read_b128 v[206:209], v202 offset:54272
	ds_read_b128 v[210:213], v202 offset:55296
	ds_read_b128 v[214:217], v202 offset:56320
	global_load_lds_dwordx4 v[192:193], off
	s_add_i32 m0, s60, 0x2000
	s_add_u32 s58, s58, 0x80080
	v_lshl_add_u64 v[192:193], v[218:219], 0, s[22:23]
	s_addc_u32 s59, s59, 0
	s_add_i32 s60, s93, s66
	global_load_lds_dwordx4 v[192:193], off
	v_lshl_add_u64 v[192:193], s[58:59], 0, v[170:171]
	s_mov_b32 m0, s60
	s_nop 0
	global_load_lds_dwordx4 v[192:193], off
	v_lshl_add_u64 v[192:193], s[58:59], 0, v[168:169]
	s_add_i32 m0, s60, 0x2000
	s_nop 0
	global_load_lds_dwordx4 v[192:193], off
	v_lshl_add_u64 v[192:193], v[222:223], 0, s[22:23]
	s_mov_b32 m0, s71
	s_nop 0
	global_load_lds_dwordx4 v[192:193], off
	v_lshl_add_u64 v[192:193], v[224:225], 0, s[22:23]
	s_mov_b32 m0, s72
	s_nop 0
	global_load_lds_dwordx4 v[192:193], off
	s_waitcnt vmcnt(8)
	s_waitcnt lgkmcnt(0)
	s_barrier
	s_setprio 1
	s_waitcnt lgkmcnt(0)
	v_mfma_f32_16x16x32_bf16 v[92:95], v[120:123], v[160:163], v[92:95]
	v_mfma_f32_16x16x32_bf16 v[28:31], v[128:131], v[160:163], v[28:31]
	v_mfma_f32_16x16x32_bf16 v[84:87], v[120:123], v[180:183], v[84:87]
	v_mfma_f32_16x16x32_bf16 v[20:23], v[128:131], v[180:183], v[20:23]
	v_mfma_f32_16x16x32_bf16 v[76:79], v[120:123], v[188:191], v[76:79]
	v_mfma_f32_16x16x32_bf16 v[12:15], v[128:131], v[188:191], v[12:15]
	v_mfma_f32_16x16x32_bf16 v[72:75], v[120:123], v[210:213], v[72:75]
	v_mfma_f32_16x16x32_bf16 v[8:11], v[128:131], v[210:213], v[8:11]
	v_mfma_f32_16x16x32_bf16 v[92:95], v[124:127], v[164:167], v[92:95]
	v_mfma_f32_16x16x32_bf16 v[28:31], v[132:135], v[164:167], v[28:31]
	v_mfma_f32_16x16x32_bf16 v[84:87], v[124:127], v[184:187], v[84:87]
	v_mfma_f32_16x16x32_bf16 v[20:23], v[132:135], v[184:187], v[20:23]
	v_mfma_f32_16x16x32_bf16 v[76:79], v[124:127], v[206:209], v[76:79]
	v_mfma_f32_16x16x32_bf16 v[12:15], v[132:135], v[206:209], v[12:15]
	v_mfma_f32_16x16x32_bf16 v[72:75], v[124:127], v[214:217], v[72:75]
	v_mfma_f32_16x16x32_bf16 v[8:11], v[132:135], v[214:217], v[8:11]
	v_mfma_f32_16x16x32_bf16 v[88:91], v[136:139], v[160:163], v[88:91]
	v_mfma_f32_16x16x32_bf16 v[24:27], v[144:147], v[160:163], v[24:27]
	v_mfma_f32_16x16x32_bf16 v[80:83], v[136:139], v[180:183], v[80:83]
	v_mfma_f32_16x16x32_bf16 v[16:19], v[144:147], v[180:183], v[16:19]
	v_mfma_f32_16x16x32_bf16 v[68:71], v[136:139], v[188:191], v[68:71]
	v_mfma_f32_16x16x32_bf16 v[4:7], v[144:147], v[188:191], v[4:7]
	v_mfma_f32_16x16x32_bf16 v[64:67], v[136:139], v[210:213], v[64:67]
	v_mfma_f32_16x16x32_bf16 v[0:3], v[144:147], v[210:213], v[0:3]
	v_mfma_f32_16x16x32_bf16 v[88:91], v[140:143], v[164:167], v[88:91]
	v_mfma_f32_16x16x32_bf16 v[24:27], v[148:151], v[164:167], v[24:27]
	v_mfma_f32_16x16x32_bf16 v[80:83], v[140:143], v[184:187], v[80:83]
	v_mfma_f32_16x16x32_bf16 v[16:19], v[148:151], v[184:187], v[16:19]
	v_mfma_f32_16x16x32_bf16 v[68:71], v[140:143], v[206:209], v[68:71]
	v_mfma_f32_16x16x32_bf16 v[4:7], v[148:151], v[206:209], v[4:7]
	v_mfma_f32_16x16x32_bf16 v[64:67], v[140:143], v[214:217], v[64:67]
	v_mfma_f32_16x16x32_bf16 v[0:3], v[148:151], v[214:217], v[0:3]
	s_setprio 0
	s_barrier
	s_add_i32 s91, s91, 2
	s_add_u32 s89, s89, 0x100
	s_addc_u32 s90, s90, 0
	s_add_u32 s54, s54, 0x100
	s_addc_u32 s55, s55, 0
	s_cmp_gt_u32 s91, 29
	s_cbranch_scc0 .LBB0_679
	s_and_b64 vcc, exec, s[24:25]
	s_cbranch_vccz .LBB0_682
	s_barrier

; #define PG8_STAGE(bufoff, gbase, voff) do { _Pragma("unroll") for (int _i = 0; _i < 2; ++_i) \
;         __builtin_amdgcn_global_load_lds((const unsigned*)((const char*)(gbase) + (voff)[_i]), (PG8_LAS unsigned*)(lds + (bufoff) + ldsw + _i * 8192), 16, 0, 0); } while (0)
; #define PG8_LDA(dst, b, h) do { _Pragma("unroll") for (int m = 0; m < 4; ++m) _Pragma("unroll") for (int k = 0; k < 2; ++k) dst[m][k] = *(const PG8_LAS bf16x8*)(lds + PG8_SA(b, h) + aoff + m * 2048 + k * 1024); } while (0)
; #define PG8_LDB(dst, b, h) do { _Pragma("unroll") for (int n = 0; n < 2; ++n) _Pragma("unroll") for (int k = 0; k < 2; ++k) dst[n][k] = *(const PG8_LAS bf16x8*)(lds + PG8_SB(b, h) + boff + n * 2048 + k * 1024); } while (0)
; #define PG8_MMA(ai, bj, At, Bt) do { __builtin_amdgcn_s_setprio(1); _Pragma("unroll") for (int m = 0; m < 4; ++m) _Pragma("unroll") for (int n = 0; n < 2; ++n) _Pragma("unroll") for (int k = 0; k < 2; ++k) \
;         acc[ai][bj][m][n] = __builtin_amdgcn_mfma_f32_16x16x32_bf16(Bt[n][k], At[m][k], acc[ai][bj][m][n], 0, 0, 0); __builtin_amdgcn_s_setprio(0); } while (0)
; #define PG8_WAIT_V(n) asm volatile("s_waitcnt vmcnt(" #n ")" ::: "memory")
; #define PG8_WAIT_L(n) asm volatile("s_waitcnt lgkmcnt(" #n ")" ::: "memory")
; template <class Epi, class Sched, bool ALIGN_EPI = false, bool SP2 = false>
; __device__ __forceinline__ void gemm_phase(PG8_LAS unsigned char* lds, const Gemm g, const Sched& S, const Epi& E) {
;     ...
;             const bool last = (t == nt - 2);
;             const char* a1 = cA + (size_t)(t + 1) * kstep;
;             const char* a2 = last ? nA : cA + (size_t)(t + 2) * kstep; const char* b2 = last ? nB : cB + (size_t)(t + 2) * kstep;
;             const char* a3 = a2 + kstep; const char* b3 = b2 + kstep;
;             if (last && has_next) S.a_ready(nxt);
;             if constexpr (SP2) {
;             PG8_LDB(B0, 0, 0); PG8_LDB(B1, 0, 1); PG8_SCHED; PG8_LDA(At, 0, 0); PG8_STAGE(PG8_SA(1, 1), a1 + hstep, voffA);
;             PG8_WAIT_V(8); PG8_WAIT_L(0); PG8_BAR; PG8_MMA(0, 0, At, B0); PG8_MMA(0, 1, At, B1); PG8_BAR; PG8_SCHED;
;             PG8_LDA(At, 0, 1); PG8_STAGE(PG8_SB(0, 0), b2, voffB); PG8_STAGE(PG8_SB(0, 1), b2 + hstep, voffB); PG8_STAGE(PG8_SA(0, 0), a2, voffA);
;             PG8_WAIT_V(8); PG8_WAIT_L(0); PG8_BAR; PG8_MMA(1, 0, At, B0); PG8_MMA(1, 1, At, B1); PG8_BAR; PG8_SCHED;
.LBB0_821:
	ds_read_b128 v[92:95], v214
	ds_read_b128 v[100:103], v214 offset:1024
	ds_read_b128 v[104:107], v214 offset:2048
	ds_read_b128 v[172:175], v214 offset:3072
	ds_read_b128 v[176:179], v215
	ds_read_b128 v[180:183], v215 offset:1024
	ds_read_b128 v[184:187], v215 offset:2048
	ds_read_b128 v[188:191], v215 offset:3072
	s_add_u32 s34, s30, 0x100
	s_addc_u32 s35, s31, 0
	s_add_u32 s36, s64, s30
	s_addc_u32 s37, s65, s31
	s_cmpk_eq_i32 s66, 0x54
	s_cselect_b32 s38, s28, s36
	s_cselect_b32 s36, 0, s34
	s_cselect_b32 s39, s29, s37
	s_cselect_b32 s37, 0, s35
	s_add_u32 s36, s16, s36
	s_addc_u32 s37, s17, s37
	s_mov_b32 m0, s52
	v_lshl_add_u64 v[234:235], v[90:91], 0, s[30:31]
	ds_read_b128 v[192:195], v212
	ds_read_b128 v[196:199], v212 offset:1024
	ds_read_b128 v[200:203], v212 offset:2048
	ds_read_b128 v[204:207], v212 offset:3072
	ds_read_b128 v[208:211], v212 offset:4096
	ds_read_b128 v[222:225], v212 offset:5120
	ds_read_b128 v[226:229], v212 offset:6144
	ds_read_b128 v[230:233], v212 offset:7168
	global_load_lds_dwordx4 v[234:235], off
	v_lshl_add_u64 v[234:235], v[88:89], 0, s[30:31]
	s_mov_b32 m0, s53
	s_nop 0
	global_load_lds_dwordx4 v[234:235], off
	s_waitcnt vmcnt(8)
	s_waitcnt lgkmcnt(0)
	s_barrier
	s_setprio 1
	s_waitcnt lgkmcnt(0)
	v_mfma_f32_16x16x32_bf16 v[140:143], v[92:95], v[192:195], v[140:143]
	v_mfma_f32_16x16x32_bf16 v[136:139], v[104:107], v[192:195], v[136:139]
	v_mfma_f32_16x16x32_bf16 v[124:127], v[92:95], v[200:203], v[124:127]
	v_mfma_f32_16x16x32_bf16 v[120:123], v[104:107], v[200:203], v[120:123]
	v_mfma_f32_16x16x32_bf16 v[108:111], v[92:95], v[208:211], v[108:111]
	v_mfma_f32_16x16x32_bf16 v[96:99], v[104:107], v[208:211], v[96:99]
	v_mfma_f32_16x16x32_bf16 v[76:79], v[92:95], v[226:229], v[76:79]
	v_mfma_f32_16x16x32_bf16 v[72:75], v[104:107], v[226:229], v[72:75]
	v_mfma_f32_16x16x32_bf16 v[140:143], v[100:103], v[196:199], v[140:143]
	v_mfma_f32_16x16x32_bf16 v[136:139], v[172:175], v[196:199], v[136:139]
	v_mfma_f32_16x16x32_bf16 v[124:127], v[100:103], v[204:207], v[124:127]
	v_mfma_f32_16x16x32_bf16 v[120:123], v[172:175], v[204:207], v[120:123]
	v_mfma_f32_16x16x32_bf16 v[108:111], v[100:103], v[222:225], v[108:111]
	v_mfma_f32_16x16x32_bf16 v[96:99], v[172:175], v[222:225], v[96:99]
	v_mfma_f32_16x16x32_bf16 v[76:79], v[100:103], v[230:233], v[76:79]
	v_mfma_f32_16x16x32_bf16 v[72:75], v[172:175], v[230:233], v[72:75]
	v_mfma_f32_16x16x32_bf16 v[132:135], v[176:179], v[192:195], v[132:135]
	v_mfma_f32_16x16x32_bf16 v[128:131], v[184:187], v[192:195], v[128:131]
	v_mfma_f32_16x16x32_bf16 v[116:119], v[176:179], v[200:203], v[116:119]
	v_mfma_f32_16x16x32_bf16 v[112:115], v[184:187], v[200:203], v[112:115]
	v_mfma_f32_16x16x32_bf16 v[84:87], v[176:179], v[208:211], v[84:87]
	v_mfma_f32_16x16x32_bf16 v[80:83], v[184:187], v[208:211], v[80:83]
	v_mfma_f32_16x16x32_bf16 v[68:71], v[176:179], v[226:229], v[68:71]
	v_mfma_f32_16x16x32_bf16 v[64:67], v[184:187], v[226:229], v[64:67]
	v_mfma_f32_16x16x32_bf16 v[132:135], v[180:183], v[196:199], v[132:135]
	v_mfma_f32_16x16x32_bf16 v[128:131], v[188:191], v[196:199], v[128:131]
	v_mfma_f32_16x16x32_bf16 v[116:119], v[180:183], v[204:207], v[116:119]
	v_mfma_f32_16x16x32_bf16 v[112:115], v[188:191], v[204:207], v[112:115]
	v_mfma_f32_16x16x32_bf16 v[84:87], v[180:183], v[222:225], v[84:87]
	v_mfma_f32_16x16x32_bf16 v[80:83], v[188:191], v[222:225], v[80:83]
	v_mfma_f32_16x16x32_bf16 v[68:71], v[180:183], v[230:233], v[68:71]
	v_mfma_f32_16x16x32_bf16 v[64:67], v[188:191], v[230:233], v[64:67]
	s_setprio 0
	s_barrier
	s_mov_b32 m0, s54
	v_lshl_add_u64 v[234:235], s[36:37], 0, v[146:147]
	s_add_u32 s30, s36, 0x160000
	ds_read_b128 v[192:195], v212 offset:16384
	ds_read_b128 v[196:199], v212 offset:17408
	ds_read_b128 v[200:203], v212 offset:18432
	ds_read_b128 v[204:207], v212 offset:19456
	ds_read_b128 v[208:211], v212 offset:20480
	ds_read_b128 v[222:225], v212 offset:21504
	ds_read_b128 v[226:229], v212 offset:22528
	ds_read_b128 v[230:233], v212 offset:23552
	global_load_lds_dwordx4 v[234:235], off
	v_lshl_add_u64 v[236:237], s[36:37], 0, v[144:145]
	s_mov_b32 m0, s55
	s_addc_u32 s31, s37, 0
	global_load_lds_dwordx4 v[236:237], off
	v_lshl_add_u64 v[238:239], s[30:31], 0, v[146:147]
	s_mov_b32 m0, s58
	v_lshl_add_u64 v[240:241], s[38:39], 0, v[144:145]
	global_load_lds_dwordx4 v[238:239], off
	v_lshl_add_u64 v[238:239], s[30:31], 0, v[144:145]
	s_mov_b32 m0, s59
	s_nop 0
	global_load_lds_dwordx4 v[238:239], off
	v_lshl_add_u64 v[238:239], s[38:39], 0, v[146:147]
	s_mov_b32 m0, s44
	s_nop 0
	global_load_lds_dwordx4 v[238:239], off
	s_mov_b32 m0, s45
	s_nop 0
	global_load_lds_dwordx4 v[240:241], off
	s_waitcnt vmcnt(8)
	s_waitcnt lgkmcnt(0)
	s_barrier
; #define PG8_STAGE(bufoff, gbase, voff) do { _Pragma("unroll") for (int _i = 0; _i < 2; ++_i) \
;         __builtin_amdgcn_global_load_lds((const unsigned*)((const char*)(gbase) + (voff)[_i]), (PG8_LAS unsigned*)(lds + (bufoff) + ldsw + _i * 8192), 16, 0, 0); } while (0)
; #define PG8_LDA(dst, b, h) do { _Pragma("unroll") for (int m = 0; m < 4; ++m) _Pragma("unroll") for (int k = 0; k < 2; ++k) dst[m][k] = *(const PG8_LAS bf16x8*)(lds + PG8_SA(b, h) + aoff + m * 2048 + k * 1024); } while (0)
; #define PG8_LDB(dst, b, h) do { _Pragma("unroll") for (int n = 0; n < 2; ++n) _Pragma("unroll") for (int k = 0; k < 2; ++k) dst[n][k] = *(const PG8_LAS bf16x8*)(lds + PG8_SB(b, h) + boff + n * 2048 + k * 1024); } while (0)
; #define PG8_MMA(ai, bj, At, Bt) do { __builtin_amdgcn_s_setprio(1); _Pragma("unroll") for (int m = 0; m < 4; ++m) _Pragma("unroll") for (int n = 0; n < 2; ++n) _Pragma("unroll") for (int k = 0; k < 2; ++k) \
;         acc[ai][bj][m][n] = __builtin_amdgcn_mfma_f32_16x16x32_bf16(Bt[n][k], At[m][k], acc[ai][bj][m][n], 0, 0, 0); __builtin_amdgcn_s_setprio(0); } while (0)
; #define PG8_WAIT_V(n) asm volatile("s_waitcnt vmcnt(" #n ")" ::: "memory")
; #define PG8_WAIT_L(n) asm volatile("s_waitcnt lgkmcnt(" #n ")" ::: "memory")
; #define PG8_BAR __builtin_amdgcn_s_barrier()
; #define PG8_SCHED __builtin_amdgcn_sched_barrier(0)
; template <class Epi, class Sched, bool ALIGN_EPI = false, bool SP2 = false>
; __device__ __forceinline__ void gemm_phase(PG8_LAS unsigned char* lds, const Gemm g, const Sched& S, const Epi& E) {
;     ...
;             PG8_WAIT_V(8); PG8_WAIT_L(0); PG8_BAR; PG8_MMA(1, 0, At, B0); PG8_MMA(1, 1, At, B1); PG8_BAR; PG8_SCHED;
;             PG8_LDB(B0, 1, 0); PG8_LDB(B1, 1, 1); PG8_SCHED; PG8_LDA(At, 1, 0); PG8_STAGE(PG8_SA(0, 1), a2 + hstep, voffA);
;             PG8_WAIT_V(8); PG8_WAIT_L(0); PG8_BAR; PG8_MMA(0, 0, At, B0); PG8_MMA(0, 1, At, B1); PG8_BAR; PG8_SCHED;
	s_setprio 1
	s_waitcnt lgkmcnt(0)
	v_mfma_f32_16x16x32_bf16 v[60:63], v[92:95], v[192:195], v[60:63]
	v_mfma_f32_16x16x32_bf16 v[56:59], v[104:107], v[192:195], v[56:59]
	v_mfma_f32_16x16x32_bf16 v[44:47], v[92:95], v[200:203], v[44:47]
	v_mfma_f32_16x16x32_bf16 v[40:43], v[104:107], v[200:203], v[40:43]
	v_mfma_f32_16x16x32_bf16 v[28:31], v[92:95], v[208:211], v[28:31]
	v_mfma_f32_16x16x32_bf16 v[24:27], v[104:107], v[208:211], v[24:27]
	v_mfma_f32_16x16x32_bf16 v[12:15], v[92:95], v[226:229], v[12:15]
	v_mfma_f32_16x16x32_bf16 v[8:11], v[104:107], v[226:229], v[8:11]
	v_mfma_f32_16x16x32_bf16 v[60:63], v[100:103], v[196:199], v[60:63]
	v_mfma_f32_16x16x32_bf16 v[56:59], v[172:175], v[196:199], v[56:59]
	v_mfma_f32_16x16x32_bf16 v[44:47], v[100:103], v[204:207], v[44:47]
	v_mfma_f32_16x16x32_bf16 v[40:43], v[172:175], v[204:207], v[40:43]
	v_mfma_f32_16x16x32_bf16 v[28:31], v[100:103], v[222:225], v[28:31]
	v_mfma_f32_16x16x32_bf16 v[24:27], v[172:175], v[222:225], v[24:27]
	v_mfma_f32_16x16x32_bf16 v[12:15], v[100:103], v[230:233], v[12:15]
	v_mfma_f32_16x16x32_bf16 v[8:11], v[172:175], v[230:233], v[8:11]
	v_mfma_f32_16x16x32_bf16 v[52:55], v[176:179], v[192:195], v[52:55]
	v_mfma_f32_16x16x32_bf16 v[48:51], v[184:187], v[192:195], v[48:51]
	v_mfma_f32_16x16x32_bf16 v[36:39], v[176:179], v[200:203], v[36:39]
	v_mfma_f32_16x16x32_bf16 v[32:35], v[184:187], v[200:203], v[32:35]
	v_mfma_f32_16x16x32_bf16 v[20:23], v[176:179], v[208:211], v[20:23]
	v_mfma_f32_16x16x32_bf16 v[16:19], v[184:187], v[208:211], v[16:19]
	v_mfma_f32_16x16x32_bf16 v[4:7], v[176:179], v[226:229], v[4:7]
	v_mfma_f32_16x16x32_bf16 v[0:3], v[184:187], v[226:229], v[0:3]
	v_mfma_f32_16x16x32_bf16 v[52:55], v[180:183], v[196:199], v[52:55]
	v_mfma_f32_16x16x32_bf16 v[48:51], v[188:191], v[196:199], v[48:51]
	v_mfma_f32_16x16x32_bf16 v[36:39], v[180:183], v[204:207], v[36:39]
	v_mfma_f32_16x16x32_bf16 v[32:35], v[188:191], v[204:207], v[32:35]
	v_mfma_f32_16x16x32_bf16 v[20:23], v[180:183], v[222:225], v[20:23]
	v_mfma_f32_16x16x32_bf16 v[16:19], v[188:191], v[222:225], v[16:19]
	v_mfma_f32_16x16x32_bf16 v[4:7], v[180:183], v[230:233], v[4:7]
	v_mfma_f32_16x16x32_bf16 v[0:3], v[188:191], v[230:233], v[0:3]
	s_setprio 0
	s_barrier
	ds_read_b128 v[92:95], v216
	ds_read_b128 v[100:103], v216 offset:1024
	ds_read_b128 v[104:107], v216 offset:2048
	ds_read_b128 v[172:175], v216 offset:3072
	ds_read_b128 v[176:179], v217
	ds_read_b128 v[180:183], v217 offset:1024
	ds_read_b128 v[184:187], v217 offset:2048
	ds_read_b128 v[188:191], v217 offset:3072
	s_add_u32 s30, s38, 0x160000
	s_addc_u32 s31, s39, 0
	s_mov_b32 m0, s46
	v_lshl_add_u64 v[242:243], s[30:31], 0, v[146:147]
	ds_read_b128 v[192:195], v212 offset:32768
	ds_read_b128 v[196:199], v212 offset:33792
	ds_read_b128 v[200:203], v212 offset:34816
	ds_read_b128 v[204:207], v212 offset:35840
	ds_read_b128 v[208:211], v212 offset:36864
	ds_read_b128 v[222:225], v212 offset:37888
	ds_read_b128 v[226:229], v212 offset:38912
	ds_read_b128 v[230:233], v212 offset:39936
	global_load_lds_dwordx4 v[242:243], off
	v_lshl_add_u64 v[242:243], s[30:31], 0, v[144:145]
	s_mov_b32 m0, s47
	s_nop 0
	global_load_lds_dwordx4 v[242:243], off
	s_waitcnt vmcnt(8)
	s_waitcnt lgkmcnt(0)
	s_barrier
	s_setprio 1
	s_waitcnt lgkmcnt(0)
	v_mfma_f32_16x16x32_bf16 v[140:143], v[92:95], v[192:195], v[140:143]
	v_mfma_f32_16x16x32_bf16 v[136:139], v[104:107], v[192:195], v[136:139]
	v_mfma_f32_16x16x32_bf16 v[124:127], v[92:95], v[200:203], v[124:127]
	v_mfma_f32_16x16x32_bf16 v[120:123], v[104:107], v[200:203], v[120:123]
	v_mfma_f32_16x16x32_bf16 v[108:111], v[92:95], v[208:211], v[108:111]
	v_mfma_f32_16x16x32_bf16 v[96:99], v[104:107], v[208:211], v[96:99]
	v_mfma_f32_16x16x32_bf16 v[76:79], v[92:95], v[226:229], v[76:79]
	v_mfma_f32_16x16x32_bf16 v[72:75], v[104:107], v[226:229], v[72:75]
	v_mfma_f32_16x16x32_bf16 v[140:143], v[100:103], v[196:199], v[140:143]
	v_mfma_f32_16x16x32_bf16 v[136:139], v[172:175], v[196:199], v[136:139]
	v_mfma_f32_16x16x32_bf16 v[124:127], v[100:103], v[204:207], v[124:127]
	v_mfma_f32_16x16x32_bf16 v[120:123], v[172:175], v[204:207], v[120:123]
	v_mfma_f32_16x16x32_bf16 v[108:111], v[100:103], v[222:225], v[108:111]
	v_mfma_f32_16x16x32_bf16 v[96:99], v[172:175], v[222:225], v[96:99]
	v_mfma_f32_16x16x32_bf16 v[76:79], v[100:103], v[230:233], v[76:79]
	v_mfma_f32_16x16x32_bf16 v[72:75], v[172:175], v[230:233], v[72:75]
	v_mfma_f32_16x16x32_bf16 v[132:135], v[176:179], v[192:195], v[132:135]
	v_mfma_f32_16x16x32_bf16 v[128:131], v[184:187], v[192:195], v[128:131]
	v_mfma_f32_16x16x32_bf16 v[116:119], v[176:179], v[200:203], v[116:119]
	v_mfma_f32_16x16x32_bf16 v[112:115], v[184:187], v[200:203], v[112:115]
	v_mfma_f32_16x16x32_bf16 v[84:87], v[176:179], v[208:211], v[84:87]
	v_mfma_f32_16x16x32_bf16 v[80:83], v[184:187], v[208:211], v[80:83]
	v_mfma_f32_16x16x32_bf16 v[68:71], v[176:179], v[226:229], v[68:71]
	v_mfma_f32_16x16x32_bf16 v[64:67], v[184:187], v[226:229], v[64:67]
	v_mfma_f32_16x16x32_bf16 v[132:135], v[180:183], v[196:199], v[132:135]
	v_mfma_f32_16x16x32_bf16 v[128:131], v[188:191], v[196:199], v[128:131]
	v_mfma_f32_16x16x32_bf16 v[116:119], v[180:183], v[204:207], v[116:119]
	v_mfma_f32_16x16x32_bf16 v[112:115], v[188:191], v[204:207], v[112:115]
	v_mfma_f32_16x16x32_bf16 v[84:87], v[180:183], v[222:225], v[84:87]
	v_mfma_f32_16x16x32_bf16 v[80:83], v[188:191], v[222:225], v[80:83]
	v_mfma_f32_16x16x32_bf16 v[68:71], v[180:183], v[230:233], v[68:71]
	v_mfma_f32_16x16x32_bf16 v[64:67], v[188:191], v[230:233], v[64:67]
	s_setprio 0
	s_barrier
; #define PG8_STAGE(bufoff, gbase, voff) do { _Pragma("unroll") for (int _i = 0; _i < 2; ++_i) \
;         __builtin_amdgcn_global_load_lds((const unsigned*)((const char*)(gbase) + (voff)[_i]), (PG8_LAS unsigned*)(lds + (bufoff) + ldsw + _i * 8192), 16, 0, 0); } while (0)
; #define PG8_LDA(dst, b, h) do { _Pragma("unroll") for (int m = 0; m < 4; ++m) _Pragma("unroll") for (int k = 0; k < 2; ++k) dst[m][k] = *(const PG8_LAS bf16x8*)(lds + PG8_SA(b, h) + aoff + m * 2048 + k * 1024); } while (0)
; #define PG8_MMA(ai, bj, At, Bt) do { __builtin_amdgcn_s_setprio(1); _Pragma("unroll") for (int m = 0; m < 4; ++m) _Pragma("unroll") for (int n = 0; n < 2; ++n) _Pragma("unroll") for (int k = 0; k < 2; ++k) \
;         acc[ai][bj][m][n] = __builtin_amdgcn_mfma_f32_16x16x32_bf16(Bt[n][k], At[m][k], acc[ai][bj][m][n], 0, 0, 0); __builtin_amdgcn_s_setprio(0); } while (0)
; #define PG8_WAIT_V(n) asm volatile("s_waitcnt vmcnt(" #n ")" ::: "memory")
; #define PG8_WAIT_L(n) asm volatile("s_waitcnt lgkmcnt(" #n ")" ::: "memory")
; #define PG8_BAR __builtin_amdgcn_s_barrier()
; #define PG8_SCHED __builtin_amdgcn_sched_barrier(0)
; template <class Epi, class Sched, bool ALIGN_EPI = false, bool SP2 = false>
; __device__ __forceinline__ void gemm_phase(PG8_LAS unsigned char* lds, const Gemm g, const Sched& S, const Epi& E) {
;     ...
;             PG8_LDA(At, 1, 1); PG8_STAGE(PG8_SB(1, 0), b3, voffB); PG8_STAGE(PG8_SB(1, 1), b3 + hstep, voffB); PG8_STAGE(PG8_SA(1, 0), a3, voffA);
;             PG8_WAIT_V(8); PG8_WAIT_L(0); PG8_BAR; PG8_MMA(1, 0, At, B0); PG8_MMA(1, 1, At, B1); PG8_BAR; PG8_SCHED;
;     ...
;         if constexpr (ALIGN_EPI) { if (wr == 0) PG8_BAR; }
	s_mov_b32 m0, s61
	v_lshl_add_u64 v[234:235], v[234:235], 0, s[26:27]
	ds_read_b128 v[192:195], v212 offset:49152
	ds_read_b128 v[196:199], v212 offset:50176
	ds_read_b128 v[200:203], v212 offset:51200
	ds_read_b128 v[204:207], v212 offset:52224
	ds_read_b128 v[208:211], v212 offset:53248
	ds_read_b128 v[222:225], v212 offset:54272
	ds_read_b128 v[226:229], v212 offset:55296
	ds_read_b128 v[230:233], v212 offset:56320
	global_load_lds_dwordx4 v[234:235], off
	s_add_i32 m0, s61, 0x2000
	s_add_u32 s30, s36, 0x160080
	v_lshl_add_u64 v[234:235], v[236:237], 0, s[26:27]
	s_addc_u32 s31, s37, 0
	s_add_i32 s36, s60, s42
	global_load_lds_dwordx4 v[234:235], off
	v_lshl_add_u64 v[234:235], s[30:31], 0, v[146:147]
	s_mov_b32 m0, s36
	s_nop 0
	global_load_lds_dwordx4 v[234:235], off
	v_lshl_add_u64 v[234:235], s[30:31], 0, v[144:145]
	s_add_i32 m0, s36, 0x2000
	s_nop 0
	global_load_lds_dwordx4 v[234:235], off
	v_lshl_add_u64 v[234:235], v[238:239], 0, s[26:27]
	s_mov_b32 m0, s50
	s_nop 0
	global_load_lds_dwordx4 v[234:235], off
	v_lshl_add_u64 v[234:235], v[240:241], 0, s[26:27]
	s_mov_b32 m0, s51
	s_nop 0
	global_load_lds_dwordx4 v[234:235], off
	s_waitcnt vmcnt(8)
	s_waitcnt lgkmcnt(0)
	s_barrier
	s_setprio 1
	s_waitcnt lgkmcnt(0)
	v_mfma_f32_16x16x32_bf16 v[60:63], v[92:95], v[192:195], v[60:63]
	v_mfma_f32_16x16x32_bf16 v[56:59], v[104:107], v[192:195], v[56:59]
	v_mfma_f32_16x16x32_bf16 v[44:47], v[92:95], v[200:203], v[44:47]
	v_mfma_f32_16x16x32_bf16 v[40:43], v[104:107], v[200:203], v[40:43]
	v_mfma_f32_16x16x32_bf16 v[28:31], v[92:95], v[208:211], v[28:31]
	v_mfma_f32_16x16x32_bf16 v[24:27], v[104:107], v[208:211], v[24:27]
	v_mfma_f32_16x16x32_bf16 v[12:15], v[92:95], v[226:229], v[12:15]
	v_mfma_f32_16x16x32_bf16 v[8:11], v[104:107], v[226:229], v[8:11]
	v_mfma_f32_16x16x32_bf16 v[60:63], v[100:103], v[196:199], v[60:63]
	v_mfma_f32_16x16x32_bf16 v[56:59], v[172:175], v[196:199], v[56:59]
	v_mfma_f32_16x16x32_bf16 v[44:47], v[100:103], v[204:207], v[44:47]
	v_mfma_f32_16x16x32_bf16 v[40:43], v[172:175], v[204:207], v[40:43]
	v_mfma_f32_16x16x32_bf16 v[28:31], v[100:103], v[222:225], v[28:31]
	v_mfma_f32_16x16x32_bf16 v[24:27], v[172:175], v[222:225], v[24:27]
	v_mfma_f32_16x16x32_bf16 v[12:15], v[100:103], v[230:233], v[12:15]
	v_mfma_f32_16x16x32_bf16 v[8:11], v[172:175], v[230:233], v[8:11]
	v_mfma_f32_16x16x32_bf16 v[52:55], v[176:179], v[192:195], v[52:55]
	v_mfma_f32_16x16x32_bf16 v[48:51], v[184:187], v[192:195], v[48:51]
	v_mfma_f32_16x16x32_bf16 v[36:39], v[176:179], v[200:203], v[36:39]
	v_mfma_f32_16x16x32_bf16 v[32:35], v[184:187], v[200:203], v[32:35]
	v_mfma_f32_16x16x32_bf16 v[20:23], v[176:179], v[208:211], v[20:23]
	v_mfma_f32_16x16x32_bf16 v[16:19], v[184:187], v[208:211], v[16:19]
	v_mfma_f32_16x16x32_bf16 v[4:7], v[176:179], v[226:229], v[4:7]
	v_mfma_f32_16x16x32_bf16 v[0:3], v[184:187], v[226:229], v[0:3]
	v_mfma_f32_16x16x32_bf16 v[52:55], v[180:183], v[196:199], v[52:55]
	v_mfma_f32_16x16x32_bf16 v[48:51], v[188:191], v[196:199], v[48:51]
	v_mfma_f32_16x16x32_bf16 v[36:39], v[180:183], v[204:207], v[36:39]
	v_mfma_f32_16x16x32_bf16 v[32:35], v[188:191], v[204:207], v[32:35]
	v_mfma_f32_16x16x32_bf16 v[20:23], v[180:183], v[222:225], v[20:23]
	v_mfma_f32_16x16x32_bf16 v[16:19], v[188:191], v[222:225], v[16:19]
	v_mfma_f32_16x16x32_bf16 v[4:7], v[180:183], v[230:233], v[4:7]
	v_mfma_f32_16x16x32_bf16 v[0:3], v[188:191], v[230:233], v[0:3]
	s_setprio 0
	s_barrier
	s_add_i32 s66, s66, 2
	s_cmpk_gt_u32 s66, 0x55
	s_mov_b64 s[30:31], s[34:35]
	s_cbranch_scc0 .LBB0_821
	s_and_b64 vcc, exec, s[4:5]
	s_cbranch_vccz .LBB0_824
	s_barrier

; #define PG8_STAGE(bufoff, gbase, voff) do { _Pragma("unroll") for (int _i = 0; _i < 2; ++_i) \
;         __builtin_amdgcn_global_load_lds((const unsigned*)((const char*)(gbase) + (voff)[_i]), (PG8_LAS unsigned*)(lds + (bufoff) + ldsw + _i * 8192), 16, 0, 0); } while (0)
; #define PG8_LDA(dst, b, h) do { _Pragma("unroll") for (int m = 0; m < 4; ++m) _Pragma("unroll") for (int k = 0; k < 2; ++k) dst[m][k] = *(const PG8_LAS bf16x8*)(lds + PG8_SA(b, h) + aoff + m * 2048 + k * 1024); } while (0)
; #define PG8_LDB(dst, b, h) do { _Pragma("unroll") for (int n = 0; n < 2; ++n) _Pragma("unroll") for (int k = 0; k < 2; ++k) dst[n][k] = *(const PG8_LAS bf16x8*)(lds + PG8_SB(b, h) + boff + n * 2048 + k * 1024); } while (0)
; #define PG8_MMA(ai, bj, At, Bt) do { __builtin_amdgcn_s_setprio(1); _Pragma("unroll") for (int m = 0; m < 4; ++m) _Pragma("unroll") for (int n = 0; n < 2; ++n) _Pragma("unroll") for (int k = 0; k < 2; ++k) \
;         acc[ai][bj][m][n] = __builtin_amdgcn_mfma_f32_16x16x32_bf16(Bt[n][k], At[m][k], acc[ai][bj][m][n], 0, 0, 0); __builtin_amdgcn_s_setprio(0); } while (0)
; #define PG8_WAIT_V(n) asm volatile("s_waitcnt vmcnt(" #n ")" ::: "memory")
; #define PG8_WAIT_L(n) asm volatile("s_waitcnt lgkmcnt(" #n ")" ::: "memory")
; template <class Epi, class Sched, bool ALIGN_EPI = false, bool SP2 = false>
; __device__ __forceinline__ void gemm_phase(PG8_LAS unsigned char* lds, const Gemm g, const Sched& S, const Epi& E) {
;     ...
;             const bool last = (t == nt - 2);
;             const char* a1 = cA + (size_t)(t + 1) * kstep;
;             const char* a2 = last ? nA : cA + (size_t)(t + 2) * kstep; const char* b2 = last ? nB : cB + (size_t)(t + 2) * kstep;
;             const char* a3 = a2 + kstep; const char* b3 = b2 + kstep;
;             if (last && has_next) S.a_ready(nxt);
;             if constexpr (SP2) {
;             PG8_LDB(B0, 0, 0); PG8_LDB(B1, 0, 1); PG8_SCHED; PG8_LDA(At, 0, 0); PG8_STAGE(PG8_SA(1, 1), a1 + hstep, voffA);
;             PG8_WAIT_V(8); PG8_WAIT_L(0); PG8_BAR; PG8_MMA(0, 0, At, B0); PG8_MMA(0, 1, At, B1); PG8_BAR; PG8_SCHED;
;             PG8_LDA(At, 0, 1); PG8_STAGE(PG8_SB(0, 0), b2, voffB); PG8_STAGE(PG8_SB(0, 1), b2 + hstep, voffB); PG8_STAGE(PG8_SA(0, 0), a2, voffA);
;             PG8_WAIT_V(8); PG8_WAIT_L(0); PG8_BAR; PG8_MMA(1, 0, At, B0); PG8_MMA(1, 1, At, B1); PG8_BAR; PG8_SCHED;
.LBB0_877:
	ds_read_b128 v[128:131], v165
	ds_read_b128 v[132:135], v165 offset:1024
	ds_read_b128 v[136:139], v165 offset:2048
	ds_read_b128 v[140:143], v165 offset:3072
	ds_read_b128 v[156:159], v166
	ds_read_b128 v[168:171], v166 offset:1024
	ds_read_b128 v[172:175], v166 offset:2048
	ds_read_b128 v[176:179], v166 offset:3072
	s_add_u32 s22, s20, 0x100
	s_addc_u32 s23, s21, 0
	s_cmpk_eq_i32 s53, 0x54
	s_cselect_b32 s27, s9, s23
	s_cselect_b32 s26, s8, s22
	s_cselect_b32 s25, s19, s52
	s_cselect_b32 s24, s18, s51
	v_lshl_add_u64 v[160:161], s[20:21], 0, v[150:151]
	s_add_i32 m0, s35, 0xc000
	ds_read_b128 v[180:183], v167
	ds_read_b128 v[184:187], v167 offset:1024
	ds_read_b128 v[188:191], v167 offset:2048
	ds_read_b128 v[192:195], v167 offset:3072
	ds_read_b128 v[196:199], v167 offset:4096
	ds_read_b128 v[200:203], v167 offset:5120
	ds_read_b128 v[204:207], v167 offset:6144
	ds_read_b128 v[208:211], v167 offset:7168
	global_load_lds_dwordx4 v[160:161], off
	v_lshl_add_u64 v[160:161], s[20:21], 0, v[148:149]
	s_add_i32 m0, s35, 0xe000
	s_nop 0
	global_load_lds_dwordx4 v[160:161], off
	s_waitcnt vmcnt(8)
	s_waitcnt lgkmcnt(0)
	s_barrier
	s_setprio 1
	s_waitcnt lgkmcnt(0)
	v_mfma_f32_16x16x32_bf16 v[124:127], v[128:131], v[180:183], v[124:127]
	v_mfma_f32_16x16x32_bf16 v[120:123], v[136:139], v[180:183], v[120:123]
	v_mfma_f32_16x16x32_bf16 v[116:119], v[128:131], v[188:191], v[116:119]
	v_mfma_f32_16x16x32_bf16 v[112:115], v[136:139], v[188:191], v[112:115]
	v_mfma_f32_16x16x32_bf16 v[92:95], v[128:131], v[196:199], v[92:95]
	v_mfma_f32_16x16x32_bf16 v[88:91], v[136:139], v[196:199], v[88:91]
	v_mfma_f32_16x16x32_bf16 v[84:87], v[128:131], v[204:207], v[84:87]
	v_mfma_f32_16x16x32_bf16 v[80:83], v[136:139], v[204:207], v[80:83]
	v_mfma_f32_16x16x32_bf16 v[124:127], v[132:135], v[184:187], v[124:127]
	v_mfma_f32_16x16x32_bf16 v[120:123], v[140:143], v[184:187], v[120:123]
	v_mfma_f32_16x16x32_bf16 v[116:119], v[132:135], v[192:195], v[116:119]
	v_mfma_f32_16x16x32_bf16 v[112:115], v[140:143], v[192:195], v[112:115]
	v_mfma_f32_16x16x32_bf16 v[92:95], v[132:135], v[200:203], v[92:95]
	v_mfma_f32_16x16x32_bf16 v[88:91], v[140:143], v[200:203], v[88:91]
	v_mfma_f32_16x16x32_bf16 v[84:87], v[132:135], v[208:211], v[84:87]
	v_mfma_f32_16x16x32_bf16 v[80:83], v[140:143], v[208:211], v[80:83]
	v_mfma_f32_16x16x32_bf16 v[108:111], v[156:159], v[180:183], v[108:111]
	v_mfma_f32_16x16x32_bf16 v[104:107], v[172:175], v[180:183], v[104:107]
	v_mfma_f32_16x16x32_bf16 v[100:103], v[156:159], v[188:191], v[100:103]
	v_mfma_f32_16x16x32_bf16 v[96:99], v[172:175], v[188:191], v[96:99]
	v_mfma_f32_16x16x32_bf16 v[76:79], v[156:159], v[196:199], v[76:79]
	v_mfma_f32_16x16x32_bf16 v[72:75], v[172:175], v[196:199], v[72:75]
	v_mfma_f32_16x16x32_bf16 v[68:71], v[156:159], v[204:207], v[68:71]
	v_mfma_f32_16x16x32_bf16 v[64:67], v[172:175], v[204:207], v[64:67]
	v_mfma_f32_16x16x32_bf16 v[108:111], v[168:171], v[184:187], v[108:111]
	v_mfma_f32_16x16x32_bf16 v[104:107], v[176:179], v[184:187], v[104:107]
	v_mfma_f32_16x16x32_bf16 v[100:103], v[168:171], v[192:195], v[100:103]
	v_mfma_f32_16x16x32_bf16 v[96:99], v[176:179], v[192:195], v[96:99]
	v_mfma_f32_16x16x32_bf16 v[76:79], v[168:171], v[200:203], v[76:79]
	v_mfma_f32_16x16x32_bf16 v[72:75], v[176:179], v[200:203], v[72:75]
	v_mfma_f32_16x16x32_bf16 v[68:71], v[168:171], v[208:211], v[68:71]
	v_mfma_f32_16x16x32_bf16 v[64:67], v[176:179], v[208:211], v[64:67]
	s_setprio 0
	s_barrier
	s_add_i32 s20, s44, s34
	v_lshl_add_u64 v[160:161], s[24:25], 0, v[144:145]
	s_mov_b32 m0, s20
	ds_read_b128 v[180:183], v167 offset:16384
	ds_read_b128 v[184:187], v167 offset:17408
	ds_read_b128 v[188:191], v167 offset:18432
	ds_read_b128 v[192:195], v167 offset:19456
	ds_read_b128 v[196:199], v167 offset:20480
	ds_read_b128 v[200:203], v167 offset:21504
	ds_read_b128 v[204:207], v167 offset:22528
	ds_read_b128 v[208:211], v167 offset:23552
	global_load_lds_dwordx4 v[160:161], off
	s_add_i32 m0, s20, 0x2000
	s_add_u32 s20, s24, 0x160000
	v_lshl_add_u64 v[212:213], s[24:25], 0, v[146:147]
	s_addc_u32 s21, s25, 0
	s_add_i32 s54, s45, s34
	global_load_lds_dwordx4 v[212:213], off
	v_lshl_add_u64 v[214:215], s[20:21], 0, v[144:145]
	s_mov_b32 m0, s54
	v_lshl_add_u64 v[216:217], s[26:27], 0, v[146:147]
	global_load_lds_dwordx4 v[214:215], off
	v_lshl_add_u64 v[214:215], s[20:21], 0, v[146:147]
	s_add_i32 m0, s54, 0x2000
	s_nop 0
	global_load_lds_dwordx4 v[214:215], off
	v_lshl_add_u64 v[214:215], s[26:27], 0, v[144:145]
	s_mov_b32 m0, s35
	s_nop 0
	global_load_lds_dwordx4 v[214:215], off
	s_mov_b32 m0, s36
	s_nop 0
	global_load_lds_dwordx4 v[216:217], off
	s_waitcnt vmcnt(8)
	s_waitcnt lgkmcnt(0)
	s_barrier
; #define PG8_STAGE(bufoff, gbase, voff) do { _Pragma("unroll") for (int _i = 0; _i < 2; ++_i) \
;         __builtin_amdgcn_global_load_lds((const unsigned*)((const char*)(gbase) + (voff)[_i]), (PG8_LAS unsigned*)(lds + (bufoff) + ldsw + _i * 8192), 16, 0, 0); } while (0)
; #define PG8_LDA(dst, b, h) do { _Pragma("unroll") for (int m = 0; m < 4; ++m) _Pragma("unroll") for (int k = 0; k < 2; ++k) dst[m][k] = *(const PG8_LAS bf16x8*)(lds + PG8_SA(b, h) + aoff + m * 2048 + k * 1024); } while (0)
; #define PG8_LDB(dst, b, h) do { _Pragma("unroll") for (int n = 0; n < 2; ++n) _Pragma("unroll") for (int k = 0; k < 2; ++k) dst[n][k] = *(const PG8_LAS bf16x8*)(lds + PG8_SB(b, h) + boff + n * 2048 + k * 1024); } while (0)
; #define PG8_MMA(ai, bj, At, Bt) do { __builtin_amdgcn_s_setprio(1); _Pragma("unroll") for (int m = 0; m < 4; ++m) _Pragma("unroll") for (int n = 0; n < 2; ++n) _Pragma("unroll") for (int k = 0; k < 2; ++k) \
;         acc[ai][bj][m][n] = __builtin_amdgcn_mfma_f32_16x16x32_bf16(Bt[n][k], At[m][k], acc[ai][bj][m][n], 0, 0, 0); __builtin_amdgcn_s_setprio(0); } while (0)
; #define PG8_WAIT_V(n) asm volatile("s_waitcnt vmcnt(" #n ")" ::: "memory")
; #define PG8_WAIT_L(n) asm volatile("s_waitcnt lgkmcnt(" #n ")" ::: "memory")
; #define PG8_BAR __builtin_amdgcn_s_barrier()
; #define PG8_SCHED __builtin_amdgcn_sched_barrier(0)
; template <class Epi, class Sched, bool ALIGN_EPI = false, bool SP2 = false>
; __device__ __forceinline__ void gemm_phase(PG8_LAS unsigned char* lds, const Gemm g, const Sched& S, const Epi& E) {
;     ...
;             PG8_LDB(B0, 0, 0); PG8_LDB(B1, 0, 1); PG8_SCHED; PG8_LDA(At, 0, 0); PG8_STAGE(PG8_SA(1, 1), a1 + hstep, voffA);
;             PG8_WAIT_V(8); PG8_WAIT_L(0); PG8_BAR; PG8_MMA(0, 0, At, B0); PG8_MMA(0, 1, At, B1); PG8_BAR; PG8_SCHED;
;             PG8_LDA(At, 0, 1); PG8_STAGE(PG8_SB(0, 0), b2, voffB); PG8_STAGE(PG8_SB(0, 1), b2 + hstep, voffB); PG8_STAGE(PG8_SA(0, 0), a2, voffA);
;             PG8_WAIT_V(8); PG8_WAIT_L(0); PG8_BAR; PG8_MMA(1, 0, At, B0); PG8_MMA(1, 1, At, B1); PG8_BAR; PG8_SCHED;
;             PG8_LDB(B0, 1, 0); PG8_LDB(B1, 1, 1); PG8_SCHED; PG8_LDA(At, 1, 0); PG8_STAGE(PG8_SA(0, 1), a2 + hstep, voffA);
;             PG8_WAIT_V(8); PG8_WAIT_L(0); PG8_BAR; PG8_MMA(0, 0, At, B0); PG8_MMA(0, 1, At, B1); PG8_BAR; PG8_SCHED;
	s_setprio 1
	s_waitcnt lgkmcnt(0)
	v_mfma_f32_16x16x32_bf16 v[60:63], v[128:131], v[180:183], v[60:63]
	v_mfma_f32_16x16x32_bf16 v[56:59], v[136:139], v[180:183], v[56:59]
	v_mfma_f32_16x16x32_bf16 v[52:55], v[128:131], v[188:191], v[52:55]
	v_mfma_f32_16x16x32_bf16 v[48:51], v[136:139], v[188:191], v[48:51]
	v_mfma_f32_16x16x32_bf16 v[36:39], v[128:131], v[196:199], v[36:39]
	v_mfma_f32_16x16x32_bf16 v[24:27], v[136:139], v[196:199], v[24:27]
	v_mfma_f32_16x16x32_bf16 v[16:19], v[128:131], v[204:207], v[16:19]
	v_mfma_f32_16x16x32_bf16 v[8:11], v[136:139], v[204:207], v[8:11]
	v_mfma_f32_16x16x32_bf16 v[60:63], v[132:135], v[184:187], v[60:63]
	v_mfma_f32_16x16x32_bf16 v[56:59], v[140:143], v[184:187], v[56:59]
	v_mfma_f32_16x16x32_bf16 v[52:55], v[132:135], v[192:195], v[52:55]
	v_mfma_f32_16x16x32_bf16 v[48:51], v[140:143], v[192:195], v[48:51]
	v_mfma_f32_16x16x32_bf16 v[36:39], v[132:135], v[200:203], v[36:39]
	v_mfma_f32_16x16x32_bf16 v[24:27], v[140:143], v[200:203], v[24:27]
	v_mfma_f32_16x16x32_bf16 v[16:19], v[132:135], v[208:211], v[16:19]
	v_mfma_f32_16x16x32_bf16 v[8:11], v[140:143], v[208:211], v[8:11]
	v_mfma_f32_16x16x32_bf16 v[44:47], v[156:159], v[180:183], v[44:47]
	v_mfma_f32_16x16x32_bf16 v[40:43], v[172:175], v[180:183], v[40:43]
	v_mfma_f32_16x16x32_bf16 v[32:35], v[156:159], v[188:191], v[32:35]
	v_mfma_f32_16x16x32_bf16 v[28:31], v[172:175], v[188:191], v[28:31]
	v_mfma_f32_16x16x32_bf16 v[20:23], v[156:159], v[196:199], v[20:23]
	v_mfma_f32_16x16x32_bf16 v[12:15], v[172:175], v[196:199], v[12:15]
	v_mfma_f32_16x16x32_bf16 v[4:7], v[156:159], v[204:207], v[4:7]
	v_mfma_f32_16x16x32_bf16 v[0:3], v[172:175], v[204:207], v[0:3]
	v_mfma_f32_16x16x32_bf16 v[44:47], v[168:171], v[184:187], v[44:47]
	v_mfma_f32_16x16x32_bf16 v[40:43], v[176:179], v[184:187], v[40:43]
	v_mfma_f32_16x16x32_bf16 v[32:35], v[168:171], v[192:195], v[32:35]
	v_mfma_f32_16x16x32_bf16 v[28:31], v[176:179], v[192:195], v[28:31]
	v_mfma_f32_16x16x32_bf16 v[20:23], v[168:171], v[200:203], v[20:23]
	v_mfma_f32_16x16x32_bf16 v[12:15], v[176:179], v[200:203], v[12:15]
	v_mfma_f32_16x16x32_bf16 v[4:7], v[168:171], v[208:211], v[4:7]
	v_mfma_f32_16x16x32_bf16 v[0:3], v[176:179], v[208:211], v[0:3]
	s_setprio 0
	s_barrier
	s_add_i32 s54, 0, 0x18000
	s_add_i32 s55, 0, 0x1c000
	v_add_u32_e32 v140, s54, v163
	v_add_u32_e32 v176, s55, v163
	ds_read_b128 v[128:131], v140
	ds_read_b128 v[132:135], v140 offset:1024
	ds_read_b128 v[136:139], v140 offset:2048
	ds_read_b128 v[140:143], v140 offset:3072
	ds_read_b128 v[156:159], v176
	ds_read_b128 v[168:171], v176 offset:1024
	ds_read_b128 v[172:175], v176 offset:2048
	ds_read_b128 v[176:179], v176 offset:3072
	s_add_u32 s20, s26, 0x160000
	s_addc_u32 s21, s27, 0
	s_mov_b32 m0, s37
	v_lshl_add_u64 v[218:219], s[20:21], 0, v[144:145]
	ds_read_b128 v[180:183], v167 offset:32768
	ds_read_b128 v[184:187], v167 offset:33792
	ds_read_b128 v[188:191], v167 offset:34816
	ds_read_b128 v[192:195], v167 offset:35840
	ds_read_b128 v[196:199], v167 offset:36864
	ds_read_b128 v[200:203], v167 offset:37888
	ds_read_b128 v[204:207], v167 offset:38912
	ds_read_b128 v[208:211], v167 offset:39936
	global_load_lds_dwordx4 v[218:219], off
	v_lshl_add_u64 v[218:219], s[20:21], 0, v[146:147]
	s_mov_b32 m0, s38
	s_nop 0
	global_load_lds_dwordx4 v[218:219], off
	s_waitcnt vmcnt(8)
	s_waitcnt lgkmcnt(0)
	s_barrier
	s_setprio 1
	s_waitcnt lgkmcnt(0)
	v_mfma_f32_16x16x32_bf16 v[124:127], v[128:131], v[180:183], v[124:127]
	v_mfma_f32_16x16x32_bf16 v[120:123], v[136:139], v[180:183], v[120:123]
	v_mfma_f32_16x16x32_bf16 v[116:119], v[128:131], v[188:191], v[116:119]
	v_mfma_f32_16x16x32_bf16 v[112:115], v[136:139], v[188:191], v[112:115]
	v_mfma_f32_16x16x32_bf16 v[92:95], v[128:131], v[196:199], v[92:95]
	v_mfma_f32_16x16x32_bf16 v[88:91], v[136:139], v[196:199], v[88:91]
	v_mfma_f32_16x16x32_bf16 v[84:87], v[128:131], v[204:207], v[84:87]
	v_mfma_f32_16x16x32_bf16 v[80:83], v[136:139], v[204:207], v[80:83]
	v_mfma_f32_16x16x32_bf16 v[124:127], v[132:135], v[184:187], v[124:127]
	v_mfma_f32_16x16x32_bf16 v[120:123], v[140:143], v[184:187], v[120:123]
	v_mfma_f32_16x16x32_bf16 v[116:119], v[132:135], v[192:195], v[116:119]
	v_mfma_f32_16x16x32_bf16 v[112:115], v[140:143], v[192:195], v[112:115]
	v_mfma_f32_16x16x32_bf16 v[92:95], v[132:135], v[200:203], v[92:95]
	v_mfma_f32_16x16x32_bf16 v[88:91], v[140:143], v[200:203], v[88:91]
	v_mfma_f32_16x16x32_bf16 v[84:87], v[132:135], v[208:211], v[84:87]
	v_mfma_f32_16x16x32_bf16 v[80:83], v[140:143], v[208:211], v[80:83]
	v_mfma_f32_16x16x32_bf16 v[108:111], v[156:159], v[180:183], v[108:111]
	v_mfma_f32_16x16x32_bf16 v[104:107], v[172:175], v[180:183], v[104:107]
	v_mfma_f32_16x16x32_bf16 v[100:103], v[156:159], v[188:191], v[100:103]
	v_mfma_f32_16x16x32_bf16 v[96:99], v[172:175], v[188:191], v[96:99]
	v_mfma_f32_16x16x32_bf16 v[76:79], v[156:159], v[196:199], v[76:79]
	v_mfma_f32_16x16x32_bf16 v[72:75], v[172:175], v[196:199], v[72:75]
	v_mfma_f32_16x16x32_bf16 v[68:71], v[156:159], v[204:207], v[68:71]
	v_mfma_f32_16x16x32_bf16 v[64:67], v[172:175], v[204:207], v[64:67]
	v_mfma_f32_16x16x32_bf16 v[108:111], v[168:171], v[184:187], v[108:111]
	v_mfma_f32_16x16x32_bf16 v[104:107], v[176:179], v[184:187], v[104:107]
	v_mfma_f32_16x16x32_bf16 v[100:103], v[168:171], v[192:195], v[100:103]
	v_mfma_f32_16x16x32_bf16 v[96:99], v[176:179], v[192:195], v[96:99]
	v_mfma_f32_16x16x32_bf16 v[76:79], v[168:171], v[200:203], v[76:79]
	v_mfma_f32_16x16x32_bf16 v[72:75], v[176:179], v[200:203], v[72:75]
	v_mfma_f32_16x16x32_bf16 v[68:71], v[168:171], v[208:211], v[68:71]
	v_mfma_f32_16x16x32_bf16 v[64:67], v[176:179], v[208:211], v[64:67]
	s_setprio 0
	s_barrier
; #define PG8_STAGE(bufoff, gbase, voff) do { _Pragma("unroll") for (int _i = 0; _i < 2; ++_i) \
;         __builtin_amdgcn_global_load_lds((const unsigned*)((const char*)(gbase) + (voff)[_i]), (PG8_LAS unsigned*)(lds + (bufoff) + ldsw + _i * 8192), 16, 0, 0); } while (0)
; #define PG8_LDA(dst, b, h) do { _Pragma("unroll") for (int m = 0; m < 4; ++m) _Pragma("unroll") for (int k = 0; k < 2; ++k) dst[m][k] = *(const PG8_LAS bf16x8*)(lds + PG8_SA(b, h) + aoff + m * 2048 + k * 1024); } while (0)
; #define PG8_MMA(ai, bj, At, Bt) do { __builtin_amdgcn_s_setprio(1); _Pragma("unroll") for (int m = 0; m < 4; ++m) _Pragma("unroll") for (int n = 0; n < 2; ++n) _Pragma("unroll") for (int k = 0; k < 2; ++k) \
;         acc[ai][bj][m][n] = __builtin_amdgcn_mfma_f32_16x16x32_bf16(Bt[n][k], At[m][k], acc[ai][bj][m][n], 0, 0, 0); __builtin_amdgcn_s_setprio(0); } while (0)
; #define PG8_WAIT_V(n) asm volatile("s_waitcnt vmcnt(" #n ")" ::: "memory")
; #define PG8_WAIT_L(n) asm volatile("s_waitcnt lgkmcnt(" #n ")" ::: "memory")
; #define PG8_BAR __builtin_amdgcn_s_barrier()
; #define PG8_SCHED __builtin_amdgcn_sched_barrier(0)
; template <class Epi, class Sched, bool ALIGN_EPI = false, bool SP2 = false>
; __device__ __forceinline__ void gemm_phase(PG8_LAS unsigned char* lds, const Gemm g, const Sched& S, const Epi& E) {
;     ...
;         for (int t = 0; t < nt; t += 2) {
;     ...
;             PG8_LDA(At, 1, 1); PG8_STAGE(PG8_SB(1, 0), b3, voffB); PG8_STAGE(PG8_SB(1, 1), b3 + hstep, voffB); PG8_STAGE(PG8_SA(1, 0), a3, voffA);
;             PG8_WAIT_V(8); PG8_WAIT_L(0); PG8_BAR; PG8_MMA(1, 0, At, B0); PG8_MMA(1, 1, At, B1); PG8_BAR; PG8_SCHED;
	s_add_i32 s20, s54, s34
	v_lshl_add_u64 v[160:161], v[160:161], 0, s[10:11]
	s_mov_b32 m0, s20
	ds_read_b128 v[180:183], v167 offset:49152
	ds_read_b128 v[184:187], v167 offset:50176
	ds_read_b128 v[188:191], v167 offset:51200
	ds_read_b128 v[192:195], v167 offset:52224
	ds_read_b128 v[196:199], v167 offset:53248
	ds_read_b128 v[200:203], v167 offset:54272
	ds_read_b128 v[204:207], v167 offset:55296
	ds_read_b128 v[208:211], v167 offset:56320
	global_load_lds_dwordx4 v[160:161], off
	s_add_i32 m0, s20, 0x2000
	s_add_u32 s20, s24, 0x160080
	v_lshl_add_u64 v[160:161], v[212:213], 0, s[10:11]
	s_addc_u32 s21, s25, 0
	s_add_i32 s24, s55, s34
	global_load_lds_dwordx4 v[160:161], off
	v_lshl_add_u64 v[160:161], s[20:21], 0, v[144:145]
	s_mov_b32 m0, s24
	s_nop 0
	global_load_lds_dwordx4 v[160:161], off
	v_lshl_add_u64 v[160:161], s[20:21], 0, v[146:147]
	s_add_i32 m0, s24, 0x2000
	s_nop 0
	global_load_lds_dwordx4 v[160:161], off
	v_lshl_add_u64 v[160:161], v[214:215], 0, s[10:11]
	s_mov_b32 m0, s42
	s_nop 0
	global_load_lds_dwordx4 v[160:161], off
	v_lshl_add_u64 v[160:161], v[216:217], 0, s[10:11]
	s_mov_b32 m0, s43
	s_nop 0
	global_load_lds_dwordx4 v[160:161], off
	s_waitcnt vmcnt(8)
	s_waitcnt lgkmcnt(0)
	s_barrier
	s_setprio 1
	s_waitcnt lgkmcnt(0)
	v_mfma_f32_16x16x32_bf16 v[60:63], v[128:131], v[180:183], v[60:63]
	v_mfma_f32_16x16x32_bf16 v[56:59], v[136:139], v[180:183], v[56:59]
	v_mfma_f32_16x16x32_bf16 v[52:55], v[128:131], v[188:191], v[52:55]
	v_mfma_f32_16x16x32_bf16 v[48:51], v[136:139], v[188:191], v[48:51]
	v_mfma_f32_16x16x32_bf16 v[36:39], v[128:131], v[196:199], v[36:39]
	v_mfma_f32_16x16x32_bf16 v[24:27], v[136:139], v[196:199], v[24:27]
	v_mfma_f32_16x16x32_bf16 v[16:19], v[128:131], v[204:207], v[16:19]
	v_mfma_f32_16x16x32_bf16 v[8:11], v[136:139], v[204:207], v[8:11]
	v_mfma_f32_16x16x32_bf16 v[60:63], v[132:135], v[184:187], v[60:63]
	v_mfma_f32_16x16x32_bf16 v[56:59], v[140:143], v[184:187], v[56:59]
	v_mfma_f32_16x16x32_bf16 v[52:55], v[132:135], v[192:195], v[52:55]
	v_mfma_f32_16x16x32_bf16 v[48:51], v[140:143], v[192:195], v[48:51]
	v_mfma_f32_16x16x32_bf16 v[36:39], v[132:135], v[200:203], v[36:39]
	v_mfma_f32_16x16x32_bf16 v[24:27], v[140:143], v[200:203], v[24:27]
	v_mfma_f32_16x16x32_bf16 v[16:19], v[132:135], v[208:211], v[16:19]
	v_mfma_f32_16x16x32_bf16 v[8:11], v[140:143], v[208:211], v[8:11]
	v_mfma_f32_16x16x32_bf16 v[44:47], v[156:159], v[180:183], v[44:47]
	v_mfma_f32_16x16x32_bf16 v[40:43], v[172:175], v[180:183], v[40:43]
	v_mfma_f32_16x16x32_bf16 v[32:35], v[156:159], v[188:191], v[32:35]
	v_mfma_f32_16x16x32_bf16 v[28:31], v[172:175], v[188:191], v[28:31]
	v_mfma_f32_16x16x32_bf16 v[20:23], v[156:159], v[196:199], v[20:23]
	v_mfma_f32_16x16x32_bf16 v[12:15], v[172:175], v[196:199], v[12:15]
	v_mfma_f32_16x16x32_bf16 v[4:7], v[156:159], v[204:207], v[4:7]
	v_mfma_f32_16x16x32_bf16 v[0:3], v[172:175], v[204:207], v[0:3]
	v_mfma_f32_16x16x32_bf16 v[44:47], v[168:171], v[184:187], v[44:47]
	v_mfma_f32_16x16x32_bf16 v[40:43], v[176:179], v[184:187], v[40:43]
	v_mfma_f32_16x16x32_bf16 v[32:35], v[168:171], v[192:195], v[32:35]
	v_mfma_f32_16x16x32_bf16 v[28:31], v[176:179], v[192:195], v[28:31]
	v_mfma_f32_16x16x32_bf16 v[20:23], v[168:171], v[200:203], v[20:23]
	v_mfma_f32_16x16x32_bf16 v[12:15], v[176:179], v[200:203], v[12:15]
	v_mfma_f32_16x16x32_bf16 v[4:7], v[168:171], v[208:211], v[4:7]
	v_mfma_f32_16x16x32_bf16 v[0:3], v[176:179], v[208:211], v[0:3]
	s_setprio 0
	s_barrier
	s_add_i32 s53, s53, 2
	s_add_u32 s51, s51, 0x100
	s_addc_u32 s52, s52, 0
	s_cmpk_gt_u32 s53, 0x55
	s_mov_b64 s[20:21], s[22:23]
	s_cbranch_scc0 .LBB0_877
	s_and_b64 vcc, exec, s[14:15]
	s_cbranch_vccz .LBB0_880
	s_barrier

; #define PG8_STAGE(bufoff, gbase, voff) do { _Pragma("unroll") for (int _i = 0; _i < 2; ++_i) \
;         __builtin_amdgcn_global_load_lds((const unsigned*)((const char*)(gbase) + (voff)[_i]), (PG8_LAS unsigned*)(lds + (bufoff) + ldsw + _i * 8192), 16, 0, 0); } while (0)
; #define PG8_LDA(dst, b, h) do { _Pragma("unroll") for (int m = 0; m < 4; ++m) _Pragma("unroll") for (int k = 0; k < 2; ++k) dst[m][k] = *(const PG8_LAS bf16x8*)(lds + PG8_SA(b, h) + aoff + m * 2048 + k * 1024); } while (0)
; #define PG8_LDB(dst, b, h) do { _Pragma("unroll") for (int n = 0; n < 2; ++n) _Pragma("unroll") for (int k = 0; k < 2; ++k) dst[n][k] = *(const PG8_LAS bf16x8*)(lds + PG8_SB(b, h) + boff + n * 2048 + k * 1024); } while (0)
; #define PG8_MMA(ai, bj, At, Bt) do { __builtin_amdgcn_s_setprio(1); _Pragma("unroll") for (int m = 0; m < 4; ++m) _Pragma("unroll") for (int n = 0; n < 2; ++n) _Pragma("unroll") for (int k = 0; k < 2; ++k) \
;         acc[ai][bj][m][n] = __builtin_amdgcn_mfma_f32_16x16x32_bf16(Bt[n][k], At[m][k], acc[ai][bj][m][n], 0, 0, 0); __builtin_amdgcn_s_setprio(0); } while (0)
; #define PG8_WAIT_V(n) asm volatile("s_waitcnt vmcnt(" #n ")" ::: "memory")
; #define PG8_WAIT_L(n) asm volatile("s_waitcnt lgkmcnt(" #n ")" ::: "memory")
; #define PG8_BAR __builtin_amdgcn_s_barrier()
; #define PG8_SCHED __builtin_amdgcn_sched_barrier(0)
; template <class Epi, class Sched, bool ALIGN_EPI = false, bool SP2 = false>
; __device__ __forceinline__ void gemm_phase(PG8_LAS unsigned char* lds, const Gemm g, const Sched& S, const Epi& E) {
;     ...
;             PG8_LDB(B0, 0, 0); PG8_LDB(B1, 0, 1); PG8_SCHED; PG8_LDA(At, 0, 0); PG8_STAGE(PG8_SA(1, 1), a1 + hstep, voffA);
;             PG8_WAIT_V(8); PG8_WAIT_L(0); PG8_BAR; PG8_MMA(0, 0, At, B0); PG8_MMA(0, 1, At, B1); PG8_BAR; PG8_SCHED;
;             PG8_LDA(At, 0, 1); PG8_STAGE(PG8_SB(0, 0), b2, voffB); PG8_STAGE(PG8_SB(0, 1), b2 + hstep, voffB); PG8_STAGE(PG8_SA(0, 0), a2, voffA);
;             PG8_WAIT_V(8); PG8_WAIT_L(0); PG8_BAR; PG8_MMA(1, 0, At, B0); PG8_MMA(1, 1, At, B1); PG8_BAR; PG8_SCHED;
.LBB0_1027:
	ds_read_b128 v[144:147], v155
	ds_read_b128 v[148:151], v155 offset:1024
	ds_read_b128 v[158:161], v155 offset:2048
	ds_read_b128 v[162:165], v155 offset:3072
	ds_read_b128 v[166:169], v156
	ds_read_b128 v[170:173], v156 offset:1024
	ds_read_b128 v[174:177], v156 offset:2048
	ds_read_b128 v[178:181], v156 offset:3072
	s_add_u32 s52, s50, 0xfff80080
	s_addc_u32 s53, s51, -1
	s_cmp_eq_u32 s71, 28
	s_cselect_b32 s55, s45, s53
	s_cselect_b32 s54, s67, s52
	s_cselect_b32 s53, s43, s70
	s_cselect_b32 s52, s68, s69
	v_lshl_add_u64 v[214:215], s[50:51], 0, v[136:137]
	s_add_i32 m0, s29, 0xc000
	ds_read_b128 v[182:185], v157
	ds_read_b128 v[186:189], v157 offset:1024
	ds_read_b128 v[190:193], v157 offset:2048
	ds_read_b128 v[194:197], v157 offset:3072
	ds_read_b128 v[198:201], v157 offset:4096
	ds_read_b128 v[202:205], v157 offset:5120
	ds_read_b128 v[206:209], v157 offset:6144
	ds_read_b128 v[210:213], v157 offset:7168
	global_load_lds_dwordx4 v[214:215], off
	v_lshl_add_u64 v[214:215], s[50:51], 0, v[138:139]
	s_add_i32 m0, s29, 0xe000
	s_nop 0
	global_load_lds_dwordx4 v[214:215], off
	s_waitcnt vmcnt(8)
	s_waitcnt lgkmcnt(0)
	s_barrier
	s_setprio 1
	s_waitcnt lgkmcnt(0)
	v_mfma_f32_16x16x32_bf16 v[124:127], v[144:147], v[182:185], v[124:127]
	v_mfma_f32_16x16x32_bf16 v[120:123], v[158:161], v[182:185], v[120:123]
	v_mfma_f32_16x16x32_bf16 v[108:111], v[144:147], v[190:193], v[108:111]
	v_mfma_f32_16x16x32_bf16 v[104:107], v[158:161], v[190:193], v[104:107]
	v_mfma_f32_16x16x32_bf16 v[92:95], v[144:147], v[198:201], v[92:95]
	v_mfma_f32_16x16x32_bf16 v[88:91], v[158:161], v[198:201], v[88:91]
	v_mfma_f32_16x16x32_bf16 v[76:79], v[144:147], v[206:209], v[76:79]
	v_mfma_f32_16x16x32_bf16 v[72:75], v[158:161], v[206:209], v[72:75]
	v_mfma_f32_16x16x32_bf16 v[124:127], v[148:151], v[186:189], v[124:127]
	v_mfma_f32_16x16x32_bf16 v[120:123], v[162:165], v[186:189], v[120:123]
	v_mfma_f32_16x16x32_bf16 v[108:111], v[148:151], v[194:197], v[108:111]
	v_mfma_f32_16x16x32_bf16 v[104:107], v[162:165], v[194:197], v[104:107]
	v_mfma_f32_16x16x32_bf16 v[92:95], v[148:151], v[202:205], v[92:95]
	v_mfma_f32_16x16x32_bf16 v[88:91], v[162:165], v[202:205], v[88:91]
	v_mfma_f32_16x16x32_bf16 v[76:79], v[148:151], v[210:213], v[76:79]
	v_mfma_f32_16x16x32_bf16 v[72:75], v[162:165], v[210:213], v[72:75]
	v_mfma_f32_16x16x32_bf16 v[116:119], v[166:169], v[182:185], v[116:119]
	v_mfma_f32_16x16x32_bf16 v[112:115], v[174:177], v[182:185], v[112:115]
	v_mfma_f32_16x16x32_bf16 v[100:103], v[166:169], v[190:193], v[100:103]
	v_mfma_f32_16x16x32_bf16 v[96:99], v[174:177], v[190:193], v[96:99]
	v_mfma_f32_16x16x32_bf16 v[84:87], v[166:169], v[198:201], v[84:87]
	v_mfma_f32_16x16x32_bf16 v[80:83], v[174:177], v[198:201], v[80:83]
	v_mfma_f32_16x16x32_bf16 v[68:71], v[166:169], v[206:209], v[68:71]
	v_mfma_f32_16x16x32_bf16 v[64:67], v[174:177], v[206:209], v[64:67]
	v_mfma_f32_16x16x32_bf16 v[116:119], v[170:173], v[186:189], v[116:119]
	v_mfma_f32_16x16x32_bf16 v[112:115], v[178:181], v[186:189], v[112:115]
	v_mfma_f32_16x16x32_bf16 v[100:103], v[170:173], v[194:197], v[100:103]
	v_mfma_f32_16x16x32_bf16 v[96:99], v[178:181], v[194:197], v[96:99]
	v_mfma_f32_16x16x32_bf16 v[84:87], v[170:173], v[202:205], v[84:87]
	v_mfma_f32_16x16x32_bf16 v[80:83], v[178:181], v[202:205], v[80:83]
	v_mfma_f32_16x16x32_bf16 v[68:71], v[170:173], v[210:213], v[68:71]
	v_mfma_f32_16x16x32_bf16 v[64:67], v[178:181], v[210:213], v[64:67]
	s_setprio 0
	s_barrier
	s_add_i32 s72, s61, s27
	v_lshl_add_u64 v[214:215], s[52:53], 0, v[132:133]
	s_mov_b32 m0, s72
	ds_read_b128 v[182:185], v157 offset:16384
	ds_read_b128 v[186:189], v157 offset:17408
	ds_read_b128 v[190:193], v157 offset:18432
	ds_read_b128 v[194:197], v157 offset:19456
	ds_read_b128 v[198:201], v157 offset:20480
	ds_read_b128 v[202:205], v157 offset:21504
	ds_read_b128 v[206:209], v157 offset:22528
	ds_read_b128 v[210:213], v157 offset:23552
	global_load_lds_dwordx4 v[214:215], off
	s_add_i32 m0, s72, 0x2000
	s_add_u32 s72, s52, 0x80000
	v_lshl_add_u64 v[216:217], s[52:53], 0, v[128:129]
	s_addc_u32 s73, s53, 0
	s_add_i32 s76, s62, s27
	global_load_lds_dwordx4 v[216:217], off
	v_lshl_add_u64 v[218:219], s[72:73], 0, v[132:133]
	s_mov_b32 m0, s76
	v_lshl_add_u64 v[222:223], s[54:55], 0, v[130:131]
	global_load_lds_dwordx4 v[218:219], off
	v_lshl_add_u64 v[218:219], s[72:73], 0, v[128:129]
	s_add_i32 m0, s76, 0x2000
	s_nop 0
	global_load_lds_dwordx4 v[218:219], off
	v_lshl_add_u64 v[218:219], s[54:55], 0, v[134:135]
	s_mov_b32 m0, s29
	s_nop 0
	global_load_lds_dwordx4 v[218:219], off
	s_mov_b32 m0, s31
	s_nop 0
	global_load_lds_dwordx4 v[222:223], off
	s_waitcnt vmcnt(8)
	s_waitcnt lgkmcnt(0)
	s_barrier
; #define PG8_STAGE(bufoff, gbase, voff) do { _Pragma("unroll") for (int _i = 0; _i < 2; ++_i) \
;         __builtin_amdgcn_global_load_lds((const unsigned*)((const char*)(gbase) + (voff)[_i]), (PG8_LAS unsigned*)(lds + (bufoff) + ldsw + _i * 8192), 16, 0, 0); } while (0)
; #define PG8_LDA(dst, b, h) do { _Pragma("unroll") for (int m = 0; m < 4; ++m) _Pragma("unroll") for (int k = 0; k < 2; ++k) dst[m][k] = *(const PG8_LAS bf16x8*)(lds + PG8_SA(b, h) + aoff + m * 2048 + k * 1024); } while (0)
; #define PG8_LDB(dst, b, h) do { _Pragma("unroll") for (int n = 0; n < 2; ++n) _Pragma("unroll") for (int k = 0; k < 2; ++k) dst[n][k] = *(const PG8_LAS bf16x8*)(lds + PG8_SB(b, h) + boff + n * 2048 + k * 1024); } while (0)
; #define PG8_MMA(ai, bj, At, Bt) do { __builtin_amdgcn_s_setprio(1); _Pragma("unroll") for (int m = 0; m < 4; ++m) _Pragma("unroll") for (int n = 0; n < 2; ++n) _Pragma("unroll") for (int k = 0; k < 2; ++k) \
;         acc[ai][bj][m][n] = __builtin_amdgcn_mfma_f32_16x16x32_bf16(Bt[n][k], At[m][k], acc[ai][bj][m][n], 0, 0, 0); __builtin_amdgcn_s_setprio(0); } while (0)
; #define PG8_WAIT_V(n) asm volatile("s_waitcnt vmcnt(" #n ")" ::: "memory")
; #define PG8_WAIT_L(n) asm volatile("s_waitcnt lgkmcnt(" #n ")" ::: "memory")
; #define PG8_BAR __builtin_amdgcn_s_barrier()
; #define PG8_SCHED __builtin_amdgcn_sched_barrier(0)
; template <class Epi, class Sched, bool ALIGN_EPI = false, bool SP2 = false>
; __device__ __forceinline__ void gemm_phase(PG8_LAS unsigned char* lds, const Gemm g, const Sched& S, const Epi& E) {
;     ...
;             PG8_WAIT_V(8); PG8_WAIT_L(0); PG8_BAR; PG8_MMA(1, 0, At, B0); PG8_MMA(1, 1, At, B1); PG8_BAR; PG8_SCHED;
;             PG8_LDB(B0, 1, 0); PG8_LDB(B1, 1, 1); PG8_SCHED; PG8_LDA(At, 1, 0); PG8_STAGE(PG8_SA(0, 1), a2 + hstep, voffA);
;             PG8_WAIT_V(8); PG8_WAIT_L(0); PG8_BAR; PG8_MMA(0, 0, At, B0); PG8_MMA(0, 1, At, B1); PG8_BAR; PG8_SCHED;
	s_setprio 1
	s_waitcnt lgkmcnt(0)
	v_mfma_f32_16x16x32_bf16 v[60:63], v[144:147], v[182:185], v[60:63]
	v_mfma_f32_16x16x32_bf16 v[56:59], v[158:161], v[182:185], v[56:59]
	v_mfma_f32_16x16x32_bf16 v[44:47], v[144:147], v[190:193], v[44:47]
	v_mfma_f32_16x16x32_bf16 v[40:43], v[158:161], v[190:193], v[40:43]
	v_mfma_f32_16x16x32_bf16 v[28:31], v[144:147], v[198:201], v[28:31]
	v_mfma_f32_16x16x32_bf16 v[24:27], v[158:161], v[198:201], v[24:27]
	v_mfma_f32_16x16x32_bf16 v[12:15], v[144:147], v[206:209], v[12:15]
	v_mfma_f32_16x16x32_bf16 v[8:11], v[158:161], v[206:209], v[8:11]
	v_mfma_f32_16x16x32_bf16 v[60:63], v[148:151], v[186:189], v[60:63]
	v_mfma_f32_16x16x32_bf16 v[56:59], v[162:165], v[186:189], v[56:59]
	v_mfma_f32_16x16x32_bf16 v[44:47], v[148:151], v[194:197], v[44:47]
	v_mfma_f32_16x16x32_bf16 v[40:43], v[162:165], v[194:197], v[40:43]
	v_mfma_f32_16x16x32_bf16 v[28:31], v[148:151], v[202:205], v[28:31]
	v_mfma_f32_16x16x32_bf16 v[24:27], v[162:165], v[202:205], v[24:27]
	v_mfma_f32_16x16x32_bf16 v[12:15], v[148:151], v[210:213], v[12:15]
	v_mfma_f32_16x16x32_bf16 v[8:11], v[162:165], v[210:213], v[8:11]
	v_mfma_f32_16x16x32_bf16 v[52:55], v[166:169], v[182:185], v[52:55]
	v_mfma_f32_16x16x32_bf16 v[48:51], v[174:177], v[182:185], v[48:51]
	v_mfma_f32_16x16x32_bf16 v[36:39], v[166:169], v[190:193], v[36:39]
	v_mfma_f32_16x16x32_bf16 v[32:35], v[174:177], v[190:193], v[32:35]
	v_mfma_f32_16x16x32_bf16 v[20:23], v[166:169], v[198:201], v[20:23]
	v_mfma_f32_16x16x32_bf16 v[16:19], v[174:177], v[198:201], v[16:19]
	v_mfma_f32_16x16x32_bf16 v[4:7], v[166:169], v[206:209], v[4:7]
	v_mfma_f32_16x16x32_bf16 v[0:3], v[174:177], v[206:209], v[0:3]
	v_mfma_f32_16x16x32_bf16 v[52:55], v[170:173], v[186:189], v[52:55]
	v_mfma_f32_16x16x32_bf16 v[48:51], v[178:181], v[186:189], v[48:51]
	v_mfma_f32_16x16x32_bf16 v[36:39], v[170:173], v[194:197], v[36:39]
	v_mfma_f32_16x16x32_bf16 v[32:35], v[178:181], v[194:197], v[32:35]
	v_mfma_f32_16x16x32_bf16 v[20:23], v[170:173], v[202:205], v[20:23]
	v_mfma_f32_16x16x32_bf16 v[16:19], v[178:181], v[202:205], v[16:19]
	v_mfma_f32_16x16x32_bf16 v[4:7], v[170:173], v[210:213], v[4:7]
	v_mfma_f32_16x16x32_bf16 v[0:3], v[178:181], v[210:213], v[0:3]
	s_setprio 0
	s_barrier
	s_add_i32 s72, 0, 0x18000
	s_add_i32 s73, 0, 0x1c000
	v_add_u32_e32 v162, s72, v153
	v_add_u32_e32 v178, s73, v153
	ds_read_b128 v[144:147], v162
	ds_read_b128 v[148:151], v162 offset:1024
	ds_read_b128 v[158:161], v162 offset:2048
	ds_read_b128 v[162:165], v162 offset:3072
	ds_read_b128 v[166:169], v178
	ds_read_b128 v[170:173], v178 offset:1024
	ds_read_b128 v[174:177], v178 offset:2048
	ds_read_b128 v[178:181], v178 offset:3072
	s_add_u32 s54, s54, 0x80000
	s_addc_u32 s55, s55, 0
	s_mov_b32 m0, s56
	v_lshl_add_u64 v[224:225], s[54:55], 0, v[134:135]
	ds_read_b128 v[182:185], v157 offset:32768
	ds_read_b128 v[186:189], v157 offset:33792
	ds_read_b128 v[190:193], v157 offset:34816
	ds_read_b128 v[194:197], v157 offset:35840
	ds_read_b128 v[198:201], v157 offset:36864
	ds_read_b128 v[202:205], v157 offset:37888
	ds_read_b128 v[206:209], v157 offset:38912
	ds_read_b128 v[210:213], v157 offset:39936
	global_load_lds_dwordx4 v[224:225], off
	v_lshl_add_u64 v[224:225], s[54:55], 0, v[130:131]
	s_mov_b32 m0, s57
	s_nop 0
	global_load_lds_dwordx4 v[224:225], off
	s_waitcnt vmcnt(8)
	s_waitcnt lgkmcnt(0)
	s_barrier
	s_setprio 1
	s_waitcnt lgkmcnt(0)
	v_mfma_f32_16x16x32_bf16 v[124:127], v[144:147], v[182:185], v[124:127]
	v_mfma_f32_16x16x32_bf16 v[120:123], v[158:161], v[182:185], v[120:123]
	v_mfma_f32_16x16x32_bf16 v[108:111], v[144:147], v[190:193], v[108:111]
	v_mfma_f32_16x16x32_bf16 v[104:107], v[158:161], v[190:193], v[104:107]
	v_mfma_f32_16x16x32_bf16 v[92:95], v[144:147], v[198:201], v[92:95]
	v_mfma_f32_16x16x32_bf16 v[88:91], v[158:161], v[198:201], v[88:91]
	v_mfma_f32_16x16x32_bf16 v[76:79], v[144:147], v[206:209], v[76:79]
	v_mfma_f32_16x16x32_bf16 v[72:75], v[158:161], v[206:209], v[72:75]
	v_mfma_f32_16x16x32_bf16 v[124:127], v[148:151], v[186:189], v[124:127]
	v_mfma_f32_16x16x32_bf16 v[120:123], v[162:165], v[186:189], v[120:123]
	v_mfma_f32_16x16x32_bf16 v[108:111], v[148:151], v[194:197], v[108:111]
	v_mfma_f32_16x16x32_bf16 v[104:107], v[162:165], v[194:197], v[104:107]
	v_mfma_f32_16x16x32_bf16 v[92:95], v[148:151], v[202:205], v[92:95]
	v_mfma_f32_16x16x32_bf16 v[88:91], v[162:165], v[202:205], v[88:91]
	v_mfma_f32_16x16x32_bf16 v[76:79], v[148:151], v[210:213], v[76:79]
	v_mfma_f32_16x16x32_bf16 v[72:75], v[162:165], v[210:213], v[72:75]
	v_mfma_f32_16x16x32_bf16 v[116:119], v[166:169], v[182:185], v[116:119]
	v_mfma_f32_16x16x32_bf16 v[112:115], v[174:177], v[182:185], v[112:115]
	v_mfma_f32_16x16x32_bf16 v[100:103], v[166:169], v[190:193], v[100:103]
	v_mfma_f32_16x16x32_bf16 v[96:99], v[174:177], v[190:193], v[96:99]
	v_mfma_f32_16x16x32_bf16 v[84:87], v[166:169], v[198:201], v[84:87]
	v_mfma_f32_16x16x32_bf16 v[80:83], v[174:177], v[198:201], v[80:83]
	v_mfma_f32_16x16x32_bf16 v[68:71], v[166:169], v[206:209], v[68:71]
	v_mfma_f32_16x16x32_bf16 v[64:67], v[174:177], v[206:209], v[64:67]
	v_mfma_f32_16x16x32_bf16 v[116:119], v[170:173], v[186:189], v[116:119]
	v_mfma_f32_16x16x32_bf16 v[112:115], v[178:181], v[186:189], v[112:115]
	v_mfma_f32_16x16x32_bf16 v[100:103], v[170:173], v[194:197], v[100:103]
	v_mfma_f32_16x16x32_bf16 v[96:99], v[178:181], v[194:197], v[96:99]
	v_mfma_f32_16x16x32_bf16 v[84:87], v[170:173], v[202:205], v[84:87]
	v_mfma_f32_16x16x32_bf16 v[80:83], v[178:181], v[202:205], v[80:83]
	v_mfma_f32_16x16x32_bf16 v[68:71], v[170:173], v[210:213], v[68:71]
	v_mfma_f32_16x16x32_bf16 v[64:67], v[178:181], v[210:213], v[64:67]
	s_setprio 0
	s_barrier
; #define PG8_STAGE(bufoff, gbase, voff) do { _Pragma("unroll") for (int _i = 0; _i < 2; ++_i) \
;         __builtin_amdgcn_global_load_lds((const unsigned*)((const char*)(gbase) + (voff)[_i]), (PG8_LAS unsigned*)(lds + (bufoff) + ldsw + _i * 8192), 16, 0, 0); } while (0)
; #define PG8_LDA(dst, b, h) do { _Pragma("unroll") for (int m = 0; m < 4; ++m) _Pragma("unroll") for (int k = 0; k < 2; ++k) dst[m][k] = *(const PG8_LAS bf16x8*)(lds + PG8_SA(b, h) + aoff + m * 2048 + k * 1024); } while (0)
; #define PG8_MMA(ai, bj, At, Bt) do { __builtin_amdgcn_s_setprio(1); _Pragma("unroll") for (int m = 0; m < 4; ++m) _Pragma("unroll") for (int n = 0; n < 2; ++n) _Pragma("unroll") for (int k = 0; k < 2; ++k) \
;         acc[ai][bj][m][n] = __builtin_amdgcn_mfma_f32_16x16x32_bf16(Bt[n][k], At[m][k], acc[ai][bj][m][n], 0, 0, 0); __builtin_amdgcn_s_setprio(0); } while (0)
; #define PG8_WAIT_V(n) asm volatile("s_waitcnt vmcnt(" #n ")" ::: "memory")
; #define PG8_WAIT_L(n) asm volatile("s_waitcnt lgkmcnt(" #n ")" ::: "memory")
; #define PG8_BAR __builtin_amdgcn_s_barrier()
; #define PG8_SCHED __builtin_amdgcn_sched_barrier(0)
; template <class Epi, class Sched, bool ALIGN_EPI = false, bool SP2 = false>
; __device__ __forceinline__ void gemm_phase(PG8_LAS unsigned char* lds, const Gemm g, const Sched& S, const Epi& E) {
;     ...
;         for (int t = 0; t < nt; t += 2) {
;     ...
;             PG8_LDA(At, 1, 1); PG8_STAGE(PG8_SB(1, 0), b3, voffB); PG8_STAGE(PG8_SB(1, 1), b3 + hstep, voffB); PG8_STAGE(PG8_SA(1, 0), a3, voffA);
;             PG8_WAIT_V(8); PG8_WAIT_L(0); PG8_BAR; PG8_MMA(1, 0, At, B0); PG8_MMA(1, 1, At, B1); PG8_BAR; PG8_SCHED;
	s_add_i32 s54, s72, s27
	v_lshl_add_u64 v[214:215], v[214:215], 0, s[14:15]
	s_mov_b32 m0, s54
	ds_read_b128 v[182:185], v157 offset:49152
	ds_read_b128 v[186:189], v157 offset:50176
	ds_read_b128 v[190:193], v157 offset:51200
	ds_read_b128 v[194:197], v157 offset:52224
	ds_read_b128 v[198:201], v157 offset:53248
	ds_read_b128 v[202:205], v157 offset:54272
	ds_read_b128 v[206:209], v157 offset:55296
	ds_read_b128 v[210:213], v157 offset:56320
	global_load_lds_dwordx4 v[214:215], off
	s_add_i32 m0, s54, 0x2000
	s_add_u32 s52, s52, 0x80080
	v_lshl_add_u64 v[214:215], v[216:217], 0, s[14:15]
	s_addc_u32 s53, s53, 0
	s_add_i32 s54, s73, s27
	global_load_lds_dwordx4 v[214:215], off
	v_lshl_add_u64 v[214:215], s[52:53], 0, v[132:133]
	s_mov_b32 m0, s54
	s_nop 0
	global_load_lds_dwordx4 v[214:215], off
	v_lshl_add_u64 v[214:215], s[52:53], 0, v[128:129]
	s_add_i32 m0, s54, 0x2000
	s_nop 0
	global_load_lds_dwordx4 v[214:215], off
	v_lshl_add_u64 v[214:215], v[218:219], 0, s[14:15]
	s_mov_b32 m0, s59
	s_nop 0
	global_load_lds_dwordx4 v[214:215], off
	v_lshl_add_u64 v[214:215], v[222:223], 0, s[14:15]
	s_mov_b32 m0, s60
	s_nop 0
	global_load_lds_dwordx4 v[214:215], off
	s_waitcnt vmcnt(8)
	s_waitcnt lgkmcnt(0)
	s_barrier
	s_setprio 1
	s_waitcnt lgkmcnt(0)
	v_mfma_f32_16x16x32_bf16 v[60:63], v[144:147], v[182:185], v[60:63]
	v_mfma_f32_16x16x32_bf16 v[56:59], v[158:161], v[182:185], v[56:59]
	v_mfma_f32_16x16x32_bf16 v[44:47], v[144:147], v[190:193], v[44:47]
	v_mfma_f32_16x16x32_bf16 v[40:43], v[158:161], v[190:193], v[40:43]
	v_mfma_f32_16x16x32_bf16 v[28:31], v[144:147], v[198:201], v[28:31]
	v_mfma_f32_16x16x32_bf16 v[24:27], v[158:161], v[198:201], v[24:27]
	v_mfma_f32_16x16x32_bf16 v[12:15], v[144:147], v[206:209], v[12:15]
	v_mfma_f32_16x16x32_bf16 v[8:11], v[158:161], v[206:209], v[8:11]
	v_mfma_f32_16x16x32_bf16 v[60:63], v[148:151], v[186:189], v[60:63]
	v_mfma_f32_16x16x32_bf16 v[56:59], v[162:165], v[186:189], v[56:59]
	v_mfma_f32_16x16x32_bf16 v[44:47], v[148:151], v[194:197], v[44:47]
	v_mfma_f32_16x16x32_bf16 v[40:43], v[162:165], v[194:197], v[40:43]
	v_mfma_f32_16x16x32_bf16 v[28:31], v[148:151], v[202:205], v[28:31]
	v_mfma_f32_16x16x32_bf16 v[24:27], v[162:165], v[202:205], v[24:27]
	v_mfma_f32_16x16x32_bf16 v[12:15], v[148:151], v[210:213], v[12:15]
	v_mfma_f32_16x16x32_bf16 v[8:11], v[162:165], v[210:213], v[8:11]
	v_mfma_f32_16x16x32_bf16 v[52:55], v[166:169], v[182:185], v[52:55]
	v_mfma_f32_16x16x32_bf16 v[48:51], v[174:177], v[182:185], v[48:51]
	v_mfma_f32_16x16x32_bf16 v[36:39], v[166:169], v[190:193], v[36:39]
	v_mfma_f32_16x16x32_bf16 v[32:35], v[174:177], v[190:193], v[32:35]
	v_mfma_f32_16x16x32_bf16 v[20:23], v[166:169], v[198:201], v[20:23]
	v_mfma_f32_16x16x32_bf16 v[16:19], v[174:177], v[198:201], v[16:19]
	v_mfma_f32_16x16x32_bf16 v[4:7], v[166:169], v[206:209], v[4:7]
	v_mfma_f32_16x16x32_bf16 v[0:3], v[174:177], v[206:209], v[0:3]
	v_mfma_f32_16x16x32_bf16 v[52:55], v[170:173], v[186:189], v[52:55]
	v_mfma_f32_16x16x32_bf16 v[48:51], v[178:181], v[186:189], v[48:51]
	v_mfma_f32_16x16x32_bf16 v[36:39], v[170:173], v[194:197], v[36:39]
	v_mfma_f32_16x16x32_bf16 v[32:35], v[178:181], v[194:197], v[32:35]
	v_mfma_f32_16x16x32_bf16 v[20:23], v[170:173], v[202:205], v[20:23]
	v_mfma_f32_16x16x32_bf16 v[16:19], v[178:181], v[202:205], v[16:19]
	v_mfma_f32_16x16x32_bf16 v[4:7], v[170:173], v[210:213], v[4:7]
	v_mfma_f32_16x16x32_bf16 v[0:3], v[178:181], v[210:213], v[0:3]
	s_setprio 0
	s_barrier
	s_add_i32 s71, s71, 2
	s_add_u32 s50, s50, 0x100
	s_addc_u32 s51, s51, 0
	s_add_u32 s69, s69, 0x100
	s_addc_u32 s70, s70, 0
	s_cmp_gt_u32 s71, 29
	s_cbranch_scc0 .LBB0_1027
	s_and_b64 vcc, exec, s[16:17]
	s_cbranch_vccz .LBB0_1030
	s_barrier

; #define PG8_STAGE(bufoff, gbase, voff) do { _Pragma("unroll") for (int _i = 0; _i < 2; ++_i) \
;         __builtin_amdgcn_global_load_lds((const unsigned*)((const char*)(gbase) + (voff)[_i]), (PG8_LAS unsigned*)(lds + (bufoff) + ldsw + _i * 8192), 16, 0, 0); } while (0)
; #define PG8_LDA(dst, b, h) do { _Pragma("unroll") for (int m = 0; m < 4; ++m) _Pragma("unroll") for (int k = 0; k < 2; ++k) dst[m][k] = *(const PG8_LAS bf16x8*)(lds + PG8_SA(b, h) + aoff + m * 2048 + k * 1024); } while (0)
; #define PG8_LDB(dst, b, h) do { _Pragma("unroll") for (int n = 0; n < 2; ++n) _Pragma("unroll") for (int k = 0; k < 2; ++k) dst[n][k] = *(const PG8_LAS bf16x8*)(lds + PG8_SB(b, h) + boff + n * 2048 + k * 1024); } while (0)
; #define PG8_MMA(ai, bj, At, Bt) do { __builtin_amdgcn_s_setprio(1); _Pragma("unroll") for (int m = 0; m < 4; ++m) _Pragma("unroll") for (int n = 0; n < 2; ++n) _Pragma("unroll") for (int k = 0; k < 2; ++k) \
;         acc[ai][bj][m][n] = __builtin_amdgcn_mfma_f32_16x16x32_bf16(Bt[n][k], At[m][k], acc[ai][bj][m][n], 0, 0, 0); __builtin_amdgcn_s_setprio(0); } while (0)
; #define PG8_WAIT_V(n) asm volatile("s_waitcnt vmcnt(" #n ")" ::: "memory")
; #define PG8_WAIT_L(n) asm volatile("s_waitcnt lgkmcnt(" #n ")" ::: "memory")
; #define PG8_BAR __builtin_amdgcn_s_barrier()
; #define PG8_SCHED __builtin_amdgcn_sched_barrier(0)
; template <class Epi, class Sched, bool ALIGN_EPI = false, bool SP2 = false>
; __device__ __forceinline__ void gemm_phase(PG8_LAS unsigned char* lds, const Gemm g, const Sched& S, const Epi& E) {
;     ...
;             PG8_LDB(B0, 0, 0); PG8_LDB(B1, 0, 1); PG8_SCHED; PG8_LDA(At, 0, 0); PG8_STAGE(PG8_SA(1, 1), a1 + hstep, voffA);
;             PG8_WAIT_V(8); PG8_WAIT_L(0); PG8_BAR; PG8_MMA(0, 0, At, B0); PG8_MMA(0, 1, At, B1); PG8_BAR; PG8_SCHED;
;             PG8_LDA(At, 0, 1); PG8_STAGE(PG8_SB(0, 0), b2, voffB); PG8_STAGE(PG8_SB(0, 1), b2 + hstep, voffB); PG8_STAGE(PG8_SA(0, 0), a2, voffA);
;             PG8_WAIT_V(8); PG8_WAIT_L(0); PG8_BAR; PG8_MMA(1, 0, At, B0); PG8_MMA(1, 1, At, B1); PG8_BAR; PG8_SCHED;
.LBB0_1222:
	ds_read_b128 v[92:95], v212
	ds_read_b128 v[100:103], v212 offset:1024
	ds_read_b128 v[104:107], v212 offset:2048
	ds_read_b128 v[172:175], v212 offset:3072
	ds_read_b128 v[176:179], v213
	ds_read_b128 v[180:183], v213 offset:1024
	ds_read_b128 v[184:187], v213 offset:2048
	ds_read_b128 v[188:191], v213 offset:3072
	s_add_u32 s38, s36, 0x100
	s_addc_u32 s39, s37, 0
	s_add_u32 s40, s62, s36
	s_addc_u32 s41, s63, s37
	s_cmp_eq_u32 s64, 28
	s_cselect_b32 s42, s61, s40
	s_cselect_b32 s40, 0, s38
	s_cselect_b32 s43, s31, s41
	s_cselect_b32 s41, 0, s39
	s_add_u32 s40, s18, s40
	s_addc_u32 s41, s19, s41
	s_mov_b32 m0, s52
	v_lshl_add_u64 v[234:235], v[88:89], 0, s[36:37]
	ds_read_b128 v[192:195], v214
	ds_read_b128 v[196:199], v214 offset:1024
	ds_read_b128 v[200:203], v214 offset:2048
	ds_read_b128 v[204:207], v214 offset:3072
	ds_read_b128 v[208:211], v214 offset:4096
	ds_read_b128 v[222:225], v214 offset:5120
	ds_read_b128 v[226:229], v214 offset:6144
	ds_read_b128 v[230:233], v214 offset:7168
	global_load_lds_dwordx4 v[234:235], off
	v_lshl_add_u64 v[234:235], v[90:91], 0, s[36:37]
	s_mov_b32 m0, s53
	s_nop 0
	global_load_lds_dwordx4 v[234:235], off
	s_waitcnt vmcnt(8)
	s_waitcnt lgkmcnt(0)
	s_barrier
	s_setprio 1
	s_waitcnt lgkmcnt(0)
	v_mfma_f32_16x16x32_bf16 v[140:143], v[92:95], v[192:195], v[140:143]
	v_mfma_f32_16x16x32_bf16 v[136:139], v[104:107], v[192:195], v[136:139]
	v_mfma_f32_16x16x32_bf16 v[124:127], v[92:95], v[200:203], v[124:127]
	v_mfma_f32_16x16x32_bf16 v[120:123], v[104:107], v[200:203], v[120:123]
	v_mfma_f32_16x16x32_bf16 v[108:111], v[92:95], v[208:211], v[108:111]
	v_mfma_f32_16x16x32_bf16 v[96:99], v[104:107], v[208:211], v[96:99]
	v_mfma_f32_16x16x32_bf16 v[76:79], v[92:95], v[226:229], v[76:79]
	v_mfma_f32_16x16x32_bf16 v[72:75], v[104:107], v[226:229], v[72:75]
	v_mfma_f32_16x16x32_bf16 v[140:143], v[100:103], v[196:199], v[140:143]
	v_mfma_f32_16x16x32_bf16 v[136:139], v[172:175], v[196:199], v[136:139]
	v_mfma_f32_16x16x32_bf16 v[124:127], v[100:103], v[204:207], v[124:127]
	v_mfma_f32_16x16x32_bf16 v[120:123], v[172:175], v[204:207], v[120:123]
	v_mfma_f32_16x16x32_bf16 v[108:111], v[100:103], v[222:225], v[108:111]
	v_mfma_f32_16x16x32_bf16 v[96:99], v[172:175], v[222:225], v[96:99]
	v_mfma_f32_16x16x32_bf16 v[76:79], v[100:103], v[230:233], v[76:79]
	v_mfma_f32_16x16x32_bf16 v[72:75], v[172:175], v[230:233], v[72:75]
	v_mfma_f32_16x16x32_bf16 v[132:135], v[176:179], v[192:195], v[132:135]
	v_mfma_f32_16x16x32_bf16 v[128:131], v[184:187], v[192:195], v[128:131]
	v_mfma_f32_16x16x32_bf16 v[116:119], v[176:179], v[200:203], v[116:119]
	v_mfma_f32_16x16x32_bf16 v[112:115], v[184:187], v[200:203], v[112:115]
	v_mfma_f32_16x16x32_bf16 v[84:87], v[176:179], v[208:211], v[84:87]
	v_mfma_f32_16x16x32_bf16 v[80:83], v[184:187], v[208:211], v[80:83]
	v_mfma_f32_16x16x32_bf16 v[68:71], v[176:179], v[226:229], v[68:71]
	v_mfma_f32_16x16x32_bf16 v[64:67], v[184:187], v[226:229], v[64:67]
	v_mfma_f32_16x16x32_bf16 v[132:135], v[180:183], v[196:199], v[132:135]
	v_mfma_f32_16x16x32_bf16 v[128:131], v[188:191], v[196:199], v[128:131]
	v_mfma_f32_16x16x32_bf16 v[116:119], v[180:183], v[204:207], v[116:119]
	v_mfma_f32_16x16x32_bf16 v[112:115], v[188:191], v[204:207], v[112:115]
	v_mfma_f32_16x16x32_bf16 v[84:87], v[180:183], v[222:225], v[84:87]
	v_mfma_f32_16x16x32_bf16 v[80:83], v[188:191], v[222:225], v[80:83]
	v_mfma_f32_16x16x32_bf16 v[68:71], v[180:183], v[230:233], v[68:71]
	v_mfma_f32_16x16x32_bf16 v[64:67], v[188:191], v[230:233], v[64:67]
	s_setprio 0
	s_barrier
	s_mov_b32 m0, s54
	v_lshl_add_u64 v[234:235], s[40:41], 0, v[146:147]
	s_add_u32 s36, s40, 0x80000
	ds_read_b128 v[192:195], v214 offset:16384
	ds_read_b128 v[196:199], v214 offset:17408
	ds_read_b128 v[200:203], v214 offset:18432
	ds_read_b128 v[204:207], v214 offset:19456
	ds_read_b128 v[208:211], v214 offset:20480
	ds_read_b128 v[222:225], v214 offset:21504
	ds_read_b128 v[226:229], v214 offset:22528
	ds_read_b128 v[230:233], v214 offset:23552
	global_load_lds_dwordx4 v[234:235], off
	v_lshl_add_u64 v[236:237], s[40:41], 0, v[144:145]
	s_mov_b32 m0, s55
	s_addc_u32 s37, s41, 0
	global_load_lds_dwordx4 v[236:237], off
	v_lshl_add_u64 v[238:239], s[36:37], 0, v[146:147]
	s_mov_b32 m0, s56
	v_lshl_add_u64 v[240:241], s[42:43], 0, v[144:145]
	global_load_lds_dwordx4 v[238:239], off
	v_lshl_add_u64 v[238:239], s[36:37], 0, v[144:145]
	s_mov_b32 m0, s57
	s_nop 0
	global_load_lds_dwordx4 v[238:239], off
	v_lshl_add_u64 v[238:239], s[42:43], 0, v[146:147]
	s_mov_b32 m0, s17
	s_nop 0
	global_load_lds_dwordx4 v[238:239], off
	s_mov_b32 m0, s45
	s_nop 0
	global_load_lds_dwordx4 v[240:241], off
	s_waitcnt vmcnt(8)
	s_waitcnt lgkmcnt(0)
	s_barrier
; #define PG8_STAGE(bufoff, gbase, voff) do { _Pragma("unroll") for (int _i = 0; _i < 2; ++_i) \
;         __builtin_amdgcn_global_load_lds((const unsigned*)((const char*)(gbase) + (voff)[_i]), (PG8_LAS unsigned*)(lds + (bufoff) + ldsw + _i * 8192), 16, 0, 0); } while (0)
; #define PG8_LDA(dst, b, h) do { _Pragma("unroll") for (int m = 0; m < 4; ++m) _Pragma("unroll") for (int k = 0; k < 2; ++k) dst[m][k] = *(const PG8_LAS bf16x8*)(lds + PG8_SA(b, h) + aoff + m * 2048 + k * 1024); } while (0)
; #define PG8_LDB(dst, b, h) do { _Pragma("unroll") for (int n = 0; n < 2; ++n) _Pragma("unroll") for (int k = 0; k < 2; ++k) dst[n][k] = *(const PG8_LAS bf16x8*)(lds + PG8_SB(b, h) + boff + n * 2048 + k * 1024); } while (0)
; #define PG8_MMA(ai, bj, At, Bt) do { __builtin_amdgcn_s_setprio(1); _Pragma("unroll") for (int m = 0; m < 4; ++m) _Pragma("unroll") for (int n = 0; n < 2; ++n) _Pragma("unroll") for (int k = 0; k < 2; ++k) \
;         acc[ai][bj][m][n] = __builtin_amdgcn_mfma_f32_16x16x32_bf16(Bt[n][k], At[m][k], acc[ai][bj][m][n], 0, 0, 0); __builtin_amdgcn_s_setprio(0); } while (0)
; #define PG8_WAIT_V(n) asm volatile("s_waitcnt vmcnt(" #n ")" ::: "memory")
; #define PG8_WAIT_L(n) asm volatile("s_waitcnt lgkmcnt(" #n ")" ::: "memory")
; #define PG8_BAR __builtin_amdgcn_s_barrier()
; #define PG8_SCHED __builtin_amdgcn_sched_barrier(0)
; template <class Epi, class Sched, bool ALIGN_EPI = false, bool SP2 = false>
; __device__ __forceinline__ void gemm_phase(PG8_LAS unsigned char* lds, const Gemm g, const Sched& S, const Epi& E) {
;     ...
;             PG8_WAIT_V(8); PG8_WAIT_L(0); PG8_BAR; PG8_MMA(1, 0, At, B0); PG8_MMA(1, 1, At, B1); PG8_BAR; PG8_SCHED;
;             PG8_LDB(B0, 1, 0); PG8_LDB(B1, 1, 1); PG8_SCHED; PG8_LDA(At, 1, 0); PG8_STAGE(PG8_SA(0, 1), a2 + hstep, voffA);
;             PG8_WAIT_V(8); PG8_WAIT_L(0); PG8_BAR; PG8_MMA(0, 0, At, B0); PG8_MMA(0, 1, At, B1); PG8_BAR; PG8_SCHED;
	s_setprio 1
	s_waitcnt lgkmcnt(0)
	v_mfma_f32_16x16x32_bf16 v[60:63], v[92:95], v[192:195], v[60:63]
	v_mfma_f32_16x16x32_bf16 v[56:59], v[104:107], v[192:195], v[56:59]
	v_mfma_f32_16x16x32_bf16 v[44:47], v[92:95], v[200:203], v[44:47]
	v_mfma_f32_16x16x32_bf16 v[40:43], v[104:107], v[200:203], v[40:43]
	v_mfma_f32_16x16x32_bf16 v[28:31], v[92:95], v[208:211], v[28:31]
	v_mfma_f32_16x16x32_bf16 v[24:27], v[104:107], v[208:211], v[24:27]
	v_mfma_f32_16x16x32_bf16 v[12:15], v[92:95], v[226:229], v[12:15]
	v_mfma_f32_16x16x32_bf16 v[8:11], v[104:107], v[226:229], v[8:11]
	v_mfma_f32_16x16x32_bf16 v[60:63], v[100:103], v[196:199], v[60:63]
	v_mfma_f32_16x16x32_bf16 v[56:59], v[172:175], v[196:199], v[56:59]
	v_mfma_f32_16x16x32_bf16 v[44:47], v[100:103], v[204:207], v[44:47]
	v_mfma_f32_16x16x32_bf16 v[40:43], v[172:175], v[204:207], v[40:43]
	v_mfma_f32_16x16x32_bf16 v[28:31], v[100:103], v[222:225], v[28:31]
	v_mfma_f32_16x16x32_bf16 v[24:27], v[172:175], v[222:225], v[24:27]
	v_mfma_f32_16x16x32_bf16 v[12:15], v[100:103], v[230:233], v[12:15]
	v_mfma_f32_16x16x32_bf16 v[8:11], v[172:175], v[230:233], v[8:11]
	v_mfma_f32_16x16x32_bf16 v[52:55], v[176:179], v[192:195], v[52:55]
	v_mfma_f32_16x16x32_bf16 v[48:51], v[184:187], v[192:195], v[48:51]
	v_mfma_f32_16x16x32_bf16 v[36:39], v[176:179], v[200:203], v[36:39]
	v_mfma_f32_16x16x32_bf16 v[32:35], v[184:187], v[200:203], v[32:35]
	v_mfma_f32_16x16x32_bf16 v[20:23], v[176:179], v[208:211], v[20:23]
	v_mfma_f32_16x16x32_bf16 v[16:19], v[184:187], v[208:211], v[16:19]
	v_mfma_f32_16x16x32_bf16 v[4:7], v[176:179], v[226:229], v[4:7]
	v_mfma_f32_16x16x32_bf16 v[0:3], v[184:187], v[226:229], v[0:3]
	v_mfma_f32_16x16x32_bf16 v[52:55], v[180:183], v[196:199], v[52:55]
	v_mfma_f32_16x16x32_bf16 v[48:51], v[188:191], v[196:199], v[48:51]
	v_mfma_f32_16x16x32_bf16 v[36:39], v[180:183], v[204:207], v[36:39]
	v_mfma_f32_16x16x32_bf16 v[32:35], v[188:191], v[204:207], v[32:35]
	v_mfma_f32_16x16x32_bf16 v[20:23], v[180:183], v[222:225], v[20:23]
	v_mfma_f32_16x16x32_bf16 v[16:19], v[188:191], v[222:225], v[16:19]
	v_mfma_f32_16x16x32_bf16 v[4:7], v[180:183], v[230:233], v[4:7]
	v_mfma_f32_16x16x32_bf16 v[0:3], v[188:191], v[230:233], v[0:3]
	s_setprio 0
	s_barrier
	ds_read_b128 v[92:95], v216
	ds_read_b128 v[100:103], v216 offset:1024
	ds_read_b128 v[104:107], v216 offset:2048
	ds_read_b128 v[172:175], v216 offset:3072
	ds_read_b128 v[176:179], v217
	ds_read_b128 v[180:183], v217 offset:1024
	ds_read_b128 v[184:187], v217 offset:2048
	ds_read_b128 v[188:191], v217 offset:3072
	s_add_u32 s36, s42, 0x80000
	s_addc_u32 s37, s43, 0
	s_mov_b32 m0, s46
	v_lshl_add_u64 v[242:243], s[36:37], 0, v[146:147]
	ds_read_b128 v[192:195], v214 offset:32768
	ds_read_b128 v[196:199], v214 offset:33792
	ds_read_b128 v[200:203], v214 offset:34816
	ds_read_b128 v[204:207], v214 offset:35840
	ds_read_b128 v[208:211], v214 offset:36864
	ds_read_b128 v[222:225], v214 offset:37888
	ds_read_b128 v[226:229], v214 offset:38912
	ds_read_b128 v[230:233], v214 offset:39936
	global_load_lds_dwordx4 v[242:243], off
	v_lshl_add_u64 v[242:243], s[36:37], 0, v[144:145]
	s_mov_b32 m0, s47
	s_nop 0
	global_load_lds_dwordx4 v[242:243], off
	s_waitcnt vmcnt(8)
	s_waitcnt lgkmcnt(0)
	s_barrier
	s_setprio 1
	s_waitcnt lgkmcnt(0)
	v_mfma_f32_16x16x32_bf16 v[140:143], v[92:95], v[192:195], v[140:143]
	v_mfma_f32_16x16x32_bf16 v[136:139], v[104:107], v[192:195], v[136:139]
	v_mfma_f32_16x16x32_bf16 v[124:127], v[92:95], v[200:203], v[124:127]
	v_mfma_f32_16x16x32_bf16 v[120:123], v[104:107], v[200:203], v[120:123]
	v_mfma_f32_16x16x32_bf16 v[108:111], v[92:95], v[208:211], v[108:111]
	v_mfma_f32_16x16x32_bf16 v[96:99], v[104:107], v[208:211], v[96:99]
	v_mfma_f32_16x16x32_bf16 v[76:79], v[92:95], v[226:229], v[76:79]
	v_mfma_f32_16x16x32_bf16 v[72:75], v[104:107], v[226:229], v[72:75]
	v_mfma_f32_16x16x32_bf16 v[140:143], v[100:103], v[196:199], v[140:143]
	v_mfma_f32_16x16x32_bf16 v[136:139], v[172:175], v[196:199], v[136:139]
	v_mfma_f32_16x16x32_bf16 v[124:127], v[100:103], v[204:207], v[124:127]
	v_mfma_f32_16x16x32_bf16 v[120:123], v[172:175], v[204:207], v[120:123]
	v_mfma_f32_16x16x32_bf16 v[108:111], v[100:103], v[222:225], v[108:111]
	v_mfma_f32_16x16x32_bf16 v[96:99], v[172:175], v[222:225], v[96:99]
	v_mfma_f32_16x16x32_bf16 v[76:79], v[100:103], v[230:233], v[76:79]
	v_mfma_f32_16x16x32_bf16 v[72:75], v[172:175], v[230:233], v[72:75]
	v_mfma_f32_16x16x32_bf16 v[132:135], v[176:179], v[192:195], v[132:135]
	v_mfma_f32_16x16x32_bf16 v[128:131], v[184:187], v[192:195], v[128:131]
	v_mfma_f32_16x16x32_bf16 v[116:119], v[176:179], v[200:203], v[116:119]
	v_mfma_f32_16x16x32_bf16 v[112:115], v[184:187], v[200:203], v[112:115]
	v_mfma_f32_16x16x32_bf16 v[84:87], v[176:179], v[208:211], v[84:87]
	v_mfma_f32_16x16x32_bf16 v[80:83], v[184:187], v[208:211], v[80:83]
	v_mfma_f32_16x16x32_bf16 v[68:71], v[176:179], v[226:229], v[68:71]
	v_mfma_f32_16x16x32_bf16 v[64:67], v[184:187], v[226:229], v[64:67]
	v_mfma_f32_16x16x32_bf16 v[132:135], v[180:183], v[196:199], v[132:135]
	v_mfma_f32_16x16x32_bf16 v[128:131], v[188:191], v[196:199], v[128:131]
	v_mfma_f32_16x16x32_bf16 v[116:119], v[180:183], v[204:207], v[116:119]
	v_mfma_f32_16x16x32_bf16 v[112:115], v[188:191], v[204:207], v[112:115]
	v_mfma_f32_16x16x32_bf16 v[84:87], v[180:183], v[222:225], v[84:87]
	v_mfma_f32_16x16x32_bf16 v[80:83], v[188:191], v[222:225], v[80:83]
	v_mfma_f32_16x16x32_bf16 v[68:71], v[180:183], v[230:233], v[68:71]
	v_mfma_f32_16x16x32_bf16 v[64:67], v[188:191], v[230:233], v[64:67]
	s_setprio 0
	s_barrier
; #define PG8_STAGE(bufoff, gbase, voff) do { _Pragma("unroll") for (int _i = 0; _i < 2; ++_i) \
;         __builtin_amdgcn_global_load_lds((const unsigned*)((const char*)(gbase) + (voff)[_i]), (PG8_LAS unsigned*)(lds + (bufoff) + ldsw + _i * 8192), 16, 0, 0); } while (0)
; #define PG8_LDA(dst, b, h) do { _Pragma("unroll") for (int m = 0; m < 4; ++m) _Pragma("unroll") for (int k = 0; k < 2; ++k) dst[m][k] = *(const PG8_LAS bf16x8*)(lds + PG8_SA(b, h) + aoff + m * 2048 + k * 1024); } while (0)
; #define PG8_MMA(ai, bj, At, Bt) do { __builtin_amdgcn_s_setprio(1); _Pragma("unroll") for (int m = 0; m < 4; ++m) _Pragma("unroll") for (int n = 0; n < 2; ++n) _Pragma("unroll") for (int k = 0; k < 2; ++k) \
;         acc[ai][bj][m][n] = __builtin_amdgcn_mfma_f32_16x16x32_bf16(Bt[n][k], At[m][k], acc[ai][bj][m][n], 0, 0, 0); __builtin_amdgcn_s_setprio(0); } while (0)
; #define PG8_WAIT_V(n) asm volatile("s_waitcnt vmcnt(" #n ")" ::: "memory")
; #define PG8_WAIT_L(n) asm volatile("s_waitcnt lgkmcnt(" #n ")" ::: "memory")
; #define PG8_BAR __builtin_amdgcn_s_barrier()
; #define PG8_SCHED __builtin_amdgcn_sched_barrier(0)
; template <class Epi, class Sched, bool ALIGN_EPI = false, bool SP2 = false>
; __device__ __forceinline__ void gemm_phase(PG8_LAS unsigned char* lds, const Gemm g, const Sched& S, const Epi& E) {
;     ...
;         for (int t = 0; t < nt; t += 2) {
;     ...
;             PG8_LDA(At, 1, 1); PG8_STAGE(PG8_SB(1, 0), b3, voffB); PG8_STAGE(PG8_SB(1, 1), b3 + hstep, voffB); PG8_STAGE(PG8_SA(1, 0), a3, voffA);
;             PG8_WAIT_V(8); PG8_WAIT_L(0); PG8_BAR; PG8_MMA(1, 0, At, B0); PG8_MMA(1, 1, At, B1); PG8_BAR; PG8_SCHED;
	s_add_i32 s36, s58, s44
	v_lshl_add_u64 v[234:235], v[234:235], 0, s[28:29]
	s_mov_b32 m0, s36
	ds_read_b128 v[192:195], v214 offset:49152
	ds_read_b128 v[196:199], v214 offset:50176
	ds_read_b128 v[200:203], v214 offset:51200
	ds_read_b128 v[204:207], v214 offset:52224
	ds_read_b128 v[208:211], v214 offset:53248
	ds_read_b128 v[222:225], v214 offset:54272
	ds_read_b128 v[226:229], v214 offset:55296
	ds_read_b128 v[230:233], v214 offset:56320
	global_load_lds_dwordx4 v[234:235], off
	s_add_i32 m0, s36, 0x2000
	s_add_u32 s36, s40, 0x80080
	v_lshl_add_u64 v[234:235], v[236:237], 0, s[28:29]
	s_addc_u32 s37, s41, 0
	s_add_i32 s40, s59, s44
	global_load_lds_dwordx4 v[234:235], off
	v_lshl_add_u64 v[234:235], s[36:37], 0, v[146:147]
	s_mov_b32 m0, s40
	s_nop 0
	global_load_lds_dwordx4 v[234:235], off
	v_lshl_add_u64 v[234:235], s[36:37], 0, v[144:145]
	s_add_i32 m0, s40, 0x2000
	s_nop 0
	global_load_lds_dwordx4 v[234:235], off
	v_lshl_add_u64 v[234:235], v[238:239], 0, s[28:29]
	s_mov_b32 m0, s50
	s_nop 0
	global_load_lds_dwordx4 v[234:235], off
	v_lshl_add_u64 v[234:235], v[240:241], 0, s[28:29]
	s_mov_b32 m0, s51
	s_nop 0
	global_load_lds_dwordx4 v[234:235], off
	s_waitcnt vmcnt(8)
	s_waitcnt lgkmcnt(0)
	s_barrier
	s_setprio 1
	s_waitcnt lgkmcnt(0)
	v_mfma_f32_16x16x32_bf16 v[60:63], v[92:95], v[192:195], v[60:63]
	v_mfma_f32_16x16x32_bf16 v[56:59], v[104:107], v[192:195], v[56:59]
	v_mfma_f32_16x16x32_bf16 v[44:47], v[92:95], v[200:203], v[44:47]
	v_mfma_f32_16x16x32_bf16 v[40:43], v[104:107], v[200:203], v[40:43]
	v_mfma_f32_16x16x32_bf16 v[28:31], v[92:95], v[208:211], v[28:31]
	v_mfma_f32_16x16x32_bf16 v[24:27], v[104:107], v[208:211], v[24:27]
	v_mfma_f32_16x16x32_bf16 v[12:15], v[92:95], v[226:229], v[12:15]
	v_mfma_f32_16x16x32_bf16 v[8:11], v[104:107], v[226:229], v[8:11]
	v_mfma_f32_16x16x32_bf16 v[60:63], v[100:103], v[196:199], v[60:63]
	v_mfma_f32_16x16x32_bf16 v[56:59], v[172:175], v[196:199], v[56:59]
	v_mfma_f32_16x16x32_bf16 v[44:47], v[100:103], v[204:207], v[44:47]
	v_mfma_f32_16x16x32_bf16 v[40:43], v[172:175], v[204:207], v[40:43]
	v_mfma_f32_16x16x32_bf16 v[28:31], v[100:103], v[222:225], v[28:31]
	v_mfma_f32_16x16x32_bf16 v[24:27], v[172:175], v[222:225], v[24:27]
	v_mfma_f32_16x16x32_bf16 v[12:15], v[100:103], v[230:233], v[12:15]
	v_mfma_f32_16x16x32_bf16 v[8:11], v[172:175], v[230:233], v[8:11]
	v_mfma_f32_16x16x32_bf16 v[52:55], v[176:179], v[192:195], v[52:55]
	v_mfma_f32_16x16x32_bf16 v[48:51], v[184:187], v[192:195], v[48:51]
	v_mfma_f32_16x16x32_bf16 v[36:39], v[176:179], v[200:203], v[36:39]
	v_mfma_f32_16x16x32_bf16 v[32:35], v[184:187], v[200:203], v[32:35]
	v_mfma_f32_16x16x32_bf16 v[20:23], v[176:179], v[208:211], v[20:23]
	v_mfma_f32_16x16x32_bf16 v[16:19], v[184:187], v[208:211], v[16:19]
	v_mfma_f32_16x16x32_bf16 v[4:7], v[176:179], v[226:229], v[4:7]
	v_mfma_f32_16x16x32_bf16 v[0:3], v[184:187], v[226:229], v[0:3]
	v_mfma_f32_16x16x32_bf16 v[52:55], v[180:183], v[196:199], v[52:55]
	v_mfma_f32_16x16x32_bf16 v[48:51], v[188:191], v[196:199], v[48:51]
	v_mfma_f32_16x16x32_bf16 v[36:39], v[180:183], v[204:207], v[36:39]
	v_mfma_f32_16x16x32_bf16 v[32:35], v[188:191], v[204:207], v[32:35]
	v_mfma_f32_16x16x32_bf16 v[20:23], v[180:183], v[222:225], v[20:23]
	v_mfma_f32_16x16x32_bf16 v[16:19], v[188:191], v[222:225], v[16:19]
	v_mfma_f32_16x16x32_bf16 v[4:7], v[180:183], v[230:233], v[4:7]
	v_mfma_f32_16x16x32_bf16 v[0:3], v[188:191], v[230:233], v[0:3]
	s_setprio 0
	s_barrier
	s_add_i32 s64, s64, 2
	s_cmp_gt_u32 s64, 29
	s_mov_b64 s[36:37], s[38:39]
	s_cbranch_scc0 .LBB0_1222
	s_and_b64 vcc, exec, s[4:5]
	s_cbranch_vccz .LBB0_1225
	s_barrier

; #define PG8_STAGE(bufoff, gbase, voff) do { _Pragma("unroll") for (int _i = 0; _i < 2; ++_i) \
;         __builtin_amdgcn_global_load_lds((const unsigned*)((const char*)(gbase) + (voff)[_i]), (PG8_LAS unsigned*)(lds + (bufoff) + ldsw + _i * 8192), 16, 0, 0); } while (0)
; #define PG8_LDA(dst, b, h) do { _Pragma("unroll") for (int m = 0; m < 4; ++m) _Pragma("unroll") for (int k = 0; k < 2; ++k) dst[m][k] = *(const PG8_LAS bf16x8*)(lds + PG8_SA(b, h) + aoff + m * 2048 + k * 1024); } while (0)
; #define PG8_LDB(dst, b, h) do { _Pragma("unroll") for (int n = 0; n < 2; ++n) _Pragma("unroll") for (int k = 0; k < 2; ++k) dst[n][k] = *(const PG8_LAS bf16x8*)(lds + PG8_SB(b, h) + boff + n * 2048 + k * 1024); } while (0)
; #define PG8_MMA(ai, bj, At, Bt) do { __builtin_amdgcn_s_setprio(1); _Pragma("unroll") for (int m = 0; m < 4; ++m) _Pragma("unroll") for (int n = 0; n < 2; ++n) _Pragma("unroll") for (int k = 0; k < 2; ++k) \
;         acc[ai][bj][m][n] = __builtin_amdgcn_mfma_f32_16x16x32_bf16(Bt[n][k], At[m][k], acc[ai][bj][m][n], 0, 0, 0); __builtin_amdgcn_s_setprio(0); } while (0)
; #define PG8_WAIT_V(n) asm volatile("s_waitcnt vmcnt(" #n ")" ::: "memory")
; #define PG8_WAIT_L(n) asm volatile("s_waitcnt lgkmcnt(" #n ")" ::: "memory")
; #define PG8_BAR __builtin_amdgcn_s_barrier()
; #define PG8_SCHED __builtin_amdgcn_sched_barrier(0)
; template <class Epi, class Sched, bool ALIGN_EPI = false, bool SP2 = false>
; __device__ __forceinline__ void gemm_phase(PG8_LAS unsigned char* lds, const Gemm g, const Sched& S, const Epi& E) {
;     ...
;             PG8_LDB(B0, 0, 0); PG8_LDB(B1, 0, 1); PG8_SCHED; PG8_LDA(At, 0, 0); PG8_STAGE(PG8_SA(1, 1), a1 + hstep, voffA);
;             PG8_WAIT_V(8); PG8_WAIT_L(0); PG8_BAR; PG8_MMA(0, 0, At, B0); PG8_MMA(0, 1, At, B1); PG8_BAR; PG8_SCHED;
;             PG8_LDA(At, 0, 1); PG8_STAGE(PG8_SB(0, 0), b2, voffB); PG8_STAGE(PG8_SB(0, 1), b2 + hstep, voffB); PG8_STAGE(PG8_SA(0, 0), a2, voffA);
;             PG8_WAIT_V(8); PG8_WAIT_L(0); PG8_BAR; PG8_MMA(1, 0, At, B0); PG8_MMA(1, 1, At, B1); PG8_BAR; PG8_SCHED;
.LBB0_1274:
	ds_read_b128 v[128:131], v165
	ds_read_b128 v[132:135], v165 offset:1024
	ds_read_b128 v[136:139], v165 offset:2048
	ds_read_b128 v[140:143], v165 offset:3072
	ds_read_b128 v[156:159], v166
	ds_read_b128 v[168:171], v166 offset:1024
	ds_read_b128 v[172:175], v166 offset:2048
	ds_read_b128 v[176:179], v166 offset:3072
	s_add_u32 s28, s26, 0x100
	s_addc_u32 s29, s27, 0
	s_cmp_eq_u32 s57, 28
	s_cselect_b32 s35, s19, s29
	s_cselect_b32 s34, s53, s28
	s_cselect_b32 s31, s17, s56
	s_cselect_b32 s30, s54, s55
	v_lshl_add_u64 v[160:161], s[26:27], 0, v[148:149]
	s_add_i32 m0, s25, 0xc000
	ds_read_b128 v[180:183], v167
	ds_read_b128 v[184:187], v167 offset:1024
	ds_read_b128 v[188:191], v167 offset:2048
	ds_read_b128 v[192:195], v167 offset:3072
	ds_read_b128 v[196:199], v167 offset:4096
	ds_read_b128 v[200:203], v167 offset:5120
	ds_read_b128 v[204:207], v167 offset:6144
	ds_read_b128 v[208:211], v167 offset:7168
	global_load_lds_dwordx4 v[160:161], off
	v_lshl_add_u64 v[160:161], s[26:27], 0, v[150:151]
	s_add_i32 m0, s25, 0xe000
	s_nop 0
	global_load_lds_dwordx4 v[160:161], off
	s_waitcnt vmcnt(8)
	s_waitcnt lgkmcnt(0)
	s_barrier
	s_setprio 1
	s_waitcnt lgkmcnt(0)
	v_mfma_f32_16x16x32_bf16 v[124:127], v[128:131], v[180:183], v[124:127]
	v_mfma_f32_16x16x32_bf16 v[120:123], v[136:139], v[180:183], v[120:123]
	v_mfma_f32_16x16x32_bf16 v[116:119], v[128:131], v[188:191], v[116:119]
	v_mfma_f32_16x16x32_bf16 v[112:115], v[136:139], v[188:191], v[112:115]
	v_mfma_f32_16x16x32_bf16 v[92:95], v[128:131], v[196:199], v[92:95]
	v_mfma_f32_16x16x32_bf16 v[88:91], v[136:139], v[196:199], v[88:91]
	v_mfma_f32_16x16x32_bf16 v[84:87], v[128:131], v[204:207], v[84:87]
	v_mfma_f32_16x16x32_bf16 v[80:83], v[136:139], v[204:207], v[80:83]
	v_mfma_f32_16x16x32_bf16 v[124:127], v[132:135], v[184:187], v[124:127]
	v_mfma_f32_16x16x32_bf16 v[120:123], v[140:143], v[184:187], v[120:123]
	v_mfma_f32_16x16x32_bf16 v[116:119], v[132:135], v[192:195], v[116:119]
	v_mfma_f32_16x16x32_bf16 v[112:115], v[140:143], v[192:195], v[112:115]
	v_mfma_f32_16x16x32_bf16 v[92:95], v[132:135], v[200:203], v[92:95]
	v_mfma_f32_16x16x32_bf16 v[88:91], v[140:143], v[200:203], v[88:91]
	v_mfma_f32_16x16x32_bf16 v[84:87], v[132:135], v[208:211], v[84:87]
	v_mfma_f32_16x16x32_bf16 v[80:83], v[140:143], v[208:211], v[80:83]
	v_mfma_f32_16x16x32_bf16 v[108:111], v[156:159], v[180:183], v[108:111]
	v_mfma_f32_16x16x32_bf16 v[104:107], v[172:175], v[180:183], v[104:107]
	v_mfma_f32_16x16x32_bf16 v[100:103], v[156:159], v[188:191], v[100:103]
	v_mfma_f32_16x16x32_bf16 v[96:99], v[172:175], v[188:191], v[96:99]
	v_mfma_f32_16x16x32_bf16 v[76:79], v[156:159], v[196:199], v[76:79]
	v_mfma_f32_16x16x32_bf16 v[72:75], v[172:175], v[196:199], v[72:75]
	v_mfma_f32_16x16x32_bf16 v[68:71], v[156:159], v[204:207], v[68:71]
	v_mfma_f32_16x16x32_bf16 v[64:67], v[172:175], v[204:207], v[64:67]
	v_mfma_f32_16x16x32_bf16 v[108:111], v[168:171], v[184:187], v[108:111]
	v_mfma_f32_16x16x32_bf16 v[104:107], v[176:179], v[184:187], v[104:107]
	v_mfma_f32_16x16x32_bf16 v[100:103], v[168:171], v[192:195], v[100:103]
	v_mfma_f32_16x16x32_bf16 v[96:99], v[176:179], v[192:195], v[96:99]
	v_mfma_f32_16x16x32_bf16 v[76:79], v[168:171], v[200:203], v[76:79]
	v_mfma_f32_16x16x32_bf16 v[72:75], v[176:179], v[200:203], v[72:75]
	v_mfma_f32_16x16x32_bf16 v[68:71], v[168:171], v[208:211], v[68:71]
	v_mfma_f32_16x16x32_bf16 v[64:67], v[176:179], v[208:211], v[64:67]
	s_setprio 0
	s_barrier
	s_add_i32 s26, s49, s40
	v_lshl_add_u64 v[160:161], s[30:31], 0, v[144:145]
	s_mov_b32 m0, s26
	ds_read_b128 v[180:183], v167 offset:16384
	ds_read_b128 v[184:187], v167 offset:17408
	ds_read_b128 v[188:191], v167 offset:18432
	ds_read_b128 v[192:195], v167 offset:19456
	ds_read_b128 v[196:199], v167 offset:20480
	ds_read_b128 v[200:203], v167 offset:21504
	ds_read_b128 v[204:207], v167 offset:22528
	ds_read_b128 v[208:211], v167 offset:23552
	global_load_lds_dwordx4 v[160:161], off
	s_add_i32 m0, s26, 0x2000
	s_add_u32 s26, s30, 0x80000
	v_lshl_add_u64 v[212:213], s[30:31], 0, v[146:147]
	s_addc_u32 s27, s31, 0
	s_add_i32 s58, s50, s40
	global_load_lds_dwordx4 v[212:213], off
	v_lshl_add_u64 v[214:215], s[26:27], 0, v[144:145]
	s_mov_b32 m0, s58
	v_lshl_add_u64 v[216:217], s[34:35], 0, v[146:147]
	global_load_lds_dwordx4 v[214:215], off
	v_lshl_add_u64 v[214:215], s[26:27], 0, v[146:147]
	s_add_i32 m0, s58, 0x2000
	s_nop 0
	global_load_lds_dwordx4 v[214:215], off
	v_lshl_add_u64 v[214:215], s[34:35], 0, v[144:145]
	s_mov_b32 m0, s25
	s_nop 0
	global_load_lds_dwordx4 v[214:215], off
	s_mov_b32 m0, s41
	s_nop 0
	global_load_lds_dwordx4 v[216:217], off
	s_waitcnt vmcnt(8)
	s_waitcnt lgkmcnt(0)
	s_barrier
; #define PG8_STAGE(bufoff, gbase, voff) do { _Pragma("unroll") for (int _i = 0; _i < 2; ++_i) \
;         __builtin_amdgcn_global_load_lds((const unsigned*)((const char*)(gbase) + (voff)[_i]), (PG8_LAS unsigned*)(lds + (bufoff) + ldsw + _i * 8192), 16, 0, 0); } while (0)
; #define PG8_LDA(dst, b, h) do { _Pragma("unroll") for (int m = 0; m < 4; ++m) _Pragma("unroll") for (int k = 0; k < 2; ++k) dst[m][k] = *(const PG8_LAS bf16x8*)(lds + PG8_SA(b, h) + aoff + m * 2048 + k * 1024); } while (0)
; #define PG8_LDB(dst, b, h) do { _Pragma("unroll") for (int n = 0; n < 2; ++n) _Pragma("unroll") for (int k = 0; k < 2; ++k) dst[n][k] = *(const PG8_LAS bf16x8*)(lds + PG8_SB(b, h) + boff + n * 2048 + k * 1024); } while (0)
; #define PG8_MMA(ai, bj, At, Bt) do { __builtin_amdgcn_s_setprio(1); _Pragma("unroll") for (int m = 0; m < 4; ++m) _Pragma("unroll") for (int n = 0; n < 2; ++n) _Pragma("unroll") for (int k = 0; k < 2; ++k) \
;         acc[ai][bj][m][n] = __builtin_amdgcn_mfma_f32_16x16x32_bf16(Bt[n][k], At[m][k], acc[ai][bj][m][n], 0, 0, 0); __builtin_amdgcn_s_setprio(0); } while (0)
; #define PG8_WAIT_V(n) asm volatile("s_waitcnt vmcnt(" #n ")" ::: "memory")
; #define PG8_WAIT_L(n) asm volatile("s_waitcnt lgkmcnt(" #n ")" ::: "memory")
; #define PG8_BAR __builtin_amdgcn_s_barrier()
; #define PG8_SCHED __builtin_amdgcn_sched_barrier(0)
; template <class Epi, class Sched, bool ALIGN_EPI = false, bool SP2 = false>
; __device__ __forceinline__ void gemm_phase(PG8_LAS unsigned char* lds, const Gemm g, const Sched& S, const Epi& E) {
;     ...
;             PG8_WAIT_V(8); PG8_WAIT_L(0); PG8_BAR; PG8_MMA(1, 0, At, B0); PG8_MMA(1, 1, At, B1); PG8_BAR; PG8_SCHED;
;             PG8_LDB(B0, 1, 0); PG8_LDB(B1, 1, 1); PG8_SCHED; PG8_LDA(At, 1, 0); PG8_STAGE(PG8_SA(0, 1), a2 + hstep, voffA);
;             PG8_WAIT_V(8); PG8_WAIT_L(0); PG8_BAR; PG8_MMA(0, 0, At, B0); PG8_MMA(0, 1, At, B1); PG8_BAR; PG8_SCHED;
	s_setprio 1
	s_waitcnt lgkmcnt(0)
	v_mfma_f32_16x16x32_bf16 v[60:63], v[128:131], v[180:183], v[60:63]
	v_mfma_f32_16x16x32_bf16 v[56:59], v[136:139], v[180:183], v[56:59]
	v_mfma_f32_16x16x32_bf16 v[52:55], v[128:131], v[188:191], v[52:55]
	v_mfma_f32_16x16x32_bf16 v[48:51], v[136:139], v[188:191], v[48:51]
	v_mfma_f32_16x16x32_bf16 v[36:39], v[128:131], v[196:199], v[36:39]
	v_mfma_f32_16x16x32_bf16 v[24:27], v[136:139], v[196:199], v[24:27]
	v_mfma_f32_16x16x32_bf16 v[16:19], v[128:131], v[204:207], v[16:19]
	v_mfma_f32_16x16x32_bf16 v[8:11], v[136:139], v[204:207], v[8:11]
	v_mfma_f32_16x16x32_bf16 v[60:63], v[132:135], v[184:187], v[60:63]
	v_mfma_f32_16x16x32_bf16 v[56:59], v[140:143], v[184:187], v[56:59]
	v_mfma_f32_16x16x32_bf16 v[52:55], v[132:135], v[192:195], v[52:55]
	v_mfma_f32_16x16x32_bf16 v[48:51], v[140:143], v[192:195], v[48:51]
	v_mfma_f32_16x16x32_bf16 v[36:39], v[132:135], v[200:203], v[36:39]
	v_mfma_f32_16x16x32_bf16 v[24:27], v[140:143], v[200:203], v[24:27]
	v_mfma_f32_16x16x32_bf16 v[16:19], v[132:135], v[208:211], v[16:19]
	v_mfma_f32_16x16x32_bf16 v[8:11], v[140:143], v[208:211], v[8:11]
	v_mfma_f32_16x16x32_bf16 v[44:47], v[156:159], v[180:183], v[44:47]
	v_mfma_f32_16x16x32_bf16 v[40:43], v[172:175], v[180:183], v[40:43]
	v_mfma_f32_16x16x32_bf16 v[32:35], v[156:159], v[188:191], v[32:35]
	v_mfma_f32_16x16x32_bf16 v[28:31], v[172:175], v[188:191], v[28:31]
	v_mfma_f32_16x16x32_bf16 v[20:23], v[156:159], v[196:199], v[20:23]
	v_mfma_f32_16x16x32_bf16 v[12:15], v[172:175], v[196:199], v[12:15]
	v_mfma_f32_16x16x32_bf16 v[4:7], v[156:159], v[204:207], v[4:7]
	v_mfma_f32_16x16x32_bf16 v[0:3], v[172:175], v[204:207], v[0:3]
	v_mfma_f32_16x16x32_bf16 v[44:47], v[168:171], v[184:187], v[44:47]
	v_mfma_f32_16x16x32_bf16 v[40:43], v[176:179], v[184:187], v[40:43]
	v_mfma_f32_16x16x32_bf16 v[32:35], v[168:171], v[192:195], v[32:35]
	v_mfma_f32_16x16x32_bf16 v[28:31], v[176:179], v[192:195], v[28:31]
	v_mfma_f32_16x16x32_bf16 v[20:23], v[168:171], v[200:203], v[20:23]
	v_mfma_f32_16x16x32_bf16 v[12:15], v[176:179], v[200:203], v[12:15]
	v_mfma_f32_16x16x32_bf16 v[4:7], v[168:171], v[208:211], v[4:7]
	v_mfma_f32_16x16x32_bf16 v[0:3], v[176:179], v[208:211], v[0:3]
	s_setprio 0
	s_barrier
	s_add_i32 s58, 0, 0x18000
	s_add_i32 s59, 0, 0x1c000
	v_add_u32_e32 v140, s58, v163
	v_add_u32_e32 v176, s59, v163
	ds_read_b128 v[128:131], v140
	ds_read_b128 v[132:135], v140 offset:1024
	ds_read_b128 v[136:139], v140 offset:2048
	ds_read_b128 v[140:143], v140 offset:3072
	ds_read_b128 v[156:159], v176
	ds_read_b128 v[168:171], v176 offset:1024
	ds_read_b128 v[172:175], v176 offset:2048
	ds_read_b128 v[176:179], v176 offset:3072
	s_add_u32 s26, s34, 0x80000
	s_addc_u32 s27, s35, 0
	s_mov_b32 m0, s42
	v_lshl_add_u64 v[218:219], s[26:27], 0, v[144:145]
	ds_read_b128 v[180:183], v167 offset:32768
	ds_read_b128 v[184:187], v167 offset:33792
	ds_read_b128 v[188:191], v167 offset:34816
	ds_read_b128 v[192:195], v167 offset:35840
	ds_read_b128 v[196:199], v167 offset:36864
	ds_read_b128 v[200:203], v167 offset:37888
	ds_read_b128 v[204:207], v167 offset:38912
	ds_read_b128 v[208:211], v167 offset:39936
	global_load_lds_dwordx4 v[218:219], off
	v_lshl_add_u64 v[218:219], s[26:27], 0, v[146:147]
	s_mov_b32 m0, s43
	s_nop 0
	global_load_lds_dwordx4 v[218:219], off
	s_waitcnt vmcnt(8)
	s_waitcnt lgkmcnt(0)
	s_barrier
	s_setprio 1
	s_waitcnt lgkmcnt(0)
	v_mfma_f32_16x16x32_bf16 v[124:127], v[128:131], v[180:183], v[124:127]
	v_mfma_f32_16x16x32_bf16 v[120:123], v[136:139], v[180:183], v[120:123]
	v_mfma_f32_16x16x32_bf16 v[116:119], v[128:131], v[188:191], v[116:119]
	v_mfma_f32_16x16x32_bf16 v[112:115], v[136:139], v[188:191], v[112:115]
	v_mfma_f32_16x16x32_bf16 v[92:95], v[128:131], v[196:199], v[92:95]
	v_mfma_f32_16x16x32_bf16 v[88:91], v[136:139], v[196:199], v[88:91]
	v_mfma_f32_16x16x32_bf16 v[84:87], v[128:131], v[204:207], v[84:87]
	v_mfma_f32_16x16x32_bf16 v[80:83], v[136:139], v[204:207], v[80:83]
	v_mfma_f32_16x16x32_bf16 v[124:127], v[132:135], v[184:187], v[124:127]
	v_mfma_f32_16x16x32_bf16 v[120:123], v[140:143], v[184:187], v[120:123]
	v_mfma_f32_16x16x32_bf16 v[116:119], v[132:135], v[192:195], v[116:119]
	v_mfma_f32_16x16x32_bf16 v[112:115], v[140:143], v[192:195], v[112:115]
	v_mfma_f32_16x16x32_bf16 v[92:95], v[132:135], v[200:203], v[92:95]
	v_mfma_f32_16x16x32_bf16 v[88:91], v[140:143], v[200:203], v[88:91]
	v_mfma_f32_16x16x32_bf16 v[84:87], v[132:135], v[208:211], v[84:87]
	v_mfma_f32_16x16x32_bf16 v[80:83], v[140:143], v[208:211], v[80:83]
	v_mfma_f32_16x16x32_bf16 v[108:111], v[156:159], v[180:183], v[108:111]
	v_mfma_f32_16x16x32_bf16 v[104:107], v[172:175], v[180:183], v[104:107]
	v_mfma_f32_16x16x32_bf16 v[100:103], v[156:159], v[188:191], v[100:103]
	v_mfma_f32_16x16x32_bf16 v[96:99], v[172:175], v[188:191], v[96:99]
	v_mfma_f32_16x16x32_bf16 v[76:79], v[156:159], v[196:199], v[76:79]
	v_mfma_f32_16x16x32_bf16 v[72:75], v[172:175], v[196:199], v[72:75]
	v_mfma_f32_16x16x32_bf16 v[68:71], v[156:159], v[204:207], v[68:71]
	v_mfma_f32_16x16x32_bf16 v[64:67], v[172:175], v[204:207], v[64:67]
	v_mfma_f32_16x16x32_bf16 v[108:111], v[168:171], v[184:187], v[108:111]
	v_mfma_f32_16x16x32_bf16 v[104:107], v[176:179], v[184:187], v[104:107]
	v_mfma_f32_16x16x32_bf16 v[100:103], v[168:171], v[192:195], v[100:103]
	v_mfma_f32_16x16x32_bf16 v[96:99], v[176:179], v[192:195], v[96:99]
	v_mfma_f32_16x16x32_bf16 v[76:79], v[168:171], v[200:203], v[76:79]
	v_mfma_f32_16x16x32_bf16 v[72:75], v[176:179], v[200:203], v[72:75]
	v_mfma_f32_16x16x32_bf16 v[68:71], v[168:171], v[208:211], v[68:71]
	v_mfma_f32_16x16x32_bf16 v[64:67], v[176:179], v[208:211], v[64:67]
	s_setprio 0
	s_barrier
; #define PG8_STAGE(bufoff, gbase, voff) do { _Pragma("unroll") for (int _i = 0; _i < 2; ++_i) \
;         __builtin_amdgcn_global_load_lds((const unsigned*)((const char*)(gbase) + (voff)[_i]), (PG8_LAS unsigned*)(lds + (bufoff) + ldsw + _i * 8192), 16, 0, 0); } while (0)
; #define PG8_LDA(dst, b, h) do { _Pragma("unroll") for (int m = 0; m < 4; ++m) _Pragma("unroll") for (int k = 0; k < 2; ++k) dst[m][k] = *(const PG8_LAS bf16x8*)(lds + PG8_SA(b, h) + aoff + m * 2048 + k * 1024); } while (0)
; #define PG8_MMA(ai, bj, At, Bt) do { __builtin_amdgcn_s_setprio(1); _Pragma("unroll") for (int m = 0; m < 4; ++m) _Pragma("unroll") for (int n = 0; n < 2; ++n) _Pragma("unroll") for (int k = 0; k < 2; ++k) \
;         acc[ai][bj][m][n] = __builtin_amdgcn_mfma_f32_16x16x32_bf16(Bt[n][k], At[m][k], acc[ai][bj][m][n], 0, 0, 0); __builtin_amdgcn_s_setprio(0); } while (0)
; #define PG8_WAIT_V(n) asm volatile("s_waitcnt vmcnt(" #n ")" ::: "memory")
; #define PG8_WAIT_L(n) asm volatile("s_waitcnt lgkmcnt(" #n ")" ::: "memory")
; #define PG8_BAR __builtin_amdgcn_s_barrier()
; #define PG8_SCHED __builtin_amdgcn_sched_barrier(0)
; template <class Epi, class Sched, bool ALIGN_EPI = false, bool SP2 = false>
; __device__ __forceinline__ void gemm_phase(PG8_LAS unsigned char* lds, const Gemm g, const Sched& S, const Epi& E) {
;     ...
;         for (int t = 0; t < nt; t += 2) {
;     ...
;             PG8_LDA(At, 1, 1); PG8_STAGE(PG8_SB(1, 0), b3, voffB); PG8_STAGE(PG8_SB(1, 1), b3 + hstep, voffB); PG8_STAGE(PG8_SA(1, 0), a3, voffA);
;             PG8_WAIT_V(8); PG8_WAIT_L(0); PG8_BAR; PG8_MMA(1, 0, At, B0); PG8_MMA(1, 1, At, B1); PG8_BAR; PG8_SCHED;
	s_add_i32 s26, s58, s40
	v_lshl_add_u64 v[160:161], v[160:161], 0, s[8:9]
	s_mov_b32 m0, s26
	ds_read_b128 v[180:183], v167 offset:49152
	ds_read_b128 v[184:187], v167 offset:50176
	ds_read_b128 v[188:191], v167 offset:51200
	ds_read_b128 v[192:195], v167 offset:52224
	ds_read_b128 v[196:199], v167 offset:53248
	ds_read_b128 v[200:203], v167 offset:54272
	ds_read_b128 v[204:207], v167 offset:55296
	ds_read_b128 v[208:211], v167 offset:56320
	global_load_lds_dwordx4 v[160:161], off
	s_add_i32 m0, s26, 0x2000
	s_add_u32 s26, s30, 0x80080
	v_lshl_add_u64 v[160:161], v[212:213], 0, s[8:9]
	s_addc_u32 s27, s31, 0
	s_add_i32 s30, s59, s40
	global_load_lds_dwordx4 v[160:161], off
	v_lshl_add_u64 v[160:161], s[26:27], 0, v[144:145]
	s_mov_b32 m0, s30
	s_nop 0
	global_load_lds_dwordx4 v[160:161], off
	v_lshl_add_u64 v[160:161], s[26:27], 0, v[146:147]
	s_add_i32 m0, s30, 0x2000
	s_nop 0
	global_load_lds_dwordx4 v[160:161], off
	v_lshl_add_u64 v[160:161], v[214:215], 0, s[8:9]
	s_mov_b32 m0, s47
	s_nop 0
	global_load_lds_dwordx4 v[160:161], off
	v_lshl_add_u64 v[160:161], v[216:217], 0, s[8:9]
	s_mov_b32 m0, s48
	s_nop 0
	global_load_lds_dwordx4 v[160:161], off
	s_waitcnt vmcnt(8)
	s_waitcnt lgkmcnt(0)
	s_barrier
	s_setprio 1
	s_waitcnt lgkmcnt(0)
	v_mfma_f32_16x16x32_bf16 v[60:63], v[128:131], v[180:183], v[60:63]
	v_mfma_f32_16x16x32_bf16 v[56:59], v[136:139], v[180:183], v[56:59]
	v_mfma_f32_16x16x32_bf16 v[52:55], v[128:131], v[188:191], v[52:55]
	v_mfma_f32_16x16x32_bf16 v[48:51], v[136:139], v[188:191], v[48:51]
	v_mfma_f32_16x16x32_bf16 v[36:39], v[128:131], v[196:199], v[36:39]
	v_mfma_f32_16x16x32_bf16 v[24:27], v[136:139], v[196:199], v[24:27]
	v_mfma_f32_16x16x32_bf16 v[16:19], v[128:131], v[204:207], v[16:19]
	v_mfma_f32_16x16x32_bf16 v[8:11], v[136:139], v[204:207], v[8:11]
	v_mfma_f32_16x16x32_bf16 v[60:63], v[132:135], v[184:187], v[60:63]
	v_mfma_f32_16x16x32_bf16 v[56:59], v[140:143], v[184:187], v[56:59]
	v_mfma_f32_16x16x32_bf16 v[52:55], v[132:135], v[192:195], v[52:55]
	v_mfma_f32_16x16x32_bf16 v[48:51], v[140:143], v[192:195], v[48:51]
	v_mfma_f32_16x16x32_bf16 v[36:39], v[132:135], v[200:203], v[36:39]
	v_mfma_f32_16x16x32_bf16 v[24:27], v[140:143], v[200:203], v[24:27]
	v_mfma_f32_16x16x32_bf16 v[16:19], v[132:135], v[208:211], v[16:19]
	v_mfma_f32_16x16x32_bf16 v[8:11], v[140:143], v[208:211], v[8:11]
	v_mfma_f32_16x16x32_bf16 v[44:47], v[156:159], v[180:183], v[44:47]
	v_mfma_f32_16x16x32_bf16 v[40:43], v[172:175], v[180:183], v[40:43]
	v_mfma_f32_16x16x32_bf16 v[32:35], v[156:159], v[188:191], v[32:35]
	v_mfma_f32_16x16x32_bf16 v[28:31], v[172:175], v[188:191], v[28:31]
	v_mfma_f32_16x16x32_bf16 v[20:23], v[156:159], v[196:199], v[20:23]
	v_mfma_f32_16x16x32_bf16 v[12:15], v[172:175], v[196:199], v[12:15]
	v_mfma_f32_16x16x32_bf16 v[4:7], v[156:159], v[204:207], v[4:7]
	v_mfma_f32_16x16x32_bf16 v[0:3], v[172:175], v[204:207], v[0:3]
	v_mfma_f32_16x16x32_bf16 v[44:47], v[168:171], v[184:187], v[44:47]
	v_mfma_f32_16x16x32_bf16 v[40:43], v[176:179], v[184:187], v[40:43]
	v_mfma_f32_16x16x32_bf16 v[32:35], v[168:171], v[192:195], v[32:35]
	v_mfma_f32_16x16x32_bf16 v[28:31], v[176:179], v[192:195], v[28:31]
	v_mfma_f32_16x16x32_bf16 v[20:23], v[168:171], v[200:203], v[20:23]
	v_mfma_f32_16x16x32_bf16 v[12:15], v[176:179], v[200:203], v[12:15]
	v_mfma_f32_16x16x32_bf16 v[4:7], v[168:171], v[208:211], v[4:7]
	v_mfma_f32_16x16x32_bf16 v[0:3], v[176:179], v[208:211], v[0:3]
	s_setprio 0
	s_barrier
	s_add_i32 s57, s57, 2
	s_add_u32 s55, s55, 0x100
	s_addc_u32 s56, s56, 0
	s_cmp_gt_u32 s57, 29
	s_mov_b64 s[26:27], s[28:29]
	s_cbranch_scc0 .LBB0_1274
	s_and_b64 vcc, exec, s[10:11]
	s_cbranch_vccz .LBB0_1277
	s_barrier

; #define PG8_STAGE(bufoff, gbase, voff) do { _Pragma("unroll") for (int _i = 0; _i < 2; ++_i) \
;         __builtin_amdgcn_global_load_lds((const unsigned*)((const char*)(gbase) + (voff)[_i]), (PG8_LAS unsigned*)(lds + (bufoff) + ldsw + _i * 8192), 16, 0, 0); } while (0)
; #define PG8_LDA(dst, b, h) do { _Pragma("unroll") for (int m = 0; m < 4; ++m) _Pragma("unroll") for (int k = 0; k < 2; ++k) dst[m][k] = *(const PG8_LAS bf16x8*)(lds + PG8_SA(b, h) + aoff + m * 2048 + k * 1024); } while (0)
; #define PG8_LDB(dst, b, h) do { _Pragma("unroll") for (int n = 0; n < 2; ++n) _Pragma("unroll") for (int k = 0; k < 2; ++k) dst[n][k] = *(const PG8_LAS bf16x8*)(lds + PG8_SB(b, h) + boff + n * 2048 + k * 1024); } while (0)
; #define PG8_MMA(ai, bj, At, Bt) do { __builtin_amdgcn_s_setprio(1); _Pragma("unroll") for (int m = 0; m < 4; ++m) _Pragma("unroll") for (int n = 0; n < 2; ++n) _Pragma("unroll") for (int k = 0; k < 2; ++k) \
;         acc[ai][bj][m][n] = __builtin_amdgcn_mfma_f32_16x16x32_bf16(Bt[n][k], At[m][k], acc[ai][bj][m][n], 0, 0, 0); __builtin_amdgcn_s_setprio(0); } while (0)
; #define PG8_WAIT_V(n) asm volatile("s_waitcnt vmcnt(" #n ")" ::: "memory")
; #define PG8_WAIT_L(n) asm volatile("s_waitcnt lgkmcnt(" #n ")" ::: "memory")
; #define PG8_BAR __builtin_amdgcn_s_barrier()
; #define PG8_SCHED __builtin_amdgcn_sched_barrier(0)
; template <class Epi, class Sched, bool ALIGN_EPI = false, bool SP2 = false>
; __device__ __forceinline__ void gemm_phase(PG8_LAS unsigned char* lds, const Gemm g, const Sched& S, const Epi& E) {
;     ...
;             PG8_LDB(B0, 0, 0); PG8_LDB(B1, 0, 1); PG8_SCHED; PG8_LDA(At, 0, 0); PG8_STAGE(PG8_SA(1, 1), a1 + hstep, voffA);
;             PG8_WAIT_V(8); PG8_WAIT_L(0); PG8_BAR; PG8_MMA(0, 0, At, B0); PG8_MMA(0, 1, At, B1); PG8_BAR; PG8_SCHED;
;             PG8_LDA(At, 0, 1); PG8_STAGE(PG8_SB(0, 0), b2, voffB); PG8_STAGE(PG8_SB(0, 1), b2 + hstep, voffB); PG8_STAGE(PG8_SA(0, 0), a2, voffA);
;             PG8_WAIT_V(8); PG8_WAIT_L(0); PG8_BAR; PG8_MMA(1, 0, At, B0); PG8_MMA(1, 1, At, B1); PG8_BAR; PG8_SCHED;
.LBB0_1399:
	ds_read_b128 v[120:123], v196
	ds_read_b128 v[124:127], v196 offset:1024
	ds_read_b128 v[128:131], v196 offset:2048
	ds_read_b128 v[132:135], v196 offset:3072
	ds_read_b128 v[136:139], v197
	ds_read_b128 v[140:143], v197 offset:1024
	ds_read_b128 v[144:147], v197 offset:2048
	ds_read_b128 v[148:151], v197 offset:3072
	s_add_u32 s54, s4, 0xfff80080
	s_addc_u32 s55, s5, -1
	s_cmp_eq_u32 s81, 28
	s_cselect_b32 s57, s49, s55
	s_cselect_b32 s56, s77, s54
	s_cselect_b32 s55, s47, s80
	s_cselect_b32 s54, s78, s79
	v_lshl_add_u64 v[188:189], s[4:5], 0, v[174:175]
	s_add_i32 m0, s63, 0xc000
	ds_read_b128 v[160:163], v198
	ds_read_b128 v[164:167], v198 offset:1024
	ds_read_b128 v[180:183], v198 offset:2048
	ds_read_b128 v[184:187], v198 offset:3072
	ds_read_b128 v[202:205], v198 offset:4096
	ds_read_b128 v[206:209], v198 offset:5120
	ds_read_b128 v[210:213], v198 offset:6144
	ds_read_b128 v[214:217], v198 offset:7168
	global_load_lds_dwordx4 v[188:189], off
	v_lshl_add_u64 v[188:189], s[4:5], 0, v[172:173]
	s_add_i32 m0, s63, 0xe000
	s_nop 0
	global_load_lds_dwordx4 v[188:189], off
	s_waitcnt vmcnt(8)
	s_waitcnt lgkmcnt(0)
	s_barrier
	s_setprio 1
	s_waitcnt lgkmcnt(0)
	v_mfma_f32_16x16x32_bf16 v[156:159], v[120:123], v[160:163], v[156:159]
	v_mfma_f32_16x16x32_bf16 v[60:63], v[128:131], v[160:163], v[60:63]
	v_mfma_f32_16x16x32_bf16 v[116:119], v[120:123], v[180:183], v[116:119]
	v_mfma_f32_16x16x32_bf16 v[52:55], v[128:131], v[180:183], v[52:55]
	v_mfma_f32_16x16x32_bf16 v[108:111], v[120:123], v[202:205], v[108:111]
	v_mfma_f32_16x16x32_bf16 v[44:47], v[128:131], v[202:205], v[44:47]
	v_mfma_f32_16x16x32_bf16 v[104:107], v[120:123], v[210:213], v[104:107]
	v_mfma_f32_16x16x32_bf16 v[40:43], v[128:131], v[210:213], v[40:43]
	v_mfma_f32_16x16x32_bf16 v[156:159], v[124:127], v[164:167], v[156:159]
	v_mfma_f32_16x16x32_bf16 v[60:63], v[132:135], v[164:167], v[60:63]
	v_mfma_f32_16x16x32_bf16 v[116:119], v[124:127], v[184:187], v[116:119]
	v_mfma_f32_16x16x32_bf16 v[52:55], v[132:135], v[184:187], v[52:55]
	v_mfma_f32_16x16x32_bf16 v[108:111], v[124:127], v[206:209], v[108:111]
	v_mfma_f32_16x16x32_bf16 v[44:47], v[132:135], v[206:209], v[44:47]
	v_mfma_f32_16x16x32_bf16 v[104:107], v[124:127], v[214:217], v[104:107]
	v_mfma_f32_16x16x32_bf16 v[40:43], v[132:135], v[214:217], v[40:43]
	v_mfma_f32_16x16x32_bf16 v[152:155], v[136:139], v[160:163], v[152:155]
	v_mfma_f32_16x16x32_bf16 v[56:59], v[144:147], v[160:163], v[56:59]
	v_mfma_f32_16x16x32_bf16 v[112:115], v[136:139], v[180:183], v[112:115]
	v_mfma_f32_16x16x32_bf16 v[48:51], v[144:147], v[180:183], v[48:51]
	v_mfma_f32_16x16x32_bf16 v[100:103], v[136:139], v[202:205], v[100:103]
	v_mfma_f32_16x16x32_bf16 v[36:39], v[144:147], v[202:205], v[36:39]
	v_mfma_f32_16x16x32_bf16 v[96:99], v[136:139], v[210:213], v[96:99]
	v_mfma_f32_16x16x32_bf16 v[32:35], v[144:147], v[210:213], v[32:35]
	v_mfma_f32_16x16x32_bf16 v[152:155], v[140:143], v[164:167], v[152:155]
	v_mfma_f32_16x16x32_bf16 v[56:59], v[148:151], v[164:167], v[56:59]
	v_mfma_f32_16x16x32_bf16 v[112:115], v[140:143], v[184:187], v[112:115]
	v_mfma_f32_16x16x32_bf16 v[48:51], v[148:151], v[184:187], v[48:51]
	v_mfma_f32_16x16x32_bf16 v[100:103], v[140:143], v[206:209], v[100:103]
	v_mfma_f32_16x16x32_bf16 v[36:39], v[148:151], v[206:209], v[36:39]
	v_mfma_f32_16x16x32_bf16 v[96:99], v[140:143], v[214:217], v[96:99]
	v_mfma_f32_16x16x32_bf16 v[32:35], v[148:151], v[214:217], v[32:35]
	s_setprio 0
	s_barrier
	s_add_i32 s82, s72, s62
	v_lshl_add_u64 v[188:189], s[54:55], 0, v[170:171]
	s_mov_b32 m0, s82
	ds_read_b128 v[160:163], v198 offset:16384
	ds_read_b128 v[164:167], v198 offset:17408
	ds_read_b128 v[180:183], v198 offset:18432
	ds_read_b128 v[184:187], v198 offset:19456
	ds_read_b128 v[202:205], v198 offset:20480
	ds_read_b128 v[206:209], v198 offset:21504
	ds_read_b128 v[210:213], v198 offset:22528
	ds_read_b128 v[214:217], v198 offset:23552
	global_load_lds_dwordx4 v[188:189], off
	s_add_i32 m0, s82, 0x2000
	s_add_u32 s82, s54, 0x80000
	v_lshl_add_u64 v[218:219], s[54:55], 0, v[168:169]
	s_addc_u32 s83, s55, 0
	s_add_i32 s85, s73, s62
	global_load_lds_dwordx4 v[218:219], off
	v_lshl_add_u64 v[222:223], s[82:83], 0, v[170:171]
	s_mov_b32 m0, s85
	v_lshl_add_u64 v[224:225], s[56:57], 0, v[168:169]
	global_load_lds_dwordx4 v[222:223], off
	v_lshl_add_u64 v[222:223], s[82:83], 0, v[168:169]
	s_add_i32 m0, s85, 0x2000
	s_nop 0
	global_load_lds_dwordx4 v[222:223], off
	v_lshl_add_u64 v[222:223], s[56:57], 0, v[170:171]
	s_mov_b32 m0, s63
	s_nop 0
	global_load_lds_dwordx4 v[222:223], off
	s_mov_b32 m0, s64
	s_nop 0
	global_load_lds_dwordx4 v[224:225], off
	s_waitcnt vmcnt(8)
	s_waitcnt lgkmcnt(0)
	s_barrier
; #define PG8_STAGE(bufoff, gbase, voff) do { _Pragma("unroll") for (int _i = 0; _i < 2; ++_i) \
;         __builtin_amdgcn_global_load_lds((const unsigned*)((const char*)(gbase) + (voff)[_i]), (PG8_LAS unsigned*)(lds + (bufoff) + ldsw + _i * 8192), 16, 0, 0); } while (0)
; #define PG8_LDA(dst, b, h) do { _Pragma("unroll") for (int m = 0; m < 4; ++m) _Pragma("unroll") for (int k = 0; k < 2; ++k) dst[m][k] = *(const PG8_LAS bf16x8*)(lds + PG8_SA(b, h) + aoff + m * 2048 + k * 1024); } while (0)
; #define PG8_LDB(dst, b, h) do { _Pragma("unroll") for (int n = 0; n < 2; ++n) _Pragma("unroll") for (int k = 0; k < 2; ++k) dst[n][k] = *(const PG8_LAS bf16x8*)(lds + PG8_SB(b, h) + boff + n * 2048 + k * 1024); } while (0)
; #define PG8_MMA(ai, bj, At, Bt) do { __builtin_amdgcn_s_setprio(1); _Pragma("unroll") for (int m = 0; m < 4; ++m) _Pragma("unroll") for (int n = 0; n < 2; ++n) _Pragma("unroll") for (int k = 0; k < 2; ++k) \
;         acc[ai][bj][m][n] = __builtin_amdgcn_mfma_f32_16x16x32_bf16(Bt[n][k], At[m][k], acc[ai][bj][m][n], 0, 0, 0); __builtin_amdgcn_s_setprio(0); } while (0)
; #define PG8_WAIT_V(n) asm volatile("s_waitcnt vmcnt(" #n ")" ::: "memory")
; #define PG8_WAIT_L(n) asm volatile("s_waitcnt lgkmcnt(" #n ")" ::: "memory")
; #define PG8_BAR __builtin_amdgcn_s_barrier()
; #define PG8_SCHED __builtin_amdgcn_sched_barrier(0)
; template <class Epi, class Sched, bool ALIGN_EPI = false, bool SP2 = false>
; __device__ __forceinline__ void gemm_phase(PG8_LAS unsigned char* lds, const Gemm g, const Sched& S, const Epi& E) {
;     ...
;             PG8_WAIT_V(8); PG8_WAIT_L(0); PG8_BAR; PG8_MMA(1, 0, At, B0); PG8_MMA(1, 1, At, B1); PG8_BAR; PG8_SCHED;
;             PG8_LDB(B0, 1, 0); PG8_LDB(B1, 1, 1); PG8_SCHED; PG8_LDA(At, 1, 0); PG8_STAGE(PG8_SA(0, 1), a2 + hstep, voffA);
;             PG8_WAIT_V(8); PG8_WAIT_L(0); PG8_BAR; PG8_MMA(0, 0, At, B0); PG8_MMA(0, 1, At, B1); PG8_BAR; PG8_SCHED;
	s_setprio 1
	s_waitcnt lgkmcnt(0)
	v_mfma_f32_16x16x32_bf16 v[92:95], v[120:123], v[160:163], v[92:95]
	v_mfma_f32_16x16x32_bf16 v[28:31], v[128:131], v[160:163], v[28:31]
	v_mfma_f32_16x16x32_bf16 v[84:87], v[120:123], v[180:183], v[84:87]
	v_mfma_f32_16x16x32_bf16 v[20:23], v[128:131], v[180:183], v[20:23]
	v_mfma_f32_16x16x32_bf16 v[76:79], v[120:123], v[202:205], v[76:79]
	v_mfma_f32_16x16x32_bf16 v[12:15], v[128:131], v[202:205], v[12:15]
	v_mfma_f32_16x16x32_bf16 v[72:75], v[120:123], v[210:213], v[72:75]
	v_mfma_f32_16x16x32_bf16 v[8:11], v[128:131], v[210:213], v[8:11]
	v_mfma_f32_16x16x32_bf16 v[92:95], v[124:127], v[164:167], v[92:95]
	v_mfma_f32_16x16x32_bf16 v[28:31], v[132:135], v[164:167], v[28:31]
	v_mfma_f32_16x16x32_bf16 v[84:87], v[124:127], v[184:187], v[84:87]
	v_mfma_f32_16x16x32_bf16 v[20:23], v[132:135], v[184:187], v[20:23]
	v_mfma_f32_16x16x32_bf16 v[76:79], v[124:127], v[206:209], v[76:79]
	v_mfma_f32_16x16x32_bf16 v[12:15], v[132:135], v[206:209], v[12:15]
	v_mfma_f32_16x16x32_bf16 v[72:75], v[124:127], v[214:217], v[72:75]
	v_mfma_f32_16x16x32_bf16 v[8:11], v[132:135], v[214:217], v[8:11]
	v_mfma_f32_16x16x32_bf16 v[88:91], v[136:139], v[160:163], v[88:91]
	v_mfma_f32_16x16x32_bf16 v[24:27], v[144:147], v[160:163], v[24:27]
	v_mfma_f32_16x16x32_bf16 v[80:83], v[136:139], v[180:183], v[80:83]
	v_mfma_f32_16x16x32_bf16 v[16:19], v[144:147], v[180:183], v[16:19]
	v_mfma_f32_16x16x32_bf16 v[68:71], v[136:139], v[202:205], v[68:71]
	v_mfma_f32_16x16x32_bf16 v[4:7], v[144:147], v[202:205], v[4:7]
	v_mfma_f32_16x16x32_bf16 v[64:67], v[136:139], v[210:213], v[64:67]
	v_mfma_f32_16x16x32_bf16 v[0:3], v[144:147], v[210:213], v[0:3]
	v_mfma_f32_16x16x32_bf16 v[88:91], v[140:143], v[164:167], v[88:91]
	v_mfma_f32_16x16x32_bf16 v[24:27], v[148:151], v[164:167], v[24:27]
	v_mfma_f32_16x16x32_bf16 v[80:83], v[140:143], v[184:187], v[80:83]
	v_mfma_f32_16x16x32_bf16 v[16:19], v[148:151], v[184:187], v[16:19]
	v_mfma_f32_16x16x32_bf16 v[68:71], v[140:143], v[206:209], v[68:71]
	v_mfma_f32_16x16x32_bf16 v[4:7], v[148:151], v[206:209], v[4:7]
	v_mfma_f32_16x16x32_bf16 v[64:67], v[140:143], v[214:217], v[64:67]
	v_mfma_f32_16x16x32_bf16 v[0:3], v[148:151], v[214:217], v[0:3]
	s_setprio 0
	s_barrier
	s_add_i32 s82, 0, 0x18000
	s_add_i32 s83, 0, 0x1c000
	v_add_u32_e32 v132, s82, v192
	v_add_u32_e32 v148, s83, v192
	ds_read_b128 v[120:123], v132
	ds_read_b128 v[124:127], v132 offset:1024
	ds_read_b128 v[128:131], v132 offset:2048
	ds_read_b128 v[132:135], v132 offset:3072
	ds_read_b128 v[136:139], v148
	ds_read_b128 v[140:143], v148 offset:1024
	ds_read_b128 v[144:147], v148 offset:2048
	ds_read_b128 v[148:151], v148 offset:3072
	s_add_u32 s56, s56, 0x80000
	s_addc_u32 s57, s57, 0
	s_mov_b32 m0, s65
	v_lshl_add_u64 v[226:227], s[56:57], 0, v[170:171]
	ds_read_b128 v[160:163], v198 offset:32768
	ds_read_b128 v[164:167], v198 offset:33792
	ds_read_b128 v[180:183], v198 offset:34816
	ds_read_b128 v[184:187], v198 offset:35840
	ds_read_b128 v[202:205], v198 offset:36864
	ds_read_b128 v[206:209], v198 offset:37888
	ds_read_b128 v[210:213], v198 offset:38912
	ds_read_b128 v[214:217], v198 offset:39936
	global_load_lds_dwordx4 v[226:227], off
	v_lshl_add_u64 v[226:227], s[56:57], 0, v[168:169]
	s_mov_b32 m0, s66
	s_nop 0
	global_load_lds_dwordx4 v[226:227], off
	s_waitcnt vmcnt(8)
	s_waitcnt lgkmcnt(0)
	s_barrier
	s_setprio 1
	s_waitcnt lgkmcnt(0)
	v_mfma_f32_16x16x32_bf16 v[156:159], v[120:123], v[160:163], v[156:159]
	v_mfma_f32_16x16x32_bf16 v[60:63], v[128:131], v[160:163], v[60:63]
	v_mfma_f32_16x16x32_bf16 v[116:119], v[120:123], v[180:183], v[116:119]
	v_mfma_f32_16x16x32_bf16 v[52:55], v[128:131], v[180:183], v[52:55]
	v_mfma_f32_16x16x32_bf16 v[108:111], v[120:123], v[202:205], v[108:111]
	v_mfma_f32_16x16x32_bf16 v[44:47], v[128:131], v[202:205], v[44:47]
	v_mfma_f32_16x16x32_bf16 v[104:107], v[120:123], v[210:213], v[104:107]
	v_mfma_f32_16x16x32_bf16 v[40:43], v[128:131], v[210:213], v[40:43]
	v_mfma_f32_16x16x32_bf16 v[156:159], v[124:127], v[164:167], v[156:159]
	v_mfma_f32_16x16x32_bf16 v[60:63], v[132:135], v[164:167], v[60:63]
	v_mfma_f32_16x16x32_bf16 v[116:119], v[124:127], v[184:187], v[116:119]
	v_mfma_f32_16x16x32_bf16 v[52:55], v[132:135], v[184:187], v[52:55]
	v_mfma_f32_16x16x32_bf16 v[108:111], v[124:127], v[206:209], v[108:111]
	v_mfma_f32_16x16x32_bf16 v[44:47], v[132:135], v[206:209], v[44:47]
	v_mfma_f32_16x16x32_bf16 v[104:107], v[124:127], v[214:217], v[104:107]
	v_mfma_f32_16x16x32_bf16 v[40:43], v[132:135], v[214:217], v[40:43]
	v_mfma_f32_16x16x32_bf16 v[152:155], v[136:139], v[160:163], v[152:155]
	v_mfma_f32_16x16x32_bf16 v[56:59], v[144:147], v[160:163], v[56:59]
	v_mfma_f32_16x16x32_bf16 v[112:115], v[136:139], v[180:183], v[112:115]
	v_mfma_f32_16x16x32_bf16 v[48:51], v[144:147], v[180:183], v[48:51]
	v_mfma_f32_16x16x32_bf16 v[100:103], v[136:139], v[202:205], v[100:103]
	v_mfma_f32_16x16x32_bf16 v[36:39], v[144:147], v[202:205], v[36:39]
	v_mfma_f32_16x16x32_bf16 v[96:99], v[136:139], v[210:213], v[96:99]
	v_mfma_f32_16x16x32_bf16 v[32:35], v[144:147], v[210:213], v[32:35]
	v_mfma_f32_16x16x32_bf16 v[152:155], v[140:143], v[164:167], v[152:155]
	v_mfma_f32_16x16x32_bf16 v[56:59], v[148:151], v[164:167], v[56:59]
	v_mfma_f32_16x16x32_bf16 v[112:115], v[140:143], v[184:187], v[112:115]
	v_mfma_f32_16x16x32_bf16 v[48:51], v[148:151], v[184:187], v[48:51]
	v_mfma_f32_16x16x32_bf16 v[100:103], v[140:143], v[206:209], v[100:103]
	v_mfma_f32_16x16x32_bf16 v[36:39], v[148:151], v[206:209], v[36:39]
	v_mfma_f32_16x16x32_bf16 v[96:99], v[140:143], v[214:217], v[96:99]
	v_mfma_f32_16x16x32_bf16 v[32:35], v[148:151], v[214:217], v[32:35]
	s_setprio 0
	s_barrier
; #define PG8_STAGE(bufoff, gbase, voff) do { _Pragma("unroll") for (int _i = 0; _i < 2; ++_i) \
;         __builtin_amdgcn_global_load_lds((const unsigned*)((const char*)(gbase) + (voff)[_i]), (PG8_LAS unsigned*)(lds + (bufoff) + ldsw + _i * 8192), 16, 0, 0); } while (0)
; #define PG8_LDA(dst, b, h) do { _Pragma("unroll") for (int m = 0; m < 4; ++m) _Pragma("unroll") for (int k = 0; k < 2; ++k) dst[m][k] = *(const PG8_LAS bf16x8*)(lds + PG8_SA(b, h) + aoff + m * 2048 + k * 1024); } while (0)
; #define PG8_MMA(ai, bj, At, Bt) do { __builtin_amdgcn_s_setprio(1); _Pragma("unroll") for (int m = 0; m < 4; ++m) _Pragma("unroll") for (int n = 0; n < 2; ++n) _Pragma("unroll") for (int k = 0; k < 2; ++k) \
;         acc[ai][bj][m][n] = __builtin_amdgcn_mfma_f32_16x16x32_bf16(Bt[n][k], At[m][k], acc[ai][bj][m][n], 0, 0, 0); __builtin_amdgcn_s_setprio(0); } while (0)
; #define PG8_WAIT_V(n) asm volatile("s_waitcnt vmcnt(" #n ")" ::: "memory")
; #define PG8_WAIT_L(n) asm volatile("s_waitcnt lgkmcnt(" #n ")" ::: "memory")
; #define PG8_BAR __builtin_amdgcn_s_barrier()
; #define PG8_SCHED __builtin_amdgcn_sched_barrier(0)
; template <class Epi, class Sched, bool ALIGN_EPI = false, bool SP2 = false>
; __device__ __forceinline__ void gemm_phase(PG8_LAS unsigned char* lds, const Gemm g, const Sched& S, const Epi& E) {
;     ...
;         for (int t = 0; t < nt; t += 2) {
;     ...
;             PG8_LDA(At, 1, 1); PG8_STAGE(PG8_SB(1, 0), b3, voffB); PG8_STAGE(PG8_SB(1, 1), b3 + hstep, voffB); PG8_STAGE(PG8_SA(1, 0), a3, voffA);
;             PG8_WAIT_V(8); PG8_WAIT_L(0); PG8_BAR; PG8_MMA(1, 0, At, B0); PG8_MMA(1, 1, At, B1); PG8_BAR; PG8_SCHED;
	s_add_i32 s56, s82, s62
	v_lshl_add_u64 v[188:189], v[188:189], 0, s[26:27]
	s_mov_b32 m0, s56
	ds_read_b128 v[160:163], v198 offset:49152
	ds_read_b128 v[164:167], v198 offset:50176
	ds_read_b128 v[180:183], v198 offset:51200
	ds_read_b128 v[184:187], v198 offset:52224
	ds_read_b128 v[202:205], v198 offset:53248
	ds_read_b128 v[206:209], v198 offset:54272
	ds_read_b128 v[210:213], v198 offset:55296
	ds_read_b128 v[214:217], v198 offset:56320
	global_load_lds_dwordx4 v[188:189], off
	s_add_i32 m0, s56, 0x2000
	s_add_u32 s54, s54, 0x80080
	v_lshl_add_u64 v[188:189], v[218:219], 0, s[26:27]
	s_addc_u32 s55, s55, 0
	s_add_i32 s56, s83, s62
	global_load_lds_dwordx4 v[188:189], off
	v_lshl_add_u64 v[188:189], s[54:55], 0, v[170:171]
	s_mov_b32 m0, s56
	s_nop 0
	global_load_lds_dwordx4 v[188:189], off
	v_lshl_add_u64 v[188:189], s[54:55], 0, v[168:169]
	s_add_i32 m0, s56, 0x2000
	s_nop 0
	global_load_lds_dwordx4 v[188:189], off
	v_lshl_add_u64 v[188:189], v[222:223], 0, s[26:27]
	s_mov_b32 m0, s68
	s_nop 0
	global_load_lds_dwordx4 v[188:189], off
	v_lshl_add_u64 v[188:189], v[224:225], 0, s[26:27]
	s_mov_b32 m0, s69
	s_nop 0
	global_load_lds_dwordx4 v[188:189], off
	s_waitcnt vmcnt(8)
	s_waitcnt lgkmcnt(0)
	s_barrier
	s_setprio 1
	s_waitcnt lgkmcnt(0)
	v_mfma_f32_16x16x32_bf16 v[92:95], v[120:123], v[160:163], v[92:95]
	v_mfma_f32_16x16x32_bf16 v[28:31], v[128:131], v[160:163], v[28:31]
	v_mfma_f32_16x16x32_bf16 v[84:87], v[120:123], v[180:183], v[84:87]
	v_mfma_f32_16x16x32_bf16 v[20:23], v[128:131], v[180:183], v[20:23]
	v_mfma_f32_16x16x32_bf16 v[76:79], v[120:123], v[202:205], v[76:79]
	v_mfma_f32_16x16x32_bf16 v[12:15], v[128:131], v[202:205], v[12:15]
	v_mfma_f32_16x16x32_bf16 v[72:75], v[120:123], v[210:213], v[72:75]
	v_mfma_f32_16x16x32_bf16 v[8:11], v[128:131], v[210:213], v[8:11]
	v_mfma_f32_16x16x32_bf16 v[92:95], v[124:127], v[164:167], v[92:95]
	v_mfma_f32_16x16x32_bf16 v[28:31], v[132:135], v[164:167], v[28:31]
	v_mfma_f32_16x16x32_bf16 v[84:87], v[124:127], v[184:187], v[84:87]
	v_mfma_f32_16x16x32_bf16 v[20:23], v[132:135], v[184:187], v[20:23]
	v_mfma_f32_16x16x32_bf16 v[76:79], v[124:127], v[206:209], v[76:79]
	v_mfma_f32_16x16x32_bf16 v[12:15], v[132:135], v[206:209], v[12:15]
	v_mfma_f32_16x16x32_bf16 v[72:75], v[124:127], v[214:217], v[72:75]
	v_mfma_f32_16x16x32_bf16 v[8:11], v[132:135], v[214:217], v[8:11]
	v_mfma_f32_16x16x32_bf16 v[88:91], v[136:139], v[160:163], v[88:91]
	v_mfma_f32_16x16x32_bf16 v[24:27], v[144:147], v[160:163], v[24:27]
	v_mfma_f32_16x16x32_bf16 v[80:83], v[136:139], v[180:183], v[80:83]
	v_mfma_f32_16x16x32_bf16 v[16:19], v[144:147], v[180:183], v[16:19]
	v_mfma_f32_16x16x32_bf16 v[68:71], v[136:139], v[202:205], v[68:71]
	v_mfma_f32_16x16x32_bf16 v[4:7], v[144:147], v[202:205], v[4:7]
	v_mfma_f32_16x16x32_bf16 v[64:67], v[136:139], v[210:213], v[64:67]
	v_mfma_f32_16x16x32_bf16 v[0:3], v[144:147], v[210:213], v[0:3]
	v_mfma_f32_16x16x32_bf16 v[88:91], v[140:143], v[164:167], v[88:91]
	v_mfma_f32_16x16x32_bf16 v[24:27], v[148:151], v[164:167], v[24:27]
	v_mfma_f32_16x16x32_bf16 v[80:83], v[140:143], v[184:187], v[80:83]
	v_mfma_f32_16x16x32_bf16 v[16:19], v[148:151], v[184:187], v[16:19]
	v_mfma_f32_16x16x32_bf16 v[68:71], v[140:143], v[206:209], v[68:71]
	v_mfma_f32_16x16x32_bf16 v[4:7], v[148:151], v[206:209], v[4:7]
	v_mfma_f32_16x16x32_bf16 v[64:67], v[140:143], v[214:217], v[64:67]
	v_mfma_f32_16x16x32_bf16 v[0:3], v[148:151], v[214:217], v[0:3]
	s_setprio 0
	s_barrier
	s_add_i32 s81, s81, 2
	s_add_u32 s79, s79, 0x100
	s_addc_u32 s80, s80, 0
	s_add_u32 s4, s4, 0x100
	s_addc_u32 s5, s5, 0
	s_cmp_gt_u32 s81, 29
	s_cbranch_scc0 .LBB0_1399
	s_and_b64 vcc, exec, s[28:29]
	s_cbranch_vccz .LBB0_1402
	s_barrier

; #define PG8_STAGE(bufoff, gbase, voff) do { _Pragma("unroll") for (int _i = 0; _i < 2; ++_i) \
;         __builtin_amdgcn_global_load_lds((const unsigned*)((const char*)(gbase) + (voff)[_i]), (PG8_LAS unsigned*)(lds + (bufoff) + ldsw + _i * 8192), 16, 0, 0); } while (0)
; #define PG8_LDA(dst, b, h) do { _Pragma("unroll") for (int m = 0; m < 4; ++m) _Pragma("unroll") for (int k = 0; k < 2; ++k) dst[m][k] = *(const PG8_LAS bf16x8*)(lds + PG8_SA(b, h) + aoff + m * 2048 + k * 1024); } while (0)
; #define PG8_LDB(dst, b, h) do { _Pragma("unroll") for (int n = 0; n < 2; ++n) _Pragma("unroll") for (int k = 0; k < 2; ++k) dst[n][k] = *(const PG8_LAS bf16x8*)(lds + PG8_SB(b, h) + boff + n * 2048 + k * 1024); } while (0)
; #define PG8_MMA(ai, bj, At, Bt) do { __builtin_amdgcn_s_setprio(1); _Pragma("unroll") for (int m = 0; m < 4; ++m) _Pragma("unroll") for (int n = 0; n < 2; ++n) _Pragma("unroll") for (int k = 0; k < 2; ++k) \
;         acc[ai][bj][m][n] = __builtin_amdgcn_mfma_f32_16x16x32_bf16(Bt[n][k], At[m][k], acc[ai][bj][m][n], 0, 0, 0); __builtin_amdgcn_s_setprio(0); } while (0)
; #define PG8_WAIT_V(n) asm volatile("s_waitcnt vmcnt(" #n ")" ::: "memory")
; #define PG8_WAIT_L(n) asm volatile("s_waitcnt lgkmcnt(" #n ")" ::: "memory")
; #define PG8_BAR __builtin_amdgcn_s_barrier()
; #define PG8_SCHED __builtin_amdgcn_sched_barrier(0)
; template <class Epi, class Sched, bool ALIGN_EPI = false, bool SP2 = false>
; __device__ __forceinline__ void gemm_phase(PG8_LAS unsigned char* lds, const Gemm g, const Sched& S, const Epi& E) {
;     ...
;             PG8_LDB(B0, 0, 0); PG8_LDB(B1, 0, 1); PG8_SCHED; PG8_LDA(At, 0, 0); PG8_STAGE(PG8_SA(1, 1), a1 + hstep, voffA);
;             PG8_WAIT_V(8); PG8_WAIT_L(0); PG8_BAR; PG8_MMA(0, 0, At, B0); PG8_MMA(0, 1, At, B1); PG8_BAR; PG8_SCHED;
;             PG8_LDA(At, 0, 1); PG8_STAGE(PG8_SB(0, 0), b2, voffB); PG8_STAGE(PG8_SB(0, 1), b2 + hstep, voffB); PG8_STAGE(PG8_SA(0, 0), a2, voffA);
;             PG8_WAIT_V(8); PG8_WAIT_L(0); PG8_BAR; PG8_MMA(1, 0, At, B0); PG8_MMA(1, 1, At, B1); PG8_BAR; PG8_SCHED;
.LBB0_1541:
	ds_read_b128 v[104:107], v195
	ds_read_b128 v[108:111], v195 offset:1024
	ds_read_b128 v[116:119], v195 offset:2048
	ds_read_b128 v[124:127], v195 offset:3072
	ds_read_b128 v[160:163], v196
	ds_read_b128 v[164:167], v196 offset:1024
	ds_read_b128 v[168:171], v196 offset:2048
	ds_read_b128 v[172:175], v196 offset:3072
	s_add_u32 s34, s30, 0x100
	s_addc_u32 s35, s31, 0
	s_cmpk_eq_i32 s63, 0x54
	s_cselect_b32 s39, s27, s35
	s_cselect_b32 s38, s26, s34
	s_cselect_b32 s37, s15, s29
	s_cselect_b32 s36, s14, s28
	s_mov_b32 m0, s51
	v_lshl_add_u64 v[192:193], s[30:31], 0, v[158:159]
	ds_read_b128 v[176:179], v197
	ds_read_b128 v[180:183], v197 offset:1024
	ds_read_b128 v[184:187], v197 offset:2048
	ds_read_b128 v[188:191], v197 offset:3072
	ds_read_b128 v[202:205], v197 offset:4096
	ds_read_b128 v[206:209], v197 offset:5120
	ds_read_b128 v[210:213], v197 offset:6144
	ds_read_b128 v[214:217], v197 offset:7168
	global_load_lds_dwordx4 v[192:193], off
	v_lshl_add_u64 v[192:193], s[30:31], 0, v[156:157]
	s_mov_b32 m0, s52
	s_nop 0
	global_load_lds_dwordx4 v[192:193], off
	s_waitcnt vmcnt(8)
	s_waitcnt lgkmcnt(0)
	s_barrier
	s_setprio 1
	s_waitcnt lgkmcnt(0)
	v_mfma_f32_16x16x32_bf16 v[140:143], v[104:107], v[176:179], v[140:143]
	v_mfma_f32_16x16x32_bf16 v[136:139], v[116:119], v[176:179], v[136:139]
	v_mfma_f32_16x16x32_bf16 v[120:123], v[104:107], v[184:187], v[120:123]
	v_mfma_f32_16x16x32_bf16 v[112:115], v[116:119], v[184:187], v[112:115]
	v_mfma_f32_16x16x32_bf16 v[92:95], v[104:107], v[202:205], v[92:95]
	v_mfma_f32_16x16x32_bf16 v[88:91], v[116:119], v[202:205], v[88:91]
	v_mfma_f32_16x16x32_bf16 v[76:79], v[104:107], v[210:213], v[76:79]
	v_mfma_f32_16x16x32_bf16 v[72:75], v[116:119], v[210:213], v[72:75]
	v_mfma_f32_16x16x32_bf16 v[140:143], v[108:111], v[180:183], v[140:143]
	v_mfma_f32_16x16x32_bf16 v[136:139], v[124:127], v[180:183], v[136:139]
	v_mfma_f32_16x16x32_bf16 v[120:123], v[108:111], v[188:191], v[120:123]
	v_mfma_f32_16x16x32_bf16 v[112:115], v[124:127], v[188:191], v[112:115]
	v_mfma_f32_16x16x32_bf16 v[92:95], v[108:111], v[206:209], v[92:95]
	v_mfma_f32_16x16x32_bf16 v[88:91], v[124:127], v[206:209], v[88:91]
	v_mfma_f32_16x16x32_bf16 v[76:79], v[108:111], v[214:217], v[76:79]
	v_mfma_f32_16x16x32_bf16 v[72:75], v[124:127], v[214:217], v[72:75]
	v_mfma_f32_16x16x32_bf16 v[132:135], v[160:163], v[176:179], v[132:135]
	v_mfma_f32_16x16x32_bf16 v[128:131], v[168:171], v[176:179], v[128:131]
	v_mfma_f32_16x16x32_bf16 v[100:103], v[160:163], v[184:187], v[100:103]
	v_mfma_f32_16x16x32_bf16 v[96:99], v[168:171], v[184:187], v[96:99]
	v_mfma_f32_16x16x32_bf16 v[84:87], v[160:163], v[202:205], v[84:87]
	v_mfma_f32_16x16x32_bf16 v[80:83], v[168:171], v[202:205], v[80:83]
	v_mfma_f32_16x16x32_bf16 v[68:71], v[160:163], v[210:213], v[68:71]
	v_mfma_f32_16x16x32_bf16 v[64:67], v[168:171], v[210:213], v[64:67]
	v_mfma_f32_16x16x32_bf16 v[132:135], v[164:167], v[180:183], v[132:135]
	v_mfma_f32_16x16x32_bf16 v[128:131], v[172:175], v[180:183], v[128:131]
	v_mfma_f32_16x16x32_bf16 v[100:103], v[164:167], v[188:191], v[100:103]
	v_mfma_f32_16x16x32_bf16 v[96:99], v[172:175], v[188:191], v[96:99]
	v_mfma_f32_16x16x32_bf16 v[84:87], v[164:167], v[206:209], v[84:87]
	v_mfma_f32_16x16x32_bf16 v[80:83], v[172:175], v[206:209], v[80:83]
	v_mfma_f32_16x16x32_bf16 v[68:71], v[164:167], v[214:217], v[68:71]
	v_mfma_f32_16x16x32_bf16 v[64:67], v[172:175], v[214:217], v[64:67]
	s_setprio 0
	s_barrier
	s_mov_b32 m0, s53
	v_lshl_add_u64 v[192:193], s[36:37], 0, v[146:147]
	s_add_u32 s30, s36, 0x160000
	ds_read_b128 v[176:179], v197 offset:16384
	ds_read_b128 v[180:183], v197 offset:17408
	ds_read_b128 v[184:187], v197 offset:18432
	ds_read_b128 v[188:191], v197 offset:19456
	ds_read_b128 v[202:205], v197 offset:20480
	ds_read_b128 v[206:209], v197 offset:21504
	ds_read_b128 v[210:213], v197 offset:22528
	ds_read_b128 v[214:217], v197 offset:23552
	global_load_lds_dwordx4 v[192:193], off
	v_lshl_add_u64 v[218:219], s[36:37], 0, v[144:145]
	s_mov_b32 m0, s54
	s_addc_u32 s31, s37, 0
	global_load_lds_dwordx4 v[218:219], off
	v_lshl_add_u64 v[222:223], s[30:31], 0, v[146:147]
	s_mov_b32 m0, s55
	v_lshl_add_u64 v[224:225], s[38:39], 0, v[144:145]
	global_load_lds_dwordx4 v[222:223], off
	v_lshl_add_u64 v[222:223], s[30:31], 0, v[144:145]
	s_mov_b32 m0, s56
	s_nop 0
	global_load_lds_dwordx4 v[222:223], off
	v_lshl_add_u64 v[222:223], s[38:39], 0, v[146:147]
	s_mov_b32 m0, s43
	s_nop 0
	global_load_lds_dwordx4 v[222:223], off
	s_mov_b32 m0, s44
	s_nop 0
	global_load_lds_dwordx4 v[224:225], off
	s_waitcnt vmcnt(8)
	s_waitcnt lgkmcnt(0)
	s_barrier
; #define PG8_STAGE(bufoff, gbase, voff) do { _Pragma("unroll") for (int _i = 0; _i < 2; ++_i) \
;         __builtin_amdgcn_global_load_lds((const unsigned*)((const char*)(gbase) + (voff)[_i]), (PG8_LAS unsigned*)(lds + (bufoff) + ldsw + _i * 8192), 16, 0, 0); } while (0)
; #define PG8_LDA(dst, b, h) do { _Pragma("unroll") for (int m = 0; m < 4; ++m) _Pragma("unroll") for (int k = 0; k < 2; ++k) dst[m][k] = *(const PG8_LAS bf16x8*)(lds + PG8_SA(b, h) + aoff + m * 2048 + k * 1024); } while (0)
; #define PG8_LDB(dst, b, h) do { _Pragma("unroll") for (int n = 0; n < 2; ++n) _Pragma("unroll") for (int k = 0; k < 2; ++k) dst[n][k] = *(const PG8_LAS bf16x8*)(lds + PG8_SB(b, h) + boff + n * 2048 + k * 1024); } while (0)
; #define PG8_MMA(ai, bj, At, Bt) do { __builtin_amdgcn_s_setprio(1); _Pragma("unroll") for (int m = 0; m < 4; ++m) _Pragma("unroll") for (int n = 0; n < 2; ++n) _Pragma("unroll") for (int k = 0; k < 2; ++k) \
;         acc[ai][bj][m][n] = __builtin_amdgcn_mfma_f32_16x16x32_bf16(Bt[n][k], At[m][k], acc[ai][bj][m][n], 0, 0, 0); __builtin_amdgcn_s_setprio(0); } while (0)
; #define PG8_WAIT_V(n) asm volatile("s_waitcnt vmcnt(" #n ")" ::: "memory")
; #define PG8_WAIT_L(n) asm volatile("s_waitcnt lgkmcnt(" #n ")" ::: "memory")
; #define PG8_BAR __builtin_amdgcn_s_barrier()
; #define PG8_SCHED __builtin_amdgcn_sched_barrier(0)
; template <class Epi, class Sched, bool ALIGN_EPI = false, bool SP2 = false>
; __device__ __forceinline__ void gemm_phase(PG8_LAS unsigned char* lds, const Gemm g, const Sched& S, const Epi& E) {
;     ...
;             PG8_WAIT_V(8); PG8_WAIT_L(0); PG8_BAR; PG8_MMA(1, 0, At, B0); PG8_MMA(1, 1, At, B1); PG8_BAR; PG8_SCHED;
;             PG8_LDB(B0, 1, 0); PG8_LDB(B1, 1, 1); PG8_SCHED; PG8_LDA(At, 1, 0); PG8_STAGE(PG8_SA(0, 1), a2 + hstep, voffA);
;             PG8_WAIT_V(8); PG8_WAIT_L(0); PG8_BAR; PG8_MMA(0, 0, At, B0); PG8_MMA(0, 1, At, B1); PG8_BAR; PG8_SCHED;
	s_setprio 1
	s_waitcnt lgkmcnt(0)
	v_mfma_f32_16x16x32_bf16 v[60:63], v[104:107], v[176:179], v[60:63]
	v_mfma_f32_16x16x32_bf16 v[56:59], v[116:119], v[176:179], v[56:59]
	v_mfma_f32_16x16x32_bf16 v[44:47], v[104:107], v[184:187], v[44:47]
	v_mfma_f32_16x16x32_bf16 v[40:43], v[116:119], v[184:187], v[40:43]
	v_mfma_f32_16x16x32_bf16 v[28:31], v[104:107], v[202:205], v[28:31]
	v_mfma_f32_16x16x32_bf16 v[24:27], v[116:119], v[202:205], v[24:27]
	v_mfma_f32_16x16x32_bf16 v[12:15], v[104:107], v[210:213], v[12:15]
	v_mfma_f32_16x16x32_bf16 v[8:11], v[116:119], v[210:213], v[8:11]
	v_mfma_f32_16x16x32_bf16 v[60:63], v[108:111], v[180:183], v[60:63]
	v_mfma_f32_16x16x32_bf16 v[56:59], v[124:127], v[180:183], v[56:59]
	v_mfma_f32_16x16x32_bf16 v[44:47], v[108:111], v[188:191], v[44:47]
	v_mfma_f32_16x16x32_bf16 v[40:43], v[124:127], v[188:191], v[40:43]
	v_mfma_f32_16x16x32_bf16 v[28:31], v[108:111], v[206:209], v[28:31]
	v_mfma_f32_16x16x32_bf16 v[24:27], v[124:127], v[206:209], v[24:27]
	v_mfma_f32_16x16x32_bf16 v[12:15], v[108:111], v[214:217], v[12:15]
	v_mfma_f32_16x16x32_bf16 v[8:11], v[124:127], v[214:217], v[8:11]
	v_mfma_f32_16x16x32_bf16 v[52:55], v[160:163], v[176:179], v[52:55]
	v_mfma_f32_16x16x32_bf16 v[48:51], v[168:171], v[176:179], v[48:51]
	v_mfma_f32_16x16x32_bf16 v[36:39], v[160:163], v[184:187], v[36:39]
	v_mfma_f32_16x16x32_bf16 v[32:35], v[168:171], v[184:187], v[32:35]
	v_mfma_f32_16x16x32_bf16 v[20:23], v[160:163], v[202:205], v[20:23]
	v_mfma_f32_16x16x32_bf16 v[16:19], v[168:171], v[202:205], v[16:19]
	v_mfma_f32_16x16x32_bf16 v[4:7], v[160:163], v[210:213], v[4:7]
	v_mfma_f32_16x16x32_bf16 v[0:3], v[168:171], v[210:213], v[0:3]
	v_mfma_f32_16x16x32_bf16 v[52:55], v[164:167], v[180:183], v[52:55]
	v_mfma_f32_16x16x32_bf16 v[48:51], v[172:175], v[180:183], v[48:51]
	v_mfma_f32_16x16x32_bf16 v[36:39], v[164:167], v[188:191], v[36:39]
	v_mfma_f32_16x16x32_bf16 v[32:35], v[172:175], v[188:191], v[32:35]
	v_mfma_f32_16x16x32_bf16 v[20:23], v[164:167], v[206:209], v[20:23]
	v_mfma_f32_16x16x32_bf16 v[16:19], v[172:175], v[206:209], v[16:19]
	v_mfma_f32_16x16x32_bf16 v[4:7], v[164:167], v[214:217], v[4:7]
	v_mfma_f32_16x16x32_bf16 v[0:3], v[172:175], v[214:217], v[0:3]
	s_setprio 0
	s_barrier
	ds_read_b128 v[104:107], v199
	ds_read_b128 v[108:111], v199 offset:1024
	ds_read_b128 v[116:119], v199 offset:2048
	ds_read_b128 v[124:127], v199 offset:3072
	ds_read_b128 v[160:163], v200
	ds_read_b128 v[164:167], v200 offset:1024
	ds_read_b128 v[168:171], v200 offset:2048
	ds_read_b128 v[172:175], v200 offset:3072
	s_add_u32 s30, s38, 0x160000
	s_addc_u32 s31, s39, 0
	s_mov_b32 m0, s45
	v_lshl_add_u64 v[226:227], s[30:31], 0, v[146:147]
	ds_read_b128 v[176:179], v197 offset:32768
	ds_read_b128 v[180:183], v197 offset:33792
	ds_read_b128 v[184:187], v197 offset:34816
	ds_read_b128 v[188:191], v197 offset:35840
	ds_read_b128 v[202:205], v197 offset:36864
	ds_read_b128 v[206:209], v197 offset:37888
	ds_read_b128 v[210:213], v197 offset:38912
	ds_read_b128 v[214:217], v197 offset:39936
	global_load_lds_dwordx4 v[226:227], off
	v_lshl_add_u64 v[226:227], s[30:31], 0, v[144:145]
	s_mov_b32 m0, s46
	s_nop 0
	global_load_lds_dwordx4 v[226:227], off
	s_waitcnt vmcnt(8)
	s_waitcnt lgkmcnt(0)
	s_barrier
	s_setprio 1
	s_waitcnt lgkmcnt(0)
	v_mfma_f32_16x16x32_bf16 v[140:143], v[104:107], v[176:179], v[140:143]
	v_mfma_f32_16x16x32_bf16 v[136:139], v[116:119], v[176:179], v[136:139]
	v_mfma_f32_16x16x32_bf16 v[120:123], v[104:107], v[184:187], v[120:123]
	v_mfma_f32_16x16x32_bf16 v[112:115], v[116:119], v[184:187], v[112:115]
	v_mfma_f32_16x16x32_bf16 v[92:95], v[104:107], v[202:205], v[92:95]
	v_mfma_f32_16x16x32_bf16 v[88:91], v[116:119], v[202:205], v[88:91]
	v_mfma_f32_16x16x32_bf16 v[76:79], v[104:107], v[210:213], v[76:79]
	v_mfma_f32_16x16x32_bf16 v[72:75], v[116:119], v[210:213], v[72:75]
	v_mfma_f32_16x16x32_bf16 v[140:143], v[108:111], v[180:183], v[140:143]
	v_mfma_f32_16x16x32_bf16 v[136:139], v[124:127], v[180:183], v[136:139]
	v_mfma_f32_16x16x32_bf16 v[120:123], v[108:111], v[188:191], v[120:123]
	v_mfma_f32_16x16x32_bf16 v[112:115], v[124:127], v[188:191], v[112:115]
	v_mfma_f32_16x16x32_bf16 v[92:95], v[108:111], v[206:209], v[92:95]
	v_mfma_f32_16x16x32_bf16 v[88:91], v[124:127], v[206:209], v[88:91]
	v_mfma_f32_16x16x32_bf16 v[76:79], v[108:111], v[214:217], v[76:79]
	v_mfma_f32_16x16x32_bf16 v[72:75], v[124:127], v[214:217], v[72:75]
	v_mfma_f32_16x16x32_bf16 v[132:135], v[160:163], v[176:179], v[132:135]
	v_mfma_f32_16x16x32_bf16 v[128:131], v[168:171], v[176:179], v[128:131]
	v_mfma_f32_16x16x32_bf16 v[100:103], v[160:163], v[184:187], v[100:103]
	v_mfma_f32_16x16x32_bf16 v[96:99], v[168:171], v[184:187], v[96:99]
	v_mfma_f32_16x16x32_bf16 v[84:87], v[160:163], v[202:205], v[84:87]
	v_mfma_f32_16x16x32_bf16 v[80:83], v[168:171], v[202:205], v[80:83]
	v_mfma_f32_16x16x32_bf16 v[68:71], v[160:163], v[210:213], v[68:71]
	v_mfma_f32_16x16x32_bf16 v[64:67], v[168:171], v[210:213], v[64:67]
	v_mfma_f32_16x16x32_bf16 v[132:135], v[164:167], v[180:183], v[132:135]
	v_mfma_f32_16x16x32_bf16 v[128:131], v[172:175], v[180:183], v[128:131]
	v_mfma_f32_16x16x32_bf16 v[100:103], v[164:167], v[188:191], v[100:103]
	v_mfma_f32_16x16x32_bf16 v[96:99], v[172:175], v[188:191], v[96:99]
	v_mfma_f32_16x16x32_bf16 v[84:87], v[164:167], v[206:209], v[84:87]
	v_mfma_f32_16x16x32_bf16 v[80:83], v[172:175], v[206:209], v[80:83]
	v_mfma_f32_16x16x32_bf16 v[68:71], v[164:167], v[214:217], v[68:71]
	v_mfma_f32_16x16x32_bf16 v[64:67], v[172:175], v[214:217], v[64:67]
	s_setprio 0
	s_barrier
; #define PG8_STAGE(bufoff, gbase, voff) do { _Pragma("unroll") for (int _i = 0; _i < 2; ++_i) \
;         __builtin_amdgcn_global_load_lds((const unsigned*)((const char*)(gbase) + (voff)[_i]), (PG8_LAS unsigned*)(lds + (bufoff) + ldsw + _i * 8192), 16, 0, 0); } while (0)
; #define PG8_LDA(dst, b, h) do { _Pragma("unroll") for (int m = 0; m < 4; ++m) _Pragma("unroll") for (int k = 0; k < 2; ++k) dst[m][k] = *(const PG8_LAS bf16x8*)(lds + PG8_SA(b, h) + aoff + m * 2048 + k * 1024); } while (0)
; #define PG8_MMA(ai, bj, At, Bt) do { __builtin_amdgcn_s_setprio(1); _Pragma("unroll") for (int m = 0; m < 4; ++m) _Pragma("unroll") for (int n = 0; n < 2; ++n) _Pragma("unroll") for (int k = 0; k < 2; ++k) \
;         acc[ai][bj][m][n] = __builtin_amdgcn_mfma_f32_16x16x32_bf16(Bt[n][k], At[m][k], acc[ai][bj][m][n], 0, 0, 0); __builtin_amdgcn_s_setprio(0); } while (0)
; #define PG8_WAIT_V(n) asm volatile("s_waitcnt vmcnt(" #n ")" ::: "memory")
; #define PG8_WAIT_L(n) asm volatile("s_waitcnt lgkmcnt(" #n ")" ::: "memory")
; #define PG8_BAR __builtin_amdgcn_s_barrier()
; #define PG8_SCHED __builtin_amdgcn_sched_barrier(0)
; template <class Epi, class Sched, bool ALIGN_EPI = false, bool SP2 = false>
; __device__ __forceinline__ void gemm_phase(PG8_LAS unsigned char* lds, const Gemm g, const Sched& S, const Epi& E) {
;     ...
;         for (int t = 0; t < nt; t += 2) {
;     ...
;             PG8_LDA(At, 1, 1); PG8_STAGE(PG8_SB(1, 0), b3, voffB); PG8_STAGE(PG8_SB(1, 1), b3 + hstep, voffB); PG8_STAGE(PG8_SA(1, 0), a3, voffA);
;             PG8_WAIT_V(8); PG8_WAIT_L(0); PG8_BAR; PG8_MMA(1, 0, At, B0); PG8_MMA(1, 1, At, B1); PG8_BAR; PG8_SCHED;
	s_mov_b32 m0, s57
	v_lshl_add_u64 v[192:193], v[192:193], 0, s[20:21]
	s_add_u32 s30, s36, 0x160080
	ds_read_b128 v[176:179], v197 offset:49152
	ds_read_b128 v[180:183], v197 offset:50176
	ds_read_b128 v[184:187], v197 offset:51200
	ds_read_b128 v[188:191], v197 offset:52224
	ds_read_b128 v[202:205], v197 offset:53248
	ds_read_b128 v[206:209], v197 offset:54272
	ds_read_b128 v[210:213], v197 offset:55296
	ds_read_b128 v[214:217], v197 offset:56320
	global_load_lds_dwordx4 v[192:193], off
	v_lshl_add_u64 v[192:193], v[218:219], 0, s[20:21]
	s_mov_b32 m0, s58
	s_addc_u32 s31, s37, 0
	global_load_lds_dwordx4 v[192:193], off
	v_lshl_add_u64 v[192:193], s[30:31], 0, v[146:147]
	s_mov_b32 m0, s59
	s_nop 0
	global_load_lds_dwordx4 v[192:193], off
	v_lshl_add_u64 v[192:193], s[30:31], 0, v[144:145]
	s_mov_b32 m0, s60
	s_nop 0
	global_load_lds_dwordx4 v[192:193], off
	v_lshl_add_u64 v[192:193], v[222:223], 0, s[20:21]
	s_mov_b32 m0, s49
	s_nop 0
	global_load_lds_dwordx4 v[192:193], off
	v_lshl_add_u64 v[192:193], v[224:225], 0, s[20:21]
	s_mov_b32 m0, s50
	s_nop 0
	global_load_lds_dwordx4 v[192:193], off
	s_waitcnt vmcnt(8)
	s_waitcnt lgkmcnt(0)
	s_barrier
	s_setprio 1
	s_waitcnt lgkmcnt(0)
	v_mfma_f32_16x16x32_bf16 v[60:63], v[104:107], v[176:179], v[60:63]
	v_mfma_f32_16x16x32_bf16 v[56:59], v[116:119], v[176:179], v[56:59]
	v_mfma_f32_16x16x32_bf16 v[44:47], v[104:107], v[184:187], v[44:47]
	v_mfma_f32_16x16x32_bf16 v[40:43], v[116:119], v[184:187], v[40:43]
	v_mfma_f32_16x16x32_bf16 v[28:31], v[104:107], v[202:205], v[28:31]
	v_mfma_f32_16x16x32_bf16 v[24:27], v[116:119], v[202:205], v[24:27]
	v_mfma_f32_16x16x32_bf16 v[12:15], v[104:107], v[210:213], v[12:15]
	v_mfma_f32_16x16x32_bf16 v[8:11], v[116:119], v[210:213], v[8:11]
	v_mfma_f32_16x16x32_bf16 v[60:63], v[108:111], v[180:183], v[60:63]
	v_mfma_f32_16x16x32_bf16 v[56:59], v[124:127], v[180:183], v[56:59]
	v_mfma_f32_16x16x32_bf16 v[44:47], v[108:111], v[188:191], v[44:47]
	v_mfma_f32_16x16x32_bf16 v[40:43], v[124:127], v[188:191], v[40:43]
	v_mfma_f32_16x16x32_bf16 v[28:31], v[108:111], v[206:209], v[28:31]
	v_mfma_f32_16x16x32_bf16 v[24:27], v[124:127], v[206:209], v[24:27]
	v_mfma_f32_16x16x32_bf16 v[12:15], v[108:111], v[214:217], v[12:15]
	v_mfma_f32_16x16x32_bf16 v[8:11], v[124:127], v[214:217], v[8:11]
	v_mfma_f32_16x16x32_bf16 v[52:55], v[160:163], v[176:179], v[52:55]
	v_mfma_f32_16x16x32_bf16 v[48:51], v[168:171], v[176:179], v[48:51]
	v_mfma_f32_16x16x32_bf16 v[36:39], v[160:163], v[184:187], v[36:39]
	v_mfma_f32_16x16x32_bf16 v[32:35], v[168:171], v[184:187], v[32:35]
	v_mfma_f32_16x16x32_bf16 v[20:23], v[160:163], v[202:205], v[20:23]
	v_mfma_f32_16x16x32_bf16 v[16:19], v[168:171], v[202:205], v[16:19]
	v_mfma_f32_16x16x32_bf16 v[4:7], v[160:163], v[210:213], v[4:7]
	v_mfma_f32_16x16x32_bf16 v[0:3], v[168:171], v[210:213], v[0:3]
	v_mfma_f32_16x16x32_bf16 v[52:55], v[164:167], v[180:183], v[52:55]
	v_mfma_f32_16x16x32_bf16 v[48:51], v[172:175], v[180:183], v[48:51]
	v_mfma_f32_16x16x32_bf16 v[36:39], v[164:167], v[188:191], v[36:39]
	v_mfma_f32_16x16x32_bf16 v[32:35], v[172:175], v[188:191], v[32:35]
	v_mfma_f32_16x16x32_bf16 v[20:23], v[164:167], v[206:209], v[20:23]
	v_mfma_f32_16x16x32_bf16 v[16:19], v[172:175], v[206:209], v[16:19]
	v_mfma_f32_16x16x32_bf16 v[4:7], v[164:167], v[214:217], v[4:7]
	v_mfma_f32_16x16x32_bf16 v[0:3], v[172:175], v[214:217], v[0:3]
	s_setprio 0
	s_barrier
	s_add_i32 s63, s63, 2
	s_add_u32 s28, s28, 0x100
	s_addc_u32 s29, s29, 0
	s_cmpk_gt_u32 s63, 0x55
	s_mov_b64 s[30:31], s[34:35]
	s_cbranch_scc0 .LBB0_1541
	s_and_b64 vcc, exec, s[22:23]
	s_cbranch_vccz .LBB0_1544
	s_barrier

; #define PG8_STAGE(bufoff, gbase, voff) do { _Pragma("unroll") for (int _i = 0; _i < 2; ++_i) \
;         __builtin_amdgcn_global_load_lds((const unsigned*)((const char*)(gbase) + (voff)[_i]), (PG8_LAS unsigned*)(lds + (bufoff) + ldsw + _i * 8192), 16, 0, 0); } while (0)
; #define PG8_LDA(dst, b, h) do { _Pragma("unroll") for (int m = 0; m < 4; ++m) _Pragma("unroll") for (int k = 0; k < 2; ++k) dst[m][k] = *(const PG8_LAS bf16x8*)(lds + PG8_SA(b, h) + aoff + m * 2048 + k * 1024); } while (0)
; #define PG8_LDB(dst, b, h) do { _Pragma("unroll") for (int n = 0; n < 2; ++n) _Pragma("unroll") for (int k = 0; k < 2; ++k) dst[n][k] = *(const PG8_LAS bf16x8*)(lds + PG8_SB(b, h) + boff + n * 2048 + k * 1024); } while (0)
; #define PG8_MMA(ai, bj, At, Bt) do { __builtin_amdgcn_s_setprio(1); _Pragma("unroll") for (int m = 0; m < 4; ++m) _Pragma("unroll") for (int n = 0; n < 2; ++n) _Pragma("unroll") for (int k = 0; k < 2; ++k) \
;         acc[ai][bj][m][n] = __builtin_amdgcn_mfma_f32_16x16x32_bf16(Bt[n][k], At[m][k], acc[ai][bj][m][n], 0, 0, 0); __builtin_amdgcn_s_setprio(0); } while (0)
; #define PG8_WAIT_V(n) asm volatile("s_waitcnt vmcnt(" #n ")" ::: "memory")
; #define PG8_WAIT_L(n) asm volatile("s_waitcnt lgkmcnt(" #n ")" ::: "memory")
; #define PG8_BAR __builtin_amdgcn_s_barrier()
; #define PG8_SCHED __builtin_amdgcn_sched_barrier(0)
; template <class Epi, class Sched, bool ALIGN_EPI = false, bool SP2 = false>
; __device__ __forceinline__ void gemm_phase(PG8_LAS unsigned char* lds, const Gemm g, const Sched& S, const Epi& E) {
;     ...
;             PG8_LDB(B0, 0, 0); PG8_LDB(B1, 0, 1); PG8_SCHED; PG8_LDA(At, 0, 0); PG8_STAGE(PG8_SA(1, 1), a1 + hstep, voffA);
;             PG8_WAIT_V(8); PG8_WAIT_L(0); PG8_BAR; PG8_MMA(0, 0, At, B0); PG8_MMA(0, 1, At, B1); PG8_BAR; PG8_SCHED;
;             PG8_LDA(At, 0, 1); PG8_STAGE(PG8_SB(0, 0), b2, voffB); PG8_STAGE(PG8_SB(0, 1), b2 + hstep, voffB); PG8_STAGE(PG8_SA(0, 0), a2, voffA);
;             PG8_WAIT_V(8); PG8_WAIT_L(0); PG8_BAR; PG8_MMA(1, 0, At, B0); PG8_MMA(1, 1, At, B1); PG8_BAR; PG8_SCHED;
.LBB0_1597:
	ds_read_b128 v[128:131], v165
	ds_read_b128 v[132:135], v165 offset:1024
	ds_read_b128 v[136:139], v165 offset:2048
	ds_read_b128 v[140:143], v165 offset:3072
	ds_read_b128 v[156:159], v166
	ds_read_b128 v[168:171], v166 offset:1024
	ds_read_b128 v[172:175], v166 offset:2048
	ds_read_b128 v[176:179], v166 offset:3072
	s_add_u32 s22, s20, 0x100
	s_addc_u32 s23, s21, 0
	s_cmpk_eq_i32 s53, 0x54
	s_cselect_b32 s27, s7, s23
	s_cselect_b32 s26, s6, s22
	s_cselect_b32 s25, s19, s52
	s_cselect_b32 s24, s18, s51
	v_lshl_add_u64 v[160:161], s[20:21], 0, v[150:151]
	s_add_i32 m0, s35, 0xc000
	ds_read_b128 v[180:183], v167
	ds_read_b128 v[184:187], v167 offset:1024
	ds_read_b128 v[188:191], v167 offset:2048
	ds_read_b128 v[192:195], v167 offset:3072
	ds_read_b128 v[196:199], v167 offset:4096
	ds_read_b128 v[200:203], v167 offset:5120
	ds_read_b128 v[204:207], v167 offset:6144
	ds_read_b128 v[208:211], v167 offset:7168
	global_load_lds_dwordx4 v[160:161], off
	v_lshl_add_u64 v[160:161], s[20:21], 0, v[148:149]
	s_add_i32 m0, s35, 0xe000
	s_nop 0
	global_load_lds_dwordx4 v[160:161], off
	s_waitcnt vmcnt(8)
	s_waitcnt lgkmcnt(0)
	s_barrier
	s_setprio 1
	s_waitcnt lgkmcnt(0)
	v_mfma_f32_16x16x32_bf16 v[124:127], v[128:131], v[180:183], v[124:127]
	v_mfma_f32_16x16x32_bf16 v[120:123], v[136:139], v[180:183], v[120:123]
	v_mfma_f32_16x16x32_bf16 v[116:119], v[128:131], v[188:191], v[116:119]
	v_mfma_f32_16x16x32_bf16 v[112:115], v[136:139], v[188:191], v[112:115]
	v_mfma_f32_16x16x32_bf16 v[92:95], v[128:131], v[196:199], v[92:95]
	v_mfma_f32_16x16x32_bf16 v[88:91], v[136:139], v[196:199], v[88:91]
	v_mfma_f32_16x16x32_bf16 v[84:87], v[128:131], v[204:207], v[84:87]
	v_mfma_f32_16x16x32_bf16 v[80:83], v[136:139], v[204:207], v[80:83]
	v_mfma_f32_16x16x32_bf16 v[124:127], v[132:135], v[184:187], v[124:127]
	v_mfma_f32_16x16x32_bf16 v[120:123], v[140:143], v[184:187], v[120:123]
	v_mfma_f32_16x16x32_bf16 v[116:119], v[132:135], v[192:195], v[116:119]
	v_mfma_f32_16x16x32_bf16 v[112:115], v[140:143], v[192:195], v[112:115]
	v_mfma_f32_16x16x32_bf16 v[92:95], v[132:135], v[200:203], v[92:95]
	v_mfma_f32_16x16x32_bf16 v[88:91], v[140:143], v[200:203], v[88:91]
	v_mfma_f32_16x16x32_bf16 v[84:87], v[132:135], v[208:211], v[84:87]
	v_mfma_f32_16x16x32_bf16 v[80:83], v[140:143], v[208:211], v[80:83]
	v_mfma_f32_16x16x32_bf16 v[108:111], v[156:159], v[180:183], v[108:111]
	v_mfma_f32_16x16x32_bf16 v[104:107], v[172:175], v[180:183], v[104:107]
	v_mfma_f32_16x16x32_bf16 v[100:103], v[156:159], v[188:191], v[100:103]
	v_mfma_f32_16x16x32_bf16 v[96:99], v[172:175], v[188:191], v[96:99]
	v_mfma_f32_16x16x32_bf16 v[76:79], v[156:159], v[196:199], v[76:79]
	v_mfma_f32_16x16x32_bf16 v[72:75], v[172:175], v[196:199], v[72:75]
	v_mfma_f32_16x16x32_bf16 v[68:71], v[156:159], v[204:207], v[68:71]
	v_mfma_f32_16x16x32_bf16 v[64:67], v[172:175], v[204:207], v[64:67]
	v_mfma_f32_16x16x32_bf16 v[108:111], v[168:171], v[184:187], v[108:111]
	v_mfma_f32_16x16x32_bf16 v[104:107], v[176:179], v[184:187], v[104:107]
	v_mfma_f32_16x16x32_bf16 v[100:103], v[168:171], v[192:195], v[100:103]
	v_mfma_f32_16x16x32_bf16 v[96:99], v[176:179], v[192:195], v[96:99]
	v_mfma_f32_16x16x32_bf16 v[76:79], v[168:171], v[200:203], v[76:79]
	v_mfma_f32_16x16x32_bf16 v[72:75], v[176:179], v[200:203], v[72:75]
	v_mfma_f32_16x16x32_bf16 v[68:71], v[168:171], v[208:211], v[68:71]
	v_mfma_f32_16x16x32_bf16 v[64:67], v[176:179], v[208:211], v[64:67]
	s_setprio 0
	s_barrier
	s_add_i32 s20, s44, s34
	v_lshl_add_u64 v[160:161], s[24:25], 0, v[144:145]
	s_mov_b32 m0, s20
	ds_read_b128 v[180:183], v167 offset:16384
	ds_read_b128 v[184:187], v167 offset:17408
	ds_read_b128 v[188:191], v167 offset:18432
	ds_read_b128 v[192:195], v167 offset:19456
	ds_read_b128 v[196:199], v167 offset:20480
	ds_read_b128 v[200:203], v167 offset:21504
	ds_read_b128 v[204:207], v167 offset:22528
	ds_read_b128 v[208:211], v167 offset:23552
	global_load_lds_dwordx4 v[160:161], off
	s_add_i32 m0, s20, 0x2000
	s_add_u32 s20, s24, 0x160000
	v_lshl_add_u64 v[212:213], s[24:25], 0, v[146:147]
	s_addc_u32 s21, s25, 0
	s_add_i32 s54, s45, s34
	global_load_lds_dwordx4 v[212:213], off
	v_lshl_add_u64 v[214:215], s[20:21], 0, v[144:145]
	s_mov_b32 m0, s54
	v_lshl_add_u64 v[216:217], s[26:27], 0, v[146:147]
	global_load_lds_dwordx4 v[214:215], off
	v_lshl_add_u64 v[214:215], s[20:21], 0, v[146:147]
	s_add_i32 m0, s54, 0x2000
	s_nop 0
	global_load_lds_dwordx4 v[214:215], off
	v_lshl_add_u64 v[214:215], s[26:27], 0, v[144:145]
	s_mov_b32 m0, s35
	s_nop 0
	global_load_lds_dwordx4 v[214:215], off
	s_mov_b32 m0, s36
	s_nop 0
	global_load_lds_dwordx4 v[216:217], off
	s_waitcnt vmcnt(8)
	s_waitcnt lgkmcnt(0)
	s_barrier
; #define PG8_STAGE(bufoff, gbase, voff) do { _Pragma("unroll") for (int _i = 0; _i < 2; ++_i) \
;         __builtin_amdgcn_global_load_lds((const unsigned*)((const char*)(gbase) + (voff)[_i]), (PG8_LAS unsigned*)(lds + (bufoff) + ldsw + _i * 8192), 16, 0, 0); } while (0)
; #define PG8_LDA(dst, b, h) do { _Pragma("unroll") for (int m = 0; m < 4; ++m) _Pragma("unroll") for (int k = 0; k < 2; ++k) dst[m][k] = *(const PG8_LAS bf16x8*)(lds + PG8_SA(b, h) + aoff + m * 2048 + k * 1024); } while (0)
; #define PG8_LDB(dst, b, h) do { _Pragma("unroll") for (int n = 0; n < 2; ++n) _Pragma("unroll") for (int k = 0; k < 2; ++k) dst[n][k] = *(const PG8_LAS bf16x8*)(lds + PG8_SB(b, h) + boff + n * 2048 + k * 1024); } while (0)
; #define PG8_MMA(ai, bj, At, Bt) do { __builtin_amdgcn_s_setprio(1); _Pragma("unroll") for (int m = 0; m < 4; ++m) _Pragma("unroll") for (int n = 0; n < 2; ++n) _Pragma("unroll") for (int k = 0; k < 2; ++k) \
;         acc[ai][bj][m][n] = __builtin_amdgcn_mfma_f32_16x16x32_bf16(Bt[n][k], At[m][k], acc[ai][bj][m][n], 0, 0, 0); __builtin_amdgcn_s_setprio(0); } while (0)
; #define PG8_WAIT_V(n) asm volatile("s_waitcnt vmcnt(" #n ")" ::: "memory")
; #define PG8_WAIT_L(n) asm volatile("s_waitcnt lgkmcnt(" #n ")" ::: "memory")
; #define PG8_BAR __builtin_amdgcn_s_barrier()
; #define PG8_SCHED __builtin_amdgcn_sched_barrier(0)
; template <class Epi, class Sched, bool ALIGN_EPI = false, bool SP2 = false>
; __device__ __forceinline__ void gemm_phase(PG8_LAS unsigned char* lds, const Gemm g, const Sched& S, const Epi& E) {
;     ...
;             PG8_WAIT_V(8); PG8_WAIT_L(0); PG8_BAR; PG8_MMA(1, 0, At, B0); PG8_MMA(1, 1, At, B1); PG8_BAR; PG8_SCHED;
;             PG8_LDB(B0, 1, 0); PG8_LDB(B1, 1, 1); PG8_SCHED; PG8_LDA(At, 1, 0); PG8_STAGE(PG8_SA(0, 1), a2 + hstep, voffA);
;             PG8_WAIT_V(8); PG8_WAIT_L(0); PG8_BAR; PG8_MMA(0, 0, At, B0); PG8_MMA(0, 1, At, B1); PG8_BAR; PG8_SCHED;
	s_setprio 1
	s_waitcnt lgkmcnt(0)
	v_mfma_f32_16x16x32_bf16 v[60:63], v[128:131], v[180:183], v[60:63]
	v_mfma_f32_16x16x32_bf16 v[56:59], v[136:139], v[180:183], v[56:59]
	v_mfma_f32_16x16x32_bf16 v[52:55], v[128:131], v[188:191], v[52:55]
	v_mfma_f32_16x16x32_bf16 v[48:51], v[136:139], v[188:191], v[48:51]
	v_mfma_f32_16x16x32_bf16 v[36:39], v[128:131], v[196:199], v[36:39]
	v_mfma_f32_16x16x32_bf16 v[24:27], v[136:139], v[196:199], v[24:27]
	v_mfma_f32_16x16x32_bf16 v[16:19], v[128:131], v[204:207], v[16:19]
	v_mfma_f32_16x16x32_bf16 v[8:11], v[136:139], v[204:207], v[8:11]
	v_mfma_f32_16x16x32_bf16 v[60:63], v[132:135], v[184:187], v[60:63]
	v_mfma_f32_16x16x32_bf16 v[56:59], v[140:143], v[184:187], v[56:59]
	v_mfma_f32_16x16x32_bf16 v[52:55], v[132:135], v[192:195], v[52:55]
	v_mfma_f32_16x16x32_bf16 v[48:51], v[140:143], v[192:195], v[48:51]
	v_mfma_f32_16x16x32_bf16 v[36:39], v[132:135], v[200:203], v[36:39]
	v_mfma_f32_16x16x32_bf16 v[24:27], v[140:143], v[200:203], v[24:27]
	v_mfma_f32_16x16x32_bf16 v[16:19], v[132:135], v[208:211], v[16:19]
	v_mfma_f32_16x16x32_bf16 v[8:11], v[140:143], v[208:211], v[8:11]
	v_mfma_f32_16x16x32_bf16 v[44:47], v[156:159], v[180:183], v[44:47]
	v_mfma_f32_16x16x32_bf16 v[40:43], v[172:175], v[180:183], v[40:43]
	v_mfma_f32_16x16x32_bf16 v[32:35], v[156:159], v[188:191], v[32:35]
	v_mfma_f32_16x16x32_bf16 v[28:31], v[172:175], v[188:191], v[28:31]
	v_mfma_f32_16x16x32_bf16 v[20:23], v[156:159], v[196:199], v[20:23]
	v_mfma_f32_16x16x32_bf16 v[12:15], v[172:175], v[196:199], v[12:15]
	v_mfma_f32_16x16x32_bf16 v[4:7], v[156:159], v[204:207], v[4:7]
	v_mfma_f32_16x16x32_bf16 v[0:3], v[172:175], v[204:207], v[0:3]
	v_mfma_f32_16x16x32_bf16 v[44:47], v[168:171], v[184:187], v[44:47]
	v_mfma_f32_16x16x32_bf16 v[40:43], v[176:179], v[184:187], v[40:43]
	v_mfma_f32_16x16x32_bf16 v[32:35], v[168:171], v[192:195], v[32:35]
	v_mfma_f32_16x16x32_bf16 v[28:31], v[176:179], v[192:195], v[28:31]
	v_mfma_f32_16x16x32_bf16 v[20:23], v[168:171], v[200:203], v[20:23]
	v_mfma_f32_16x16x32_bf16 v[12:15], v[176:179], v[200:203], v[12:15]
	v_mfma_f32_16x16x32_bf16 v[4:7], v[168:171], v[208:211], v[4:7]
	v_mfma_f32_16x16x32_bf16 v[0:3], v[176:179], v[208:211], v[0:3]
	s_setprio 0
	s_barrier
	s_add_i32 s54, 0, 0x18000
	s_add_i32 s55, 0, 0x1c000
	v_add_u32_e32 v140, s54, v163
	v_add_u32_e32 v176, s55, v163
	ds_read_b128 v[128:131], v140
	ds_read_b128 v[132:135], v140 offset:1024
	ds_read_b128 v[136:139], v140 offset:2048
	ds_read_b128 v[140:143], v140 offset:3072
	ds_read_b128 v[156:159], v176
	ds_read_b128 v[168:171], v176 offset:1024
	ds_read_b128 v[172:175], v176 offset:2048
	ds_read_b128 v[176:179], v176 offset:3072
	s_add_u32 s20, s26, 0x160000
	s_addc_u32 s21, s27, 0
	s_mov_b32 m0, s37
	v_lshl_add_u64 v[218:219], s[20:21], 0, v[144:145]
	ds_read_b128 v[180:183], v167 offset:32768
	ds_read_b128 v[184:187], v167 offset:33792
	ds_read_b128 v[188:191], v167 offset:34816
	ds_read_b128 v[192:195], v167 offset:35840
	ds_read_b128 v[196:199], v167 offset:36864
	ds_read_b128 v[200:203], v167 offset:37888
	ds_read_b128 v[204:207], v167 offset:38912
	ds_read_b128 v[208:211], v167 offset:39936
	global_load_lds_dwordx4 v[218:219], off
	v_lshl_add_u64 v[218:219], s[20:21], 0, v[146:147]
	s_mov_b32 m0, s38
	s_nop 0
	global_load_lds_dwordx4 v[218:219], off
	s_waitcnt vmcnt(8)
	s_waitcnt lgkmcnt(0)
	s_barrier
	s_setprio 1
	s_waitcnt lgkmcnt(0)
	v_mfma_f32_16x16x32_bf16 v[124:127], v[128:131], v[180:183], v[124:127]
	v_mfma_f32_16x16x32_bf16 v[120:123], v[136:139], v[180:183], v[120:123]
	v_mfma_f32_16x16x32_bf16 v[116:119], v[128:131], v[188:191], v[116:119]
	v_mfma_f32_16x16x32_bf16 v[112:115], v[136:139], v[188:191], v[112:115]
	v_mfma_f32_16x16x32_bf16 v[92:95], v[128:131], v[196:199], v[92:95]
	v_mfma_f32_16x16x32_bf16 v[88:91], v[136:139], v[196:199], v[88:91]
	v_mfma_f32_16x16x32_bf16 v[84:87], v[128:131], v[204:207], v[84:87]
	v_mfma_f32_16x16x32_bf16 v[80:83], v[136:139], v[204:207], v[80:83]
	v_mfma_f32_16x16x32_bf16 v[124:127], v[132:135], v[184:187], v[124:127]
	v_mfma_f32_16x16x32_bf16 v[120:123], v[140:143], v[184:187], v[120:123]
	v_mfma_f32_16x16x32_bf16 v[116:119], v[132:135], v[192:195], v[116:119]
	v_mfma_f32_16x16x32_bf16 v[112:115], v[140:143], v[192:195], v[112:115]
	v_mfma_f32_16x16x32_bf16 v[92:95], v[132:135], v[200:203], v[92:95]
	v_mfma_f32_16x16x32_bf16 v[88:91], v[140:143], v[200:203], v[88:91]
	v_mfma_f32_16x16x32_bf16 v[84:87], v[132:135], v[208:211], v[84:87]
	v_mfma_f32_16x16x32_bf16 v[80:83], v[140:143], v[208:211], v[80:83]
	v_mfma_f32_16x16x32_bf16 v[108:111], v[156:159], v[180:183], v[108:111]
	v_mfma_f32_16x16x32_bf16 v[104:107], v[172:175], v[180:183], v[104:107]
	v_mfma_f32_16x16x32_bf16 v[100:103], v[156:159], v[188:191], v[100:103]
	v_mfma_f32_16x16x32_bf16 v[96:99], v[172:175], v[188:191], v[96:99]
	v_mfma_f32_16x16x32_bf16 v[76:79], v[156:159], v[196:199], v[76:79]
	v_mfma_f32_16x16x32_bf16 v[72:75], v[172:175], v[196:199], v[72:75]
	v_mfma_f32_16x16x32_bf16 v[68:71], v[156:159], v[204:207], v[68:71]
	v_mfma_f32_16x16x32_bf16 v[64:67], v[172:175], v[204:207], v[64:67]
	v_mfma_f32_16x16x32_bf16 v[108:111], v[168:171], v[184:187], v[108:111]
	v_mfma_f32_16x16x32_bf16 v[104:107], v[176:179], v[184:187], v[104:107]
	v_mfma_f32_16x16x32_bf16 v[100:103], v[168:171], v[192:195], v[100:103]
	v_mfma_f32_16x16x32_bf16 v[96:99], v[176:179], v[192:195], v[96:99]
	v_mfma_f32_16x16x32_bf16 v[76:79], v[168:171], v[200:203], v[76:79]
	v_mfma_f32_16x16x32_bf16 v[72:75], v[176:179], v[200:203], v[72:75]
	v_mfma_f32_16x16x32_bf16 v[68:71], v[168:171], v[208:211], v[68:71]
	v_mfma_f32_16x16x32_bf16 v[64:67], v[176:179], v[208:211], v[64:67]
	s_setprio 0
	s_barrier
; #define PG8_STAGE(bufoff, gbase, voff) do { _Pragma("unroll") for (int _i = 0; _i < 2; ++_i) \
;         __builtin_amdgcn_global_load_lds((const unsigned*)((const char*)(gbase) + (voff)[_i]), (PG8_LAS unsigned*)(lds + (bufoff) + ldsw + _i * 8192), 16, 0, 0); } while (0)
; #define PG8_LDA(dst, b, h) do { _Pragma("unroll") for (int m = 0; m < 4; ++m) _Pragma("unroll") for (int k = 0; k < 2; ++k) dst[m][k] = *(const PG8_LAS bf16x8*)(lds + PG8_SA(b, h) + aoff + m * 2048 + k * 1024); } while (0)
; #define PG8_MMA(ai, bj, At, Bt) do { __builtin_amdgcn_s_setprio(1); _Pragma("unroll") for (int m = 0; m < 4; ++m) _Pragma("unroll") for (int n = 0; n < 2; ++n) _Pragma("unroll") for (int k = 0; k < 2; ++k) \
;         acc[ai][bj][m][n] = __builtin_amdgcn_mfma_f32_16x16x32_bf16(Bt[n][k], At[m][k], acc[ai][bj][m][n], 0, 0, 0); __builtin_amdgcn_s_setprio(0); } while (0)
; #define PG8_WAIT_V(n) asm volatile("s_waitcnt vmcnt(" #n ")" ::: "memory")
; #define PG8_WAIT_L(n) asm volatile("s_waitcnt lgkmcnt(" #n ")" ::: "memory")
; #define PG8_BAR __builtin_amdgcn_s_barrier()
; #define PG8_SCHED __builtin_amdgcn_sched_barrier(0)
; template <class Epi, class Sched, bool ALIGN_EPI = false, bool SP2 = false>
; __device__ __forceinline__ void gemm_phase(PG8_LAS unsigned char* lds, const Gemm g, const Sched& S, const Epi& E) {
;     ...
;         for (int t = 0; t < nt; t += 2) {
;     ...
;             PG8_LDA(At, 1, 1); PG8_STAGE(PG8_SB(1, 0), b3, voffB); PG8_STAGE(PG8_SB(1, 1), b3 + hstep, voffB); PG8_STAGE(PG8_SA(1, 0), a3, voffA);
;             PG8_WAIT_V(8); PG8_WAIT_L(0); PG8_BAR; PG8_MMA(1, 0, At, B0); PG8_MMA(1, 1, At, B1); PG8_BAR; PG8_SCHED;
	s_add_i32 s20, s54, s34
	v_lshl_add_u64 v[160:161], v[160:161], 0, s[12:13]
	s_mov_b32 m0, s20
	ds_read_b128 v[180:183], v167 offset:49152
	ds_read_b128 v[184:187], v167 offset:50176
	ds_read_b128 v[188:191], v167 offset:51200
	ds_read_b128 v[192:195], v167 offset:52224
	ds_read_b128 v[196:199], v167 offset:53248
	ds_read_b128 v[200:203], v167 offset:54272
	ds_read_b128 v[204:207], v167 offset:55296
	ds_read_b128 v[208:211], v167 offset:56320
	global_load_lds_dwordx4 v[160:161], off
	s_add_i32 m0, s20, 0x2000
	s_add_u32 s20, s24, 0x160080
	v_lshl_add_u64 v[160:161], v[212:213], 0, s[12:13]
	s_addc_u32 s21, s25, 0
	s_add_i32 s24, s55, s34
	global_load_lds_dwordx4 v[160:161], off
	v_lshl_add_u64 v[160:161], s[20:21], 0, v[144:145]
	s_mov_b32 m0, s24
	s_nop 0
	global_load_lds_dwordx4 v[160:161], off
	v_lshl_add_u64 v[160:161], s[20:21], 0, v[146:147]
	s_add_i32 m0, s24, 0x2000
	s_nop 0
	global_load_lds_dwordx4 v[160:161], off
	v_lshl_add_u64 v[160:161], v[214:215], 0, s[12:13]
	s_mov_b32 m0, s42
	s_nop 0
	global_load_lds_dwordx4 v[160:161], off
	v_lshl_add_u64 v[160:161], v[216:217], 0, s[12:13]
	s_mov_b32 m0, s43
	s_nop 0
	global_load_lds_dwordx4 v[160:161], off
	s_waitcnt vmcnt(8)
	s_waitcnt lgkmcnt(0)
	s_barrier
	s_setprio 1
	s_waitcnt lgkmcnt(0)
	v_mfma_f32_16x16x32_bf16 v[60:63], v[128:131], v[180:183], v[60:63]
	v_mfma_f32_16x16x32_bf16 v[56:59], v[136:139], v[180:183], v[56:59]
	v_mfma_f32_16x16x32_bf16 v[52:55], v[128:131], v[188:191], v[52:55]
	v_mfma_f32_16x16x32_bf16 v[48:51], v[136:139], v[188:191], v[48:51]
	v_mfma_f32_16x16x32_bf16 v[36:39], v[128:131], v[196:199], v[36:39]
	v_mfma_f32_16x16x32_bf16 v[24:27], v[136:139], v[196:199], v[24:27]
	v_mfma_f32_16x16x32_bf16 v[16:19], v[128:131], v[204:207], v[16:19]
	v_mfma_f32_16x16x32_bf16 v[8:11], v[136:139], v[204:207], v[8:11]
	v_mfma_f32_16x16x32_bf16 v[60:63], v[132:135], v[184:187], v[60:63]
	v_mfma_f32_16x16x32_bf16 v[56:59], v[140:143], v[184:187], v[56:59]
	v_mfma_f32_16x16x32_bf16 v[52:55], v[132:135], v[192:195], v[52:55]
	v_mfma_f32_16x16x32_bf16 v[48:51], v[140:143], v[192:195], v[48:51]
	v_mfma_f32_16x16x32_bf16 v[36:39], v[132:135], v[200:203], v[36:39]
	v_mfma_f32_16x16x32_bf16 v[24:27], v[140:143], v[200:203], v[24:27]
	v_mfma_f32_16x16x32_bf16 v[16:19], v[132:135], v[208:211], v[16:19]
	v_mfma_f32_16x16x32_bf16 v[8:11], v[140:143], v[208:211], v[8:11]
	v_mfma_f32_16x16x32_bf16 v[44:47], v[156:159], v[180:183], v[44:47]
	v_mfma_f32_16x16x32_bf16 v[40:43], v[172:175], v[180:183], v[40:43]
	v_mfma_f32_16x16x32_bf16 v[32:35], v[156:159], v[188:191], v[32:35]
	v_mfma_f32_16x16x32_bf16 v[28:31], v[172:175], v[188:191], v[28:31]
	v_mfma_f32_16x16x32_bf16 v[20:23], v[156:159], v[196:199], v[20:23]
	v_mfma_f32_16x16x32_bf16 v[12:15], v[172:175], v[196:199], v[12:15]
	v_mfma_f32_16x16x32_bf16 v[4:7], v[156:159], v[204:207], v[4:7]
	v_mfma_f32_16x16x32_bf16 v[0:3], v[172:175], v[204:207], v[0:3]
	v_mfma_f32_16x16x32_bf16 v[44:47], v[168:171], v[184:187], v[44:47]
	v_mfma_f32_16x16x32_bf16 v[40:43], v[176:179], v[184:187], v[40:43]
	v_mfma_f32_16x16x32_bf16 v[32:35], v[168:171], v[192:195], v[32:35]
	v_mfma_f32_16x16x32_bf16 v[28:31], v[176:179], v[192:195], v[28:31]
	v_mfma_f32_16x16x32_bf16 v[20:23], v[168:171], v[200:203], v[20:23]
	v_mfma_f32_16x16x32_bf16 v[12:15], v[176:179], v[200:203], v[12:15]
	v_mfma_f32_16x16x32_bf16 v[4:7], v[168:171], v[208:211], v[4:7]
	v_mfma_f32_16x16x32_bf16 v[0:3], v[176:179], v[208:211], v[0:3]
	s_setprio 0
	s_barrier
	s_add_i32 s53, s53, 2
	s_add_u32 s51, s51, 0x100
	s_addc_u32 s52, s52, 0
	s_cmpk_gt_u32 s53, 0x55
	s_mov_b64 s[20:21], s[22:23]
	s_cbranch_scc0 .LBB0_1597
	s_and_b64 vcc, exec, s[14:15]
	s_cbranch_vccz .LBB0_1600
	s_barrier

; __device__ __forceinline__ unsigned xb_ld(unsigned* p)              { return __hip_atomic_load(p, __ATOMIC_RELAXED, __HIP_MEMORY_SCOPE_AGENT); }
; __device__ __forceinline__ unsigned xb_add(unsigned* p, unsigned v) { return __hip_atomic_fetch_add(p, v, __ATOMIC_RELAXED, __HIP_MEMORY_SCOPE_AGENT); }
; __device__ __forceinline__ void xcd_barrier_complete(unsigned* bar, unsigned x, unsigned& nloc, unsigned& nx) {
;     const unsigned G = gridDim.x * gridDim.y * gridDim.z;
;     unsigned sum, cnt, mine, sp = 0u;
;     for (;;) {
;         sum = 0u; cnt = 0u; mine = 0u;
; #pragma unroll
;         for (unsigned j = 0; j < 16; ++j) { const unsigned c = xb_ld(&bar[XB_XCNT(j)]); sum += c; cnt += (c > 0u) ? 1u : 0u; mine = (j == x) ? c : mine; }
; __device__ __forceinline__ void xcd_barrier(const XcdBarrier& b) {
;     asm volatile("s_waitcnt vmcnt(0)" ::: "memory");
;     __syncthreads();
;     if (threadIdx.x == 0) {
;         unsigned* bar = b.bar;
;         __builtin_amdgcn_s_waitcnt(0);
;         unsigned nloc = b.st[0], nx = b.st[1];
;         if (nloc == 0u) { xcd_barrier_complete(bar, b.x, nloc, nx); b.st[0] = nloc; b.st[1] = nx; }
;         const unsigned old = xb_add(&bar[XB_XSUB(b.x)], 1u);
.LBB0_1604:
	v_readlane_b32 s2, v253, 6
	v_readlane_b32 s3, v253, 7
	s_and_b64 vcc, exec, s[2:3]
	s_cbranch_vccz .LBB0_1660
	s_mov_b64 s[4:5], s[0:1]
	s_getreg_b32 s6, hwreg(HW_REG_XCC_ID, 0, 4)
	s_waitcnt vmcnt(0)
	s_waitcnt lgkmcnt(0)
	s_barrier
	s_and_saveexec_b64 s[2:3], s[64:65]
	s_cbranch_execz .LBB0_1656
	s_add_i32 s7, 0, 0x22000
	v_mov_b32_e32 v0, s7
	s_load_dwordx2 s[4:5], s[4:5], 0xb0
	s_waitcnt vmcnt(0) expcnt(0) lgkmcnt(0)
	ds_read_b32 v2, v0
	s_add_i32 s7, 0, 0x22004
	v_mov_b32_e32 v0, s7
	ds_read_b32 v0, v0
	s_and_b32 s33, s6, 15
	s_waitcnt lgkmcnt(1)
	v_cmp_ne_u32_e32 vcc, 0, v2
	s_cbranch_vccnz .LBB0_1620
	v_readlane_b32 s6, v253, 0
	v_readlane_b32 s7, v253, 1
	s_load_dword s6, s[6:7], 0x14
	s_mov_b32 s48, 1
	v_mov_b32_e32 v16, 0
	s_waitcnt lgkmcnt(0)
	s_lshr_b32 s8, s6, 16
	s_and_b32 s6, s6, 0xffff
	s_cmp_lg_u32 s6, 0
	s_cselect_b64 s[6:7], -1, 0
	s_cmp_lg_u64 s[6:7], 0
	s_addc_u32 s6, s87, 0
	s_cmp_lg_u32 s8, 0
	s_mul_i32 s49, s6, s86
	s_cselect_b64 s[6:7], -1, 0
	s_cmp_lg_u64 s[6:7], 0
	s_load_dword s6, s[0:1], 0xc0
	s_waitcnt lgkmcnt(0)
	s_addc_u32 s6, s6, 0
	s_mul_i32 s49, s49, s6
	s_add_u32 s6, s4, 0x900200
	s_addc_u32 s7, s5, 0
	s_add_u32 s8, s4, 0x900400
	s_addc_u32 s9, s5, 0
	s_add_u32 s10, s4, 0x900500
	s_addc_u32 s11, s5, 0
	s_add_u32 s12, s4, 0x900600
	s_addc_u32 s13, s5, 0
	s_add_u32 s14, s4, 0x900700
	s_addc_u32 s15, s5, 0
	s_add_u32 s16, s4, 0x900800
	s_addc_u32 s17, s5, 0
	s_add_u32 s18, s4, 0x900900
	s_addc_u32 s19, s5, 0
	s_add_u32 s20, s4, 0x900a00
	s_addc_u32 s21, s5, 0
	s_add_u32 s22, s4, 0x900b00
	s_addc_u32 s23, s5, 0
	s_add_u32 s24, s4, 0x900c00
	s_addc_u32 s25, s5, 0
	s_add_u32 s26, s4, 0x900d00
	s_addc_u32 s27, s5, 0
	s_add_u32 s28, s4, 0x900e00
	s_addc_u32 s29, s5, 0
	s_add_u32 s30, s4, 0x900f00
	s_addc_u32 s31, s5, 0
	s_add_u32 s34, s4, 0x901000
	s_addc_u32 s35, s5, 0
	s_add_u32 s36, s4, 0x901100
	s_addc_u32 s37, s5, 0
	s_add_u32 s38, s4, 0x901200
	s_addc_u32 s39, s5, 0
	s_add_u32 s40, s4, 0x901300
	s_addc_u32 s41, s5, 0
	s_branch .LBB0_1608
